# MT=8 GEMM K-loops (phases 2,3,11) also on LDS-DMA: A double-buffered, B single, A-fragment ring
# speedup vs baseline: 1.0976x; 1.0213x over previous
.LBB0_257:
	s_ashr_i32 s4, s28, 6
	s_mul_i32 s4, s4, s21
	s_add_i32 s4, s4, s20
	s_cmp_gt_i32 s4, 15
	s_mov_b32 s8, 2
	s_cbranch_scc1 .LBB0_344
	s_ashr_i32 s5, s4, 31
	s_lshr_b32 s5, s5, 29
	s_add_i32 s7, s4, s5
	s_and_b32 s5, s7, -8
	s_and_b32 s6, s28, 7
	s_or_b32 s6, s5, s6
	s_sub_i32 s5, s4, s5
	s_lshl_b32 s8, s5, 3
	s_bfe_u32 s5, s28, 0x30003
	s_or_b32 s9, s8, s5
	s_cmp_gt_i32 s6, 15
	s_cselect_b64 s[16:17], -1, 0
	s_cmp_gt_i32 s9, 56
	s_cselect_b64 s[18:19], -1, 0
	s_or_b64 s[16:17], s[16:17], s[18:19]
	s_mov_b32 s8, 4
	s_and_b64 vcc, exec, s[16:17]
	s_cbranch_vccnz .LBB0_344
	s_lshl_b32 s6, s6, 8
	s_ashr_i32 s29, s7, 3
	s_and_b32 s7, s23, 7
	s_addk_i32 s6, 0x2000
	s_lshl_b32 s30, s7, 8
	s_ashr_i32 s7, s6, 31
	s_lshl_b64 s[18:19], s[6:7], 11
	v_lshl_add_u64 v[48:49], v[186:187], 0, s[18:19]
	v_add_co_u32_e32 v50, vcc, 0x10000, v48
	s_lshl_b32 s16, s9, 7
	s_nop 0
	v_addc_co_u32_e32 v51, vcc, 0, v49, vcc
	v_add_co_u32_e32 v52, vcc, 0x20000, v48
	s_ashr_i32 s17, s16, 31
	s_nop 0
	v_addc_co_u32_e32 v53, vcc, 0, v49, vcc
	v_add_co_u32_e32 v54, vcc, 0x30000, v48
	s_lshl_b64 s[8:9], s[16:17], 11
	s_nop 0
	v_addc_co_u32_e32 v55, vcc, 0, v49, vcc
	v_add_co_u32_e32 v56, vcc, 0x40000, v48
	v_lshl_add_u64 v[68:69], v[188:189], 0, s[8:9]
	s_nop 0
	v_addc_co_u32_e32 v57, vcc, 0, v49, vcc
	v_add_co_u32_e32 v58, vcc, 0x50000, v48
	s_mov_b32 s7, 0x10000
	s_nop 0
	v_addc_co_u32_e32 v59, vcc, 0, v49, vcc
	v_add_co_u32_e32 v64, vcc, 0x60000, v48
	s_lshl_b32 s4, s4, 3
	s_nop 0
	v_addc_co_u32_e32 v65, vcc, 0, v49, vcc
	v_add_co_u32_e32 v66, vcc, 0x70000, v48
	s_or_b32 s4, s4, s5
	s_nop 0
	v_addc_co_u32_e32 v67, vcc, 0, v49, vcc
	v_add_co_u32_e32 v70, vcc, s7, v68
	s_mov_b32 s7, 0x20000
	s_nop 0
	v_addc_co_u32_e32 v71, vcc, 0, v69, vcc
	v_add_co_u32_e32 v72, vcc, s7, v68
	s_mov_b32 s7, 0x30000
	s_nop 0
	v_addc_co_u32_e32 v73, vcc, 0, v69, vcc
	v_add_co_u32_e32 v74, vcc, s7, v68
	s_lshl_b32 s7, s29, 11
	s_nop 0
	v_addc_co_u32_e32 v75, vcc, 0, v69, vcc
	s_nop 0
	v_readfirstlane_b32 s98, v48
	v_readfirstlane_b32 s99, v49
	s_nop 0
	v_readfirstlane_b32 s100, v68
	v_readfirstlane_b32 s101, v69
	s_lshl_b32 s5, s29, 6
	s_or_b32 s7, s7, s30
	s_sub_i32 s4, s4, s5
	s_add_i32 s8, s7, 0x2000
	s_lshl_b32 s4, s4, 7
	s_ashr_i32 s9, s8, 31
	s_ashr_i32 s5, s4, 31
	s_lshl_b64 s[8:9], s[8:9], 11
	s_lshl_b64 s[18:19], s[4:5], 11
	v_mov_b32_e32 v60, 0
	s_mov_b64 s[4:5], 0
	v_mov_b32_e32 v61, v60
	v_mov_b32_e32 v62, v60
	v_mov_b32_e32 v63, v60
	v_mov_b32_e32 v16, v60
	v_mov_b32_e32 v17, v60
	v_mov_b32_e32 v18, v60
	v_mov_b32_e32 v19, v60
	v_mov_b32_e32 v20, v60
	v_mov_b32_e32 v21, v60
	v_mov_b32_e32 v22, v60
	v_mov_b32_e32 v23, v60
	v_mov_b32_e32 v28, v60
	v_mov_b32_e32 v29, v60
	v_mov_b32_e32 v30, v60
	v_mov_b32_e32 v31, v60
	v_mov_b32_e32 v40, v60
	v_mov_b32_e32 v41, v60
	v_mov_b32_e32 v42, v60
	v_mov_b32_e32 v43, v60
	v_mov_b32_e32 v44, v60
	v_mov_b32_e32 v45, v60
	v_mov_b32_e32 v46, v60
	v_mov_b32_e32 v47, v60
	v_mov_b32_e32 v4, v60
	v_mov_b32_e32 v5, v60
	v_mov_b32_e32 v6, v60
	v_mov_b32_e32 v7, v60
	v_mov_b32_e32 v0, v60
	v_mov_b32_e32 v1, v60
	v_mov_b32_e32 v2, v60
	v_mov_b32_e32 v3, v60
	v_mov_b32_e32 v32, v60
	v_mov_b32_e32 v33, v60
	v_mov_b32_e32 v34, v60
	v_mov_b32_e32 v35, v60
	v_mov_b32_e32 v24, v60
	v_mov_b32_e32 v25, v60
	v_mov_b32_e32 v26, v60
	v_mov_b32_e32 v27, v60
	v_mov_b32_e32 v12, v60
	v_mov_b32_e32 v13, v60
	v_mov_b32_e32 v14, v60
	v_mov_b32_e32 v15, v60
	v_mov_b32_e32 v8, v60
	v_mov_b32_e32 v9, v60
	v_mov_b32_e32 v10, v60
	v_mov_b32_e32 v11, v60
	v_mov_b32_e32 v36, v60
	v_mov_b32_e32 v37, v60
	v_mov_b32_e32 v38, v60
	v_mov_b32_e32 v39, v60
	v_mov_b32_e32 v56, v60
	v_mov_b32_e32 v57, v60
	v_mov_b32_e32 v58, v60
	v_mov_b32_e32 v59, v60
	v_mov_b32_e32 v52, v60
	v_mov_b32_e32 v53, v60
	v_mov_b32_e32 v54, v60
	v_mov_b32_e32 v55, v60
	v_mov_b32_e32 v48, v60
	v_mov_b32_e32 v49, v60
	v_mov_b32_e32 v50, v60
	v_mov_b32_e32 v51, v60
	v_mov_b32_e32 v68, v60
	v_mov_b32_e32 v69, v60
	v_mov_b32_e32 v70, v60
	v_mov_b32_e32 v71, v60
	v_mov_b32_e32 v72, v60
	v_mov_b32_e32 v73, v60
	v_mov_b32_e32 v74, v60
	v_mov_b32_e32 v75, v60
	v_mov_b32_e32 v64, v60
	v_mov_b32_e32 v65, v60
	v_mov_b32_e32 v66, v60
	v_mov_b32_e32 v67, v60
	v_mov_b32_e32 v76, v60
	v_mov_b32_e32 v77, v60
	v_mov_b32_e32 v78, v60
	v_mov_b32_e32 v79, v60
	v_mov_b32_e32 v80, v60
	v_mov_b32_e32 v81, v60
	v_mov_b32_e32 v82, v60
	v_mov_b32_e32 v83, v60
	v_mov_b32_e32 v84, v60
	v_mov_b32_e32 v85, v60
	v_mov_b32_e32 v86, v60
	v_mov_b32_e32 v87, v60
	v_mov_b32_e32 v88, v60
	v_mov_b32_e32 v89, v60
	v_mov_b32_e32 v90, v60
	v_mov_b32_e32 v91, v60
	v_mov_b32_e32 v92, v60
	v_mov_b32_e32 v93, v60
	v_mov_b32_e32 v94, v60
	v_mov_b32_e32 v95, v60
	v_mov_b32_e32 v96, v60
	v_mov_b32_e32 v97, v60
	v_mov_b32_e32 v98, v60
	v_mov_b32_e32 v99, v60
	v_mov_b32_e32 v100, v60
	v_mov_b32_e32 v101, v60
	v_mov_b32_e32 v102, v60
	v_mov_b32_e32 v103, v60
	v_mov_b32_e32 v104, v60
	v_mov_b32_e32 v105, v60
	v_mov_b32_e32 v106, v60
	v_mov_b32_e32 v107, v60
	v_mov_b32_e32 v108, v60
	v_mov_b32_e32 v109, v60
	v_mov_b32_e32 v110, v60
	v_mov_b32_e32 v111, v60
	v_mov_b32_e32 v112, v60
	v_mov_b32_e32 v113, v60
	v_mov_b32_e32 v114, v60
	v_mov_b32_e32 v115, v60
	v_mov_b32_e32 v116, v60
	v_mov_b32_e32 v117, v60
	v_mov_b32_e32 v118, v60
	v_mov_b32_e32 v119, v60
	v_mov_b32_e32 v120, v60
	v_mov_b32_e32 v121, v60
	v_mov_b32_e32 v122, v60
	v_mov_b32_e32 v123, v60
	v_mov_b32_e32 v124, v60
	v_mov_b32_e32 v125, v60
	v_mov_b32_e32 v126, v60
	v_mov_b32_e32 v127, v60
	v_lshl_add_u64 v[192:193], v[190:191], 0, s[8:9]
	v_lshl_add_u64 v[194:195], v[190:191], 0, s[18:19]
	v_mov_b32_e32 v194, 0
	ds_read_b64 v[192:193], v194
	v_and_b32_e32 v195, 63, v196
	v_lshrrev_b32_e32 v239, 3, v195
	v_and_b32_e32 v236, 7, v195
	v_xor_b32_e32 v236, v236, v239
	v_lshlrev_b32_e32 v236, 4, v236
	v_mul_u32_u24_e32 v239, 2048, v239
	v_add_u32_e32 v226, v239, v236
	v_add_u32_e32 v227, 65536, v226
	v_add_u32_e32 v248, 131072, v226
	v_add_u32_e32 v249, 196608, v226
	v_add_u32_e32 v247, 262144, v226
	v_add_u32_e32 v244, 327680, v226
	v_add_u32_e32 v245, 393216, v226
	v_add_u32_e32 v246, 458752, v226
	v_lshrrev_b32_e32 v239, 6, v196
	v_lshrrev_b32_e32 v236, 1, v239
	v_and_b32_e32 v239, 1, v239
	v_and_b32_e32 v237, 15, v195
	v_lshrrev_b32_e32 v238, 4, v195
	v_and_b32_e32 v235, 7, v237
	v_xor_b32_e32 v238, v238, v235
	v_lshlrev_b32_e32 v238, 4, v238
	v_lshlrev_b32_e32 v236, 7, v236
	v_add_u32_e32 v236, v236, v237
	v_lshl_add_u32 v243, v236, 7, v238
	v_xor_b32_e32 v240, 64, v243
	v_lshlrev_b32_e32 v239, 6, v239
	v_add_u32_e32 v239, v239, v237
	v_lshl_add_u32 v241, v239, 7, v238
	v_add_u32_e32 v241, 65536, v241
	v_xor_b32_e32 v242, 64, v241
	v_lshrrev_b32_e32 v239, 6, v196
	v_lshlrev_b32_e32 v239, 10, v239
	s_nop 0
	v_readfirstlane_b32 s4, v239
	s_waitcnt lgkmcnt(0)
	s_barrier
	s_add_u32 m0, s4, 0
	s_nop 0
	global_load_lds_dwordx4 v226, s[98:99]
	s_add_u32 m0, s4, 4096
	s_nop 0
	global_load_lds_dwordx4 v227, s[98:99]
	s_add_u32 m0, s4, 8192
	s_nop 0
	global_load_lds_dwordx4 v248, s[98:99]
	s_add_u32 m0, s4, 12288
	s_nop 0
	global_load_lds_dwordx4 v249, s[98:99]
	s_add_u32 m0, s4, 16384
	s_nop 0
	global_load_lds_dwordx4 v247, s[98:99]
	s_add_u32 m0, s4, 20480
	s_nop 0
	global_load_lds_dwordx4 v244, s[98:99]
	s_add_u32 m0, s4, 24576
	s_nop 0
	global_load_lds_dwordx4 v245, s[98:99]
	s_add_u32 m0, s4, 28672
	s_nop 0
	global_load_lds_dwordx4 v246, s[98:99]
	s_add_u32 m0, s4, 65536
	s_nop 0
	global_load_lds_dwordx4 v226, s[100:101]
	s_add_u32 m0, s4, 69632
	s_nop 0
	global_load_lds_dwordx4 v227, s[100:101]
	s_add_u32 m0, s4, 73728
	s_nop 0
	global_load_lds_dwordx4 v248, s[100:101]
	s_add_u32 m0, s4, 77824
	s_nop 0
	global_load_lds_dwordx4 v249, s[100:101]
	s_add_u32 s98, s98, 0x80
	s_addc_u32 s99, s99, 0
	s_add_u32 s100, s100, 0x80
	s_addc_u32 s101, s101, 0
	s_mov_b32 s5, 7
.Lg8p2_loop:
	s_waitcnt vmcnt(0) lgkmcnt(0)
	s_barrier
	s_add_u32 m0, s4, 32768
	ds_read_b128 v[128:131], v241 offset:0
	global_load_lds_dwordx4 v226, s[98:99]
	s_add_u32 m0, s4, 36864
	ds_read_b128 v[136:139], v241 offset:2048
	global_load_lds_dwordx4 v227, s[98:99]
	s_add_u32 m0, s4, 40960
	ds_read_b128 v[144:147], v241 offset:4096
	global_load_lds_dwordx4 v248, s[98:99]
	s_add_u32 m0, s4, 45056
	ds_read_b128 v[152:155], v241 offset:6144
	global_load_lds_dwordx4 v249, s[98:99]
	s_add_u32 m0, s4, 49152
	ds_read_b128 v[132:135], v242 offset:0
	global_load_lds_dwordx4 v247, s[98:99]
	s_add_u32 m0, s4, 53248
	ds_read_b128 v[140:143], v242 offset:2048
	global_load_lds_dwordx4 v244, s[98:99]
	s_add_u32 m0, s4, 57344
	ds_read_b128 v[148:151], v242 offset:4096
	global_load_lds_dwordx4 v245, s[98:99]
	s_add_u32 m0, s4, 61440
	ds_read_b128 v[156:159], v242 offset:6144
	global_load_lds_dwordx4 v246, s[98:99]
	ds_read_b128 v[160:163], v243 offset:0
	ds_read_b128 v[164:167], v243 offset:2048
	ds_read_b128 v[168:171], v243 offset:4096
	ds_read_b128 v[172:175], v243 offset:6144
	s_waitcnt lgkmcnt(4)
	s_barrier
	s_waitcnt lgkmcnt(3)
	s_add_u32 m0, s4, 65536
	v_mfma_f32_16x16x32_bf16 v[124:127], v[128:131], v[160:163], v[124:127]
	ds_read_b128 v[176:179], v243 offset:8192
	global_load_lds_dwordx4 v226, s[100:101]
	v_mfma_f32_16x16x32_bf16 v[120:123], v[136:139], v[160:163], v[120:123]
	s_add_u32 m0, s4, 69632
	v_mfma_f32_16x16x32_bf16 v[116:119], v[144:147], v[160:163], v[116:119]
	global_load_lds_dwordx4 v227, s[100:101]
	v_mfma_f32_16x16x32_bf16 v[112:115], v[152:155], v[160:163], v[112:115]
	s_waitcnt lgkmcnt(3)
	s_add_u32 m0, s4, 73728
	v_mfma_f32_16x16x32_bf16 v[108:111], v[128:131], v[164:167], v[108:111]
	ds_read_b128 v[180:183], v243 offset:10240
	global_load_lds_dwordx4 v248, s[100:101]
	v_mfma_f32_16x16x32_bf16 v[104:107], v[136:139], v[164:167], v[104:107]
	s_add_u32 m0, s4, 77824
	v_mfma_f32_16x16x32_bf16 v[100:103], v[144:147], v[164:167], v[100:103]
	global_load_lds_dwordx4 v249, s[100:101]
	v_mfma_f32_16x16x32_bf16 v[96:99], v[152:155], v[164:167], v[96:99]
	s_waitcnt lgkmcnt(3)
	v_mfma_f32_16x16x32_bf16 v[92:95], v[128:131], v[168:171], v[92:95]
	ds_read_b128 v[160:163], v243 offset:12288
	v_mfma_f32_16x16x32_bf16 v[88:91], v[136:139], v[168:171], v[88:91]
	v_mfma_f32_16x16x32_bf16 v[84:87], v[144:147], v[168:171], v[84:87]
	v_mfma_f32_16x16x32_bf16 v[80:83], v[152:155], v[168:171], v[80:83]
	s_waitcnt lgkmcnt(3)
	v_mfma_f32_16x16x32_bf16 v[76:79], v[128:131], v[172:175], v[76:79]
	ds_read_b128 v[164:167], v243 offset:14336
	v_mfma_f32_16x16x32_bf16 v[64:67], v[136:139], v[172:175], v[64:67]
	v_mfma_f32_16x16x32_bf16 v[72:75], v[144:147], v[172:175], v[72:75]
	v_mfma_f32_16x16x32_bf16 v[68:71], v[152:155], v[172:175], v[68:71]
	s_waitcnt lgkmcnt(3)
	v_mfma_f32_16x16x32_bf16 v[48:51], v[128:131], v[176:179], v[48:51]
	ds_read_b128 v[168:171], v240 offset:0
	v_mfma_f32_16x16x32_bf16 v[52:55], v[136:139], v[176:179], v[52:55]
	v_mfma_f32_16x16x32_bf16 v[56:59], v[144:147], v[176:179], v[56:59]
	v_mfma_f32_16x16x32_bf16 v[36:39], v[152:155], v[176:179], v[36:39]
	s_waitcnt lgkmcnt(3)
	v_mfma_f32_16x16x32_bf16 v[8:11], v[128:131], v[180:183], v[8:11]
	ds_read_b128 v[172:175], v240 offset:2048
	v_mfma_f32_16x16x32_bf16 v[12:15], v[136:139], v[180:183], v[12:15]
	v_mfma_f32_16x16x32_bf16 v[24:27], v[144:147], v[180:183], v[24:27]
	v_mfma_f32_16x16x32_bf16 v[32:35], v[152:155], v[180:183], v[32:35]
	s_waitcnt lgkmcnt(3)
	v_mfma_f32_16x16x32_bf16 v[0:3], v[128:131], v[160:163], v[0:3]
	ds_read_b128 v[176:179], v240 offset:4096
	v_mfma_f32_16x16x32_bf16 v[4:7], v[136:139], v[160:163], v[4:7]
	v_mfma_f32_16x16x32_bf16 v[44:47], v[144:147], v[160:163], v[44:47]
	v_mfma_f32_16x16x32_bf16 v[40:43], v[152:155], v[160:163], v[40:43]
	s_waitcnt lgkmcnt(3)
	v_mfma_f32_16x16x32_bf16 v[28:31], v[128:131], v[164:167], v[28:31]
	ds_read_b128 v[180:183], v240 offset:6144
	v_mfma_f32_16x16x32_bf16 v[20:23], v[136:139], v[164:167], v[20:23]
	v_mfma_f32_16x16x32_bf16 v[16:19], v[144:147], v[164:167], v[16:19]
	v_mfma_f32_16x16x32_bf16 v[60:63], v[152:155], v[164:167], v[60:63]
	s_waitcnt lgkmcnt(3)
	v_mfma_f32_16x16x32_bf16 v[124:127], v[132:135], v[168:171], v[124:127]
	ds_read_b128 v[160:163], v240 offset:8192
	v_mfma_f32_16x16x32_bf16 v[120:123], v[140:143], v[168:171], v[120:123]
	v_mfma_f32_16x16x32_bf16 v[116:119], v[148:151], v[168:171], v[116:119]
	v_mfma_f32_16x16x32_bf16 v[112:115], v[156:159], v[168:171], v[112:115]
	s_waitcnt lgkmcnt(3)
	v_mfma_f32_16x16x32_bf16 v[108:111], v[132:135], v[172:175], v[108:111]
	ds_read_b128 v[164:167], v240 offset:10240
	v_mfma_f32_16x16x32_bf16 v[104:107], v[140:143], v[172:175], v[104:107]
	v_mfma_f32_16x16x32_bf16 v[100:103], v[148:151], v[172:175], v[100:103]
	v_mfma_f32_16x16x32_bf16 v[96:99], v[156:159], v[172:175], v[96:99]
	s_waitcnt lgkmcnt(3)
	v_mfma_f32_16x16x32_bf16 v[92:95], v[132:135], v[176:179], v[92:95]
	ds_read_b128 v[168:171], v240 offset:12288
	v_mfma_f32_16x16x32_bf16 v[88:91], v[140:143], v[176:179], v[88:91]
	v_mfma_f32_16x16x32_bf16 v[84:87], v[148:151], v[176:179], v[84:87]
	v_mfma_f32_16x16x32_bf16 v[80:83], v[156:159], v[176:179], v[80:83]
	s_waitcnt lgkmcnt(3)
	v_mfma_f32_16x16x32_bf16 v[76:79], v[132:135], v[180:183], v[76:79]
	ds_read_b128 v[172:175], v240 offset:14336
	v_mfma_f32_16x16x32_bf16 v[64:67], v[140:143], v[180:183], v[64:67]
	v_mfma_f32_16x16x32_bf16 v[72:75], v[148:151], v[180:183], v[72:75]
	v_mfma_f32_16x16x32_bf16 v[68:71], v[156:159], v[180:183], v[68:71]
	s_waitcnt lgkmcnt(3)
	v_mfma_f32_16x16x32_bf16 v[48:51], v[132:135], v[160:163], v[48:51]
	v_mfma_f32_16x16x32_bf16 v[52:55], v[140:143], v[160:163], v[52:55]
	v_mfma_f32_16x16x32_bf16 v[56:59], v[148:151], v[160:163], v[56:59]
	v_mfma_f32_16x16x32_bf16 v[36:39], v[156:159], v[160:163], v[36:39]
	s_waitcnt lgkmcnt(2)
	v_mfma_f32_16x16x32_bf16 v[8:11], v[132:135], v[164:167], v[8:11]
	v_mfma_f32_16x16x32_bf16 v[12:15], v[140:143], v[164:167], v[12:15]
	v_mfma_f32_16x16x32_bf16 v[24:27], v[148:151], v[164:167], v[24:27]
	v_mfma_f32_16x16x32_bf16 v[32:35], v[156:159], v[164:167], v[32:35]
	s_waitcnt lgkmcnt(1)
	v_mfma_f32_16x16x32_bf16 v[0:3], v[132:135], v[168:171], v[0:3]
	v_mfma_f32_16x16x32_bf16 v[4:7], v[140:143], v[168:171], v[4:7]
	v_mfma_f32_16x16x32_bf16 v[44:47], v[148:151], v[168:171], v[44:47]
	v_mfma_f32_16x16x32_bf16 v[40:43], v[156:159], v[168:171], v[40:43]
	s_waitcnt lgkmcnt(0)
	v_mfma_f32_16x16x32_bf16 v[28:31], v[132:135], v[172:175], v[28:31]
	v_mfma_f32_16x16x32_bf16 v[20:23], v[140:143], v[172:175], v[20:23]
	v_mfma_f32_16x16x32_bf16 v[16:19], v[148:151], v[172:175], v[16:19]
	v_mfma_f32_16x16x32_bf16 v[60:63], v[156:159], v[172:175], v[60:63]
	s_add_u32 s98, s98, 0x80
	s_addc_u32 s99, s99, 0
	s_add_u32 s100, s100, 0x80
	s_addc_u32 s101, s101, 0
	s_waitcnt vmcnt(0) lgkmcnt(0)
	s_barrier
	s_add_u32 m0, s4, 0
	ds_read_b128 v[128:131], v241 offset:0
	global_load_lds_dwordx4 v226, s[98:99]
	s_add_u32 m0, s4, 4096
	ds_read_b128 v[136:139], v241 offset:2048
	global_load_lds_dwordx4 v227, s[98:99]
	s_add_u32 m0, s4, 8192
	ds_read_b128 v[144:147], v241 offset:4096
	global_load_lds_dwordx4 v248, s[98:99]
	s_add_u32 m0, s4, 12288
	ds_read_b128 v[152:155], v241 offset:6144
	global_load_lds_dwordx4 v249, s[98:99]
	s_add_u32 m0, s4, 16384
	ds_read_b128 v[132:135], v242 offset:0
	global_load_lds_dwordx4 v247, s[98:99]
	s_add_u32 m0, s4, 20480
	ds_read_b128 v[140:143], v242 offset:2048
	global_load_lds_dwordx4 v244, s[98:99]
	s_add_u32 m0, s4, 24576
	ds_read_b128 v[148:151], v242 offset:4096
	global_load_lds_dwordx4 v245, s[98:99]
	s_add_u32 m0, s4, 28672
	ds_read_b128 v[156:159], v242 offset:6144
	global_load_lds_dwordx4 v246, s[98:99]
	ds_read_b128 v[160:163], v243 offset:32768
	ds_read_b128 v[164:167], v243 offset:34816
	ds_read_b128 v[168:171], v243 offset:36864
	ds_read_b128 v[172:175], v243 offset:38912
	s_waitcnt lgkmcnt(4)
	s_barrier
	s_waitcnt lgkmcnt(3)
	s_add_u32 m0, s4, 65536
	v_mfma_f32_16x16x32_bf16 v[124:127], v[128:131], v[160:163], v[124:127]
	ds_read_b128 v[176:179], v243 offset:40960
	global_load_lds_dwordx4 v226, s[100:101]
	v_mfma_f32_16x16x32_bf16 v[120:123], v[136:139], v[160:163], v[120:123]
	s_add_u32 m0, s4, 69632
	v_mfma_f32_16x16x32_bf16 v[116:119], v[144:147], v[160:163], v[116:119]
	global_load_lds_dwordx4 v227, s[100:101]
	v_mfma_f32_16x16x32_bf16 v[112:115], v[152:155], v[160:163], v[112:115]
	s_waitcnt lgkmcnt(3)
	s_add_u32 m0, s4, 73728
	v_mfma_f32_16x16x32_bf16 v[108:111], v[128:131], v[164:167], v[108:111]
	ds_read_b128 v[180:183], v243 offset:43008
	global_load_lds_dwordx4 v248, s[100:101]
	v_mfma_f32_16x16x32_bf16 v[104:107], v[136:139], v[164:167], v[104:107]
	s_add_u32 m0, s4, 77824
	v_mfma_f32_16x16x32_bf16 v[100:103], v[144:147], v[164:167], v[100:103]
	global_load_lds_dwordx4 v249, s[100:101]
	v_mfma_f32_16x16x32_bf16 v[96:99], v[152:155], v[164:167], v[96:99]
	s_waitcnt lgkmcnt(3)
	v_mfma_f32_16x16x32_bf16 v[92:95], v[128:131], v[168:171], v[92:95]
	ds_read_b128 v[160:163], v243 offset:45056
	v_mfma_f32_16x16x32_bf16 v[88:91], v[136:139], v[168:171], v[88:91]
	v_mfma_f32_16x16x32_bf16 v[84:87], v[144:147], v[168:171], v[84:87]
	v_mfma_f32_16x16x32_bf16 v[80:83], v[152:155], v[168:171], v[80:83]
	s_waitcnt lgkmcnt(3)
	v_mfma_f32_16x16x32_bf16 v[76:79], v[128:131], v[172:175], v[76:79]
	ds_read_b128 v[164:167], v243 offset:47104
	v_mfma_f32_16x16x32_bf16 v[64:67], v[136:139], v[172:175], v[64:67]
	v_mfma_f32_16x16x32_bf16 v[72:75], v[144:147], v[172:175], v[72:75]
	v_mfma_f32_16x16x32_bf16 v[68:71], v[152:155], v[172:175], v[68:71]
	s_waitcnt lgkmcnt(3)
	v_mfma_f32_16x16x32_bf16 v[48:51], v[128:131], v[176:179], v[48:51]
	ds_read_b128 v[168:171], v240 offset:32768
	v_mfma_f32_16x16x32_bf16 v[52:55], v[136:139], v[176:179], v[52:55]
	v_mfma_f32_16x16x32_bf16 v[56:59], v[144:147], v[176:179], v[56:59]
	v_mfma_f32_16x16x32_bf16 v[36:39], v[152:155], v[176:179], v[36:39]
	s_waitcnt lgkmcnt(3)
	v_mfma_f32_16x16x32_bf16 v[8:11], v[128:131], v[180:183], v[8:11]
	ds_read_b128 v[172:175], v240 offset:34816
	v_mfma_f32_16x16x32_bf16 v[12:15], v[136:139], v[180:183], v[12:15]
	v_mfma_f32_16x16x32_bf16 v[24:27], v[144:147], v[180:183], v[24:27]
	v_mfma_f32_16x16x32_bf16 v[32:35], v[152:155], v[180:183], v[32:35]
	s_waitcnt lgkmcnt(3)
	v_mfma_f32_16x16x32_bf16 v[0:3], v[128:131], v[160:163], v[0:3]
	ds_read_b128 v[176:179], v240 offset:36864
	v_mfma_f32_16x16x32_bf16 v[4:7], v[136:139], v[160:163], v[4:7]
	v_mfma_f32_16x16x32_bf16 v[44:47], v[144:147], v[160:163], v[44:47]
	v_mfma_f32_16x16x32_bf16 v[40:43], v[152:155], v[160:163], v[40:43]
	s_waitcnt lgkmcnt(3)
	v_mfma_f32_16x16x32_bf16 v[28:31], v[128:131], v[164:167], v[28:31]
	ds_read_b128 v[180:183], v240 offset:38912
	v_mfma_f32_16x16x32_bf16 v[20:23], v[136:139], v[164:167], v[20:23]
	v_mfma_f32_16x16x32_bf16 v[16:19], v[144:147], v[164:167], v[16:19]
	v_mfma_f32_16x16x32_bf16 v[60:63], v[152:155], v[164:167], v[60:63]
	s_waitcnt lgkmcnt(3)
	v_mfma_f32_16x16x32_bf16 v[124:127], v[132:135], v[168:171], v[124:127]
	ds_read_b128 v[160:163], v240 offset:40960
	v_mfma_f32_16x16x32_bf16 v[120:123], v[140:143], v[168:171], v[120:123]
	v_mfma_f32_16x16x32_bf16 v[116:119], v[148:151], v[168:171], v[116:119]
	v_mfma_f32_16x16x32_bf16 v[112:115], v[156:159], v[168:171], v[112:115]
	s_waitcnt lgkmcnt(3)
	v_mfma_f32_16x16x32_bf16 v[108:111], v[132:135], v[172:175], v[108:111]
	ds_read_b128 v[164:167], v240 offset:43008
	v_mfma_f32_16x16x32_bf16 v[104:107], v[140:143], v[172:175], v[104:107]
	v_mfma_f32_16x16x32_bf16 v[100:103], v[148:151], v[172:175], v[100:103]
	v_mfma_f32_16x16x32_bf16 v[96:99], v[156:159], v[172:175], v[96:99]
	s_waitcnt lgkmcnt(3)
	v_mfma_f32_16x16x32_bf16 v[92:95], v[132:135], v[176:179], v[92:95]
	ds_read_b128 v[168:171], v240 offset:45056
	v_mfma_f32_16x16x32_bf16 v[88:91], v[140:143], v[176:179], v[88:91]
	v_mfma_f32_16x16x32_bf16 v[84:87], v[148:151], v[176:179], v[84:87]
	v_mfma_f32_16x16x32_bf16 v[80:83], v[156:159], v[176:179], v[80:83]
	s_waitcnt lgkmcnt(3)
	v_mfma_f32_16x16x32_bf16 v[76:79], v[132:135], v[180:183], v[76:79]
	ds_read_b128 v[172:175], v240 offset:47104
	v_mfma_f32_16x16x32_bf16 v[64:67], v[140:143], v[180:183], v[64:67]
	v_mfma_f32_16x16x32_bf16 v[72:75], v[148:151], v[180:183], v[72:75]
	v_mfma_f32_16x16x32_bf16 v[68:71], v[156:159], v[180:183], v[68:71]
	s_waitcnt lgkmcnt(3)
	v_mfma_f32_16x16x32_bf16 v[48:51], v[132:135], v[160:163], v[48:51]
	v_mfma_f32_16x16x32_bf16 v[52:55], v[140:143], v[160:163], v[52:55]
	v_mfma_f32_16x16x32_bf16 v[56:59], v[148:151], v[160:163], v[56:59]
	v_mfma_f32_16x16x32_bf16 v[36:39], v[156:159], v[160:163], v[36:39]
	s_waitcnt lgkmcnt(2)
	v_mfma_f32_16x16x32_bf16 v[8:11], v[132:135], v[164:167], v[8:11]
	v_mfma_f32_16x16x32_bf16 v[12:15], v[140:143], v[164:167], v[12:15]
	v_mfma_f32_16x16x32_bf16 v[24:27], v[148:151], v[164:167], v[24:27]
	v_mfma_f32_16x16x32_bf16 v[32:35], v[156:159], v[164:167], v[32:35]
	s_waitcnt lgkmcnt(1)
	v_mfma_f32_16x16x32_bf16 v[0:3], v[132:135], v[168:171], v[0:3]
	v_mfma_f32_16x16x32_bf16 v[4:7], v[140:143], v[168:171], v[4:7]
	v_mfma_f32_16x16x32_bf16 v[44:47], v[148:151], v[168:171], v[44:47]
	v_mfma_f32_16x16x32_bf16 v[40:43], v[156:159], v[168:171], v[40:43]
	s_waitcnt lgkmcnt(0)
	v_mfma_f32_16x16x32_bf16 v[28:31], v[132:135], v[172:175], v[28:31]
	v_mfma_f32_16x16x32_bf16 v[20:23], v[140:143], v[172:175], v[20:23]
	v_mfma_f32_16x16x32_bf16 v[16:19], v[148:151], v[172:175], v[16:19]
	v_mfma_f32_16x16x32_bf16 v[60:63], v[156:159], v[172:175], v[60:63]
	s_add_u32 s98, s98, 0x80
	s_addc_u32 s99, s99, 0
	s_add_u32 s100, s100, 0x80
	s_addc_u32 s101, s101, 0
	s_sub_u32 s5, s5, 1
	s_cmp_lg_u32 s5, 0
	s_cbranch_scc1 .Lg8p2_loop
	s_waitcnt vmcnt(0) lgkmcnt(0)
	s_barrier
	s_add_u32 m0, s4, 32768
	ds_read_b128 v[128:131], v241 offset:0
	global_load_lds_dwordx4 v226, s[98:99]
	s_add_u32 m0, s4, 36864
	ds_read_b128 v[136:139], v241 offset:2048
	global_load_lds_dwordx4 v227, s[98:99]
	s_add_u32 m0, s4, 40960
	ds_read_b128 v[144:147], v241 offset:4096
	global_load_lds_dwordx4 v248, s[98:99]
	s_add_u32 m0, s4, 45056
	ds_read_b128 v[152:155], v241 offset:6144
	global_load_lds_dwordx4 v249, s[98:99]
	s_add_u32 m0, s4, 49152
	ds_read_b128 v[132:135], v242 offset:0
	global_load_lds_dwordx4 v247, s[98:99]
	s_add_u32 m0, s4, 53248
	ds_read_b128 v[140:143], v242 offset:2048
	global_load_lds_dwordx4 v244, s[98:99]
	s_add_u32 m0, s4, 57344
	ds_read_b128 v[148:151], v242 offset:4096
	global_load_lds_dwordx4 v245, s[98:99]
	s_add_u32 m0, s4, 61440
	ds_read_b128 v[156:159], v242 offset:6144
	global_load_lds_dwordx4 v246, s[98:99]
	ds_read_b128 v[160:163], v243 offset:0
	ds_read_b128 v[164:167], v243 offset:2048
	ds_read_b128 v[168:171], v243 offset:4096
	ds_read_b128 v[172:175], v243 offset:6144
	s_waitcnt lgkmcnt(4)
	s_barrier
	s_waitcnt lgkmcnt(3)
	s_add_u32 m0, s4, 65536
	v_mfma_f32_16x16x32_bf16 v[124:127], v[128:131], v[160:163], v[124:127]
	ds_read_b128 v[176:179], v243 offset:8192
	global_load_lds_dwordx4 v226, s[100:101]
	v_mfma_f32_16x16x32_bf16 v[120:123], v[136:139], v[160:163], v[120:123]
	s_add_u32 m0, s4, 69632
	v_mfma_f32_16x16x32_bf16 v[116:119], v[144:147], v[160:163], v[116:119]
	global_load_lds_dwordx4 v227, s[100:101]
	v_mfma_f32_16x16x32_bf16 v[112:115], v[152:155], v[160:163], v[112:115]
	s_waitcnt lgkmcnt(3)
	s_add_u32 m0, s4, 73728
	v_mfma_f32_16x16x32_bf16 v[108:111], v[128:131], v[164:167], v[108:111]
	ds_read_b128 v[180:183], v243 offset:10240
	global_load_lds_dwordx4 v248, s[100:101]
	v_mfma_f32_16x16x32_bf16 v[104:107], v[136:139], v[164:167], v[104:107]
	s_add_u32 m0, s4, 77824
	v_mfma_f32_16x16x32_bf16 v[100:103], v[144:147], v[164:167], v[100:103]
	global_load_lds_dwordx4 v249, s[100:101]
	v_mfma_f32_16x16x32_bf16 v[96:99], v[152:155], v[164:167], v[96:99]
	s_waitcnt lgkmcnt(3)
	v_mfma_f32_16x16x32_bf16 v[92:95], v[128:131], v[168:171], v[92:95]
	ds_read_b128 v[160:163], v243 offset:12288
	v_mfma_f32_16x16x32_bf16 v[88:91], v[136:139], v[168:171], v[88:91]
	v_mfma_f32_16x16x32_bf16 v[84:87], v[144:147], v[168:171], v[84:87]
	v_mfma_f32_16x16x32_bf16 v[80:83], v[152:155], v[168:171], v[80:83]
	s_waitcnt lgkmcnt(3)
	v_mfma_f32_16x16x32_bf16 v[76:79], v[128:131], v[172:175], v[76:79]
	ds_read_b128 v[164:167], v243 offset:14336
	v_mfma_f32_16x16x32_bf16 v[64:67], v[136:139], v[172:175], v[64:67]
	v_mfma_f32_16x16x32_bf16 v[72:75], v[144:147], v[172:175], v[72:75]
	v_mfma_f32_16x16x32_bf16 v[68:71], v[152:155], v[172:175], v[68:71]
	s_waitcnt lgkmcnt(3)
	v_mfma_f32_16x16x32_bf16 v[48:51], v[128:131], v[176:179], v[48:51]
	ds_read_b128 v[168:171], v240 offset:0
	v_mfma_f32_16x16x32_bf16 v[52:55], v[136:139], v[176:179], v[52:55]
	v_mfma_f32_16x16x32_bf16 v[56:59], v[144:147], v[176:179], v[56:59]
	v_mfma_f32_16x16x32_bf16 v[36:39], v[152:155], v[176:179], v[36:39]
	s_waitcnt lgkmcnt(3)
	v_mfma_f32_16x16x32_bf16 v[8:11], v[128:131], v[180:183], v[8:11]
	ds_read_b128 v[172:175], v240 offset:2048
	v_mfma_f32_16x16x32_bf16 v[12:15], v[136:139], v[180:183], v[12:15]
	v_mfma_f32_16x16x32_bf16 v[24:27], v[144:147], v[180:183], v[24:27]
	v_mfma_f32_16x16x32_bf16 v[32:35], v[152:155], v[180:183], v[32:35]
	s_waitcnt lgkmcnt(3)
	v_mfma_f32_16x16x32_bf16 v[0:3], v[128:131], v[160:163], v[0:3]
	ds_read_b128 v[176:179], v240 offset:4096
	v_mfma_f32_16x16x32_bf16 v[4:7], v[136:139], v[160:163], v[4:7]
	v_mfma_f32_16x16x32_bf16 v[44:47], v[144:147], v[160:163], v[44:47]
	v_mfma_f32_16x16x32_bf16 v[40:43], v[152:155], v[160:163], v[40:43]
	s_waitcnt lgkmcnt(3)
	v_mfma_f32_16x16x32_bf16 v[28:31], v[128:131], v[164:167], v[28:31]
	ds_read_b128 v[180:183], v240 offset:6144
	v_mfma_f32_16x16x32_bf16 v[20:23], v[136:139], v[164:167], v[20:23]
	v_mfma_f32_16x16x32_bf16 v[16:19], v[144:147], v[164:167], v[16:19]
	v_mfma_f32_16x16x32_bf16 v[60:63], v[152:155], v[164:167], v[60:63]
	s_waitcnt lgkmcnt(3)
	v_mfma_f32_16x16x32_bf16 v[124:127], v[132:135], v[168:171], v[124:127]
	ds_read_b128 v[160:163], v240 offset:8192
	v_mfma_f32_16x16x32_bf16 v[120:123], v[140:143], v[168:171], v[120:123]
	v_mfma_f32_16x16x32_bf16 v[116:119], v[148:151], v[168:171], v[116:119]
	v_mfma_f32_16x16x32_bf16 v[112:115], v[156:159], v[168:171], v[112:115]
	s_waitcnt lgkmcnt(3)
	v_mfma_f32_16x16x32_bf16 v[108:111], v[132:135], v[172:175], v[108:111]
	ds_read_b128 v[164:167], v240 offset:10240
	v_mfma_f32_16x16x32_bf16 v[104:107], v[140:143], v[172:175], v[104:107]
	v_mfma_f32_16x16x32_bf16 v[100:103], v[148:151], v[172:175], v[100:103]
	v_mfma_f32_16x16x32_bf16 v[96:99], v[156:159], v[172:175], v[96:99]
	s_waitcnt lgkmcnt(3)
	v_mfma_f32_16x16x32_bf16 v[92:95], v[132:135], v[176:179], v[92:95]
	ds_read_b128 v[168:171], v240 offset:12288
	v_mfma_f32_16x16x32_bf16 v[88:91], v[140:143], v[176:179], v[88:91]
	v_mfma_f32_16x16x32_bf16 v[84:87], v[148:151], v[176:179], v[84:87]
	v_mfma_f32_16x16x32_bf16 v[80:83], v[156:159], v[176:179], v[80:83]
	s_waitcnt lgkmcnt(3)
	v_mfma_f32_16x16x32_bf16 v[76:79], v[132:135], v[180:183], v[76:79]
	ds_read_b128 v[172:175], v240 offset:14336
	v_mfma_f32_16x16x32_bf16 v[64:67], v[140:143], v[180:183], v[64:67]
	v_mfma_f32_16x16x32_bf16 v[72:75], v[148:151], v[180:183], v[72:75]
	v_mfma_f32_16x16x32_bf16 v[68:71], v[156:159], v[180:183], v[68:71]
	s_waitcnt lgkmcnt(3)
	v_mfma_f32_16x16x32_bf16 v[48:51], v[132:135], v[160:163], v[48:51]
	v_mfma_f32_16x16x32_bf16 v[52:55], v[140:143], v[160:163], v[52:55]
	v_mfma_f32_16x16x32_bf16 v[56:59], v[148:151], v[160:163], v[56:59]
	v_mfma_f32_16x16x32_bf16 v[36:39], v[156:159], v[160:163], v[36:39]
	s_waitcnt lgkmcnt(2)
	v_mfma_f32_16x16x32_bf16 v[8:11], v[132:135], v[164:167], v[8:11]
	v_mfma_f32_16x16x32_bf16 v[12:15], v[140:143], v[164:167], v[12:15]
	v_mfma_f32_16x16x32_bf16 v[24:27], v[148:151], v[164:167], v[24:27]
	v_mfma_f32_16x16x32_bf16 v[32:35], v[156:159], v[164:167], v[32:35]
	s_waitcnt lgkmcnt(1)
	v_mfma_f32_16x16x32_bf16 v[0:3], v[132:135], v[168:171], v[0:3]
	v_mfma_f32_16x16x32_bf16 v[4:7], v[140:143], v[168:171], v[4:7]
	v_mfma_f32_16x16x32_bf16 v[44:47], v[148:151], v[168:171], v[44:47]
	v_mfma_f32_16x16x32_bf16 v[40:43], v[156:159], v[168:171], v[40:43]
	s_waitcnt lgkmcnt(0)
	v_mfma_f32_16x16x32_bf16 v[28:31], v[132:135], v[172:175], v[28:31]
	v_mfma_f32_16x16x32_bf16 v[20:23], v[140:143], v[172:175], v[20:23]
	v_mfma_f32_16x16x32_bf16 v[16:19], v[148:151], v[172:175], v[16:19]
	v_mfma_f32_16x16x32_bf16 v[60:63], v[156:159], v[172:175], v[60:63]
	s_add_u32 s98, s98, 0x80
	s_addc_u32 s99, s99, 0
	s_add_u32 s100, s100, 0x80
	s_addc_u32 s101, s101, 0
	s_waitcnt vmcnt(0) lgkmcnt(0)
	s_barrier
	ds_read_b128 v[128:131], v241 offset:0
	ds_read_b128 v[136:139], v241 offset:2048
	ds_read_b128 v[144:147], v241 offset:4096
	ds_read_b128 v[152:155], v241 offset:6144
	ds_read_b128 v[132:135], v242 offset:0
	ds_read_b128 v[140:143], v242 offset:2048
	ds_read_b128 v[148:151], v242 offset:4096
	ds_read_b128 v[156:159], v242 offset:6144
	ds_read_b128 v[160:163], v243 offset:32768
	ds_read_b128 v[164:167], v243 offset:34816
	ds_read_b128 v[168:171], v243 offset:36864
	ds_read_b128 v[172:175], v243 offset:38912
	s_waitcnt lgkmcnt(4)
	s_waitcnt lgkmcnt(3)
	v_mfma_f32_16x16x32_bf16 v[124:127], v[128:131], v[160:163], v[124:127]
	ds_read_b128 v[176:179], v243 offset:40960
	v_mfma_f32_16x16x32_bf16 v[120:123], v[136:139], v[160:163], v[120:123]
	v_mfma_f32_16x16x32_bf16 v[116:119], v[144:147], v[160:163], v[116:119]
	v_mfma_f32_16x16x32_bf16 v[112:115], v[152:155], v[160:163], v[112:115]
	s_waitcnt lgkmcnt(3)
	v_mfma_f32_16x16x32_bf16 v[108:111], v[128:131], v[164:167], v[108:111]
	ds_read_b128 v[180:183], v243 offset:43008
	v_mfma_f32_16x16x32_bf16 v[104:107], v[136:139], v[164:167], v[104:107]
	v_mfma_f32_16x16x32_bf16 v[100:103], v[144:147], v[164:167], v[100:103]
	v_mfma_f32_16x16x32_bf16 v[96:99], v[152:155], v[164:167], v[96:99]
	s_waitcnt lgkmcnt(3)
	v_mfma_f32_16x16x32_bf16 v[92:95], v[128:131], v[168:171], v[92:95]
	ds_read_b128 v[160:163], v243 offset:45056
	v_mfma_f32_16x16x32_bf16 v[88:91], v[136:139], v[168:171], v[88:91]
	v_mfma_f32_16x16x32_bf16 v[84:87], v[144:147], v[168:171], v[84:87]
	v_mfma_f32_16x16x32_bf16 v[80:83], v[152:155], v[168:171], v[80:83]
	s_waitcnt lgkmcnt(3)
	v_mfma_f32_16x16x32_bf16 v[76:79], v[128:131], v[172:175], v[76:79]
	ds_read_b128 v[164:167], v243 offset:47104
	v_mfma_f32_16x16x32_bf16 v[64:67], v[136:139], v[172:175], v[64:67]
	v_mfma_f32_16x16x32_bf16 v[72:75], v[144:147], v[172:175], v[72:75]
	v_mfma_f32_16x16x32_bf16 v[68:71], v[152:155], v[172:175], v[68:71]
	s_waitcnt lgkmcnt(3)
	v_mfma_f32_16x16x32_bf16 v[48:51], v[128:131], v[176:179], v[48:51]
	ds_read_b128 v[168:171], v240 offset:32768
	v_mfma_f32_16x16x32_bf16 v[52:55], v[136:139], v[176:179], v[52:55]
	v_mfma_f32_16x16x32_bf16 v[56:59], v[144:147], v[176:179], v[56:59]
	v_mfma_f32_16x16x32_bf16 v[36:39], v[152:155], v[176:179], v[36:39]
	s_waitcnt lgkmcnt(3)
	v_mfma_f32_16x16x32_bf16 v[8:11], v[128:131], v[180:183], v[8:11]
	ds_read_b128 v[172:175], v240 offset:34816
	v_mfma_f32_16x16x32_bf16 v[12:15], v[136:139], v[180:183], v[12:15]
	v_mfma_f32_16x16x32_bf16 v[24:27], v[144:147], v[180:183], v[24:27]
	v_mfma_f32_16x16x32_bf16 v[32:35], v[152:155], v[180:183], v[32:35]
	s_waitcnt lgkmcnt(3)
	v_mfma_f32_16x16x32_bf16 v[0:3], v[128:131], v[160:163], v[0:3]
	ds_read_b128 v[176:179], v240 offset:36864
	v_mfma_f32_16x16x32_bf16 v[4:7], v[136:139], v[160:163], v[4:7]
	v_mfma_f32_16x16x32_bf16 v[44:47], v[144:147], v[160:163], v[44:47]
	v_mfma_f32_16x16x32_bf16 v[40:43], v[152:155], v[160:163], v[40:43]
	s_waitcnt lgkmcnt(3)
	v_mfma_f32_16x16x32_bf16 v[28:31], v[128:131], v[164:167], v[28:31]
	ds_read_b128 v[180:183], v240 offset:38912
	v_mfma_f32_16x16x32_bf16 v[20:23], v[136:139], v[164:167], v[20:23]
	v_mfma_f32_16x16x32_bf16 v[16:19], v[144:147], v[164:167], v[16:19]
	v_mfma_f32_16x16x32_bf16 v[60:63], v[152:155], v[164:167], v[60:63]
	s_waitcnt lgkmcnt(3)
	v_mfma_f32_16x16x32_bf16 v[124:127], v[132:135], v[168:171], v[124:127]
	ds_read_b128 v[160:163], v240 offset:40960
	v_mfma_f32_16x16x32_bf16 v[120:123], v[140:143], v[168:171], v[120:123]
	v_mfma_f32_16x16x32_bf16 v[116:119], v[148:151], v[168:171], v[116:119]
	v_mfma_f32_16x16x32_bf16 v[112:115], v[156:159], v[168:171], v[112:115]
	s_waitcnt lgkmcnt(3)
	v_mfma_f32_16x16x32_bf16 v[108:111], v[132:135], v[172:175], v[108:111]
	ds_read_b128 v[164:167], v240 offset:43008
	v_mfma_f32_16x16x32_bf16 v[104:107], v[140:143], v[172:175], v[104:107]
	v_mfma_f32_16x16x32_bf16 v[100:103], v[148:151], v[172:175], v[100:103]
	v_mfma_f32_16x16x32_bf16 v[96:99], v[156:159], v[172:175], v[96:99]
	s_waitcnt lgkmcnt(3)
	v_mfma_f32_16x16x32_bf16 v[92:95], v[132:135], v[176:179], v[92:95]
	ds_read_b128 v[168:171], v240 offset:45056
	v_mfma_f32_16x16x32_bf16 v[88:91], v[140:143], v[176:179], v[88:91]
	v_mfma_f32_16x16x32_bf16 v[84:87], v[148:151], v[176:179], v[84:87]
	v_mfma_f32_16x16x32_bf16 v[80:83], v[156:159], v[176:179], v[80:83]
	s_waitcnt lgkmcnt(3)
	v_mfma_f32_16x16x32_bf16 v[76:79], v[132:135], v[180:183], v[76:79]
	ds_read_b128 v[172:175], v240 offset:47104
	v_mfma_f32_16x16x32_bf16 v[64:67], v[140:143], v[180:183], v[64:67]
	v_mfma_f32_16x16x32_bf16 v[72:75], v[148:151], v[180:183], v[72:75]
	v_mfma_f32_16x16x32_bf16 v[68:71], v[156:159], v[180:183], v[68:71]
	s_waitcnt lgkmcnt(3)
	v_mfma_f32_16x16x32_bf16 v[48:51], v[132:135], v[160:163], v[48:51]
	v_mfma_f32_16x16x32_bf16 v[52:55], v[140:143], v[160:163], v[52:55]
	v_mfma_f32_16x16x32_bf16 v[56:59], v[148:151], v[160:163], v[56:59]
	v_mfma_f32_16x16x32_bf16 v[36:39], v[156:159], v[160:163], v[36:39]
	s_waitcnt lgkmcnt(2)
	v_mfma_f32_16x16x32_bf16 v[8:11], v[132:135], v[164:167], v[8:11]
	v_mfma_f32_16x16x32_bf16 v[12:15], v[140:143], v[164:167], v[12:15]
	v_mfma_f32_16x16x32_bf16 v[24:27], v[148:151], v[164:167], v[24:27]
	v_mfma_f32_16x16x32_bf16 v[32:35], v[156:159], v[164:167], v[32:35]
	s_waitcnt lgkmcnt(1)
	v_mfma_f32_16x16x32_bf16 v[0:3], v[132:135], v[168:171], v[0:3]
	v_mfma_f32_16x16x32_bf16 v[4:7], v[140:143], v[168:171], v[4:7]
	v_mfma_f32_16x16x32_bf16 v[44:47], v[148:151], v[168:171], v[44:47]
	v_mfma_f32_16x16x32_bf16 v[40:43], v[156:159], v[168:171], v[40:43]
	s_waitcnt lgkmcnt(0)
	v_mfma_f32_16x16x32_bf16 v[28:31], v[132:135], v[172:175], v[28:31]
	v_mfma_f32_16x16x32_bf16 v[20:23], v[140:143], v[172:175], v[20:23]
	v_mfma_f32_16x16x32_bf16 v[16:19], v[148:151], v[172:175], v[16:19]
	v_mfma_f32_16x16x32_bf16 v[60:63], v[156:159], v[172:175], v[60:63]
	s_nop 7
	s_nop 7
	s_barrier
	ds_write_b64 v194, v[192:193]
	v_mov_b32_e32 v152, v120
	v_mov_b32_e32 v153, v121
	v_mov_b32_e32 v154, v122
	v_mov_b32_e32 v155, v123
	s_movk_i32 s4, 0xc00
	v_mov_b32_e32 v160, v116
	v_mov_b32_e32 v161, v117
	v_mov_b32_e32 v162, v118
	v_mov_b32_e32 v163, v119
	v_mov_b32_e32 v192, v68
	v_mov_b32_e32 v193, v69
	v_mov_b32_e32 v194, v70
	v_mov_b32_e32 v195, v71
	v_mov_b32_e32 v230, v56
	v_mov_b32_e32 v231, v57
	v_mov_b32_e32 v232, v58
	v_mov_b32_e32 v233, v59
	v_mov_b32_e32 v246, v40
	v_mov_b32_e32 v247, v41
	v_mov_b32_e32 v248, v42
	v_mov_b32_e32 v249, v43
	v_mov_b32_e32 v180, v72
	v_mov_b32_e32 v181, v73
	v_mov_b32_e32 v182, v74
	v_mov_b32_e32 v183, v75
	v_mov_b32_e32 v242, v44
	v_mov_b32_e32 v243, v45
	v_mov_b32_e32 v244, v46
	v_mov_b32_e32 v245, v47
	v_mov_b32_e32 v208, v28
	v_mov_b32_e32 v209, v29
	v_mov_b32_e32 v210, v30
	v_mov_b32_e32 v211, v31
	v_mov_b32_e32 v148, v20
	v_mov_b32_e32 v149, v21
	v_mov_b32_e32 v150, v22
	v_mov_b32_e32 v151, v23
	v_mov_b32_e32 v156, v16
	v_mov_b32_e32 v157, v17
	v_mov_b32_e32 v158, v18
	v_mov_b32_e32 v159, v19
	v_mov_b32_e32 v164, v60
	v_mov_b32_e32 v165, v61
	v_mov_b32_e32 v166, v62
	v_mov_b32_e32 v167, v63
	v_mov_b32_e32 v28, v0
	v_mov_b32_e32 v29, v1
	v_mov_b32_e32 v30, v2
	v_mov_b32_e32 v31, v3
	v_or_b32_e32 v0, s16, v199
	v_mov_b32_e32 v140, v124
	v_mov_b32_e32 v141, v125
	v_mov_b32_e32 v142, v126
	v_mov_b32_e32 v143, v127
	v_cmp_ne_u32_e64 s[4:5], s4, v0
	v_mov_b32_e32 v128, v152
	v_mov_b32_e32 v129, v153
	v_mov_b32_e32 v130, v154
	v_mov_b32_e32 v131, v155
	v_mov_b32_e32 v124, v160
	v_mov_b32_e32 v125, v161
	v_mov_b32_e32 v126, v162
	v_mov_b32_e32 v127, v163
	v_mov_b32_e32 v72, v64
	v_mov_b32_e32 v73, v65
	v_mov_b32_e32 v74, v66
	v_mov_b32_e32 v75, v67
	v_mov_b32_e32 v68, v180
	v_mov_b32_e32 v69, v181
	v_mov_b32_e32 v70, v182
	v_mov_b32_e32 v71, v183
	v_mov_b32_e32 v64, v192
	v_mov_b32_e32 v65, v193
	v_mov_b32_e32 v66, v194
	v_mov_b32_e32 v67, v195
	v_mov_b32_e32 v60, v48
	v_mov_b32_e32 v61, v49
	v_mov_b32_e32 v62, v50
	v_mov_b32_e32 v63, v51
	v_mov_b32_e32 v56, v52
	v_mov_b32_e32 v57, v53
	v_mov_b32_e32 v58, v54
	v_mov_b32_e32 v59, v55
	v_mov_b32_e32 v52, v230
	v_mov_b32_e32 v53, v231
	v_mov_b32_e32 v54, v232
	v_mov_b32_e32 v55, v233
	v_mov_b32_e32 v48, v36
	v_mov_b32_e32 v49, v37
	v_mov_b32_e32 v50, v38
	v_mov_b32_e32 v51, v39
	v_mov_b32_e32 v44, v8
	v_mov_b32_e32 v45, v9
	v_mov_b32_e32 v46, v10
	v_mov_b32_e32 v47, v11
	v_mov_b32_e32 v40, v12
	v_mov_b32_e32 v41, v13
	v_mov_b32_e32 v42, v14
	v_mov_b32_e32 v43, v15
	v_mov_b32_e32 v36, v24
	v_mov_b32_e32 v37, v25
	v_mov_b32_e32 v38, v26
	v_mov_b32_e32 v39, v27
	v_mov_b32_e32 v24, v4
	v_mov_b32_e32 v25, v5
	v_mov_b32_e32 v26, v6
	v_mov_b32_e32 v27, v7
	v_mov_b32_e32 v20, v242
	v_mov_b32_e32 v21, v243
	v_mov_b32_e32 v22, v244
	v_mov_b32_e32 v23, v245
	v_mov_b32_e32 v12, v246
	v_mov_b32_e32 v13, v247
	v_mov_b32_e32 v14, v248
	v_mov_b32_e32 v15, v249
	v_mov_b32_e32 v16, v208
	v_mov_b32_e32 v17, v209
	v_mov_b32_e32 v18, v210
	v_mov_b32_e32 v19, v211
	v_mov_b32_e32 v8, v148
	v_mov_b32_e32 v9, v149
	v_mov_b32_e32 v10, v150
	v_mov_b32_e32 v11, v151
	v_mov_b32_e32 v4, v156
	v_mov_b32_e32 v5, v157
	v_mov_b32_e32 v6, v158
	v_mov_b32_e32 v7, v159
	v_mov_b32_e32 v0, v164
	v_mov_b32_e32 v1, v165
	v_mov_b32_e32 v2, v166
	v_mov_b32_e32 v3, v167
	s_and_saveexec_b64 s[8:9], s[4:5]
	s_xor_b64 s[8:9], exec, s[8:9]
	s_or_saveexec_b64 s[8:9], s[8:9]
	v_add_u32_e32 v120, s6, v197
	v_or_b32_e32 v116, v120, v198
	v_lshlrev_b32_e32 v116, 6, v116
	v_ashrrev_i32_e32 v117, 31, v116
	v_or_b32_e32 v184, s16, v200
	v_lshl_add_u64 v[116:117], v[116:117], 2, s[12:13]
	s_xor_b64 exec, exec, s[8:9]
	s_cbranch_execz .LBB0_263
	v_lshl_add_u64 v[118:119], v[184:185], 2, v[116:117]
	v_add_co_u32_e32 v118, vcc, 0xffffd000, v118
	s_nop 1
	v_addc_co_u32_e32 v119, vcc, -1, v119, vcc
	global_store_dwordx4 v[118:119], v[140:143], off

.LBB0_412:
	s_ashr_i32 s0, s22, 6
	s_mul_i32 s0, s0, s17
	s_add_i32 s0, s0, s15
	s_cmp_gt_i32 s0, 31
	s_mov_b32 s6, 2
	s_cbranch_scc1 .LBB0_499
	s_ashr_i32 s1, s0, 31
	s_lshr_b32 s1, s1, 29
	s_add_i32 s5, s0, s1
	s_and_b32 s1, s5, -8
	s_and_b32 s4, s22, 7
	s_or_b32 s4, s1, s4
	s_sub_i32 s1, s0, s1
	s_lshl_b32 s6, s1, 3
	s_bfe_u32 s1, s22, 0x30003
	s_or_b32 s7, s6, s1
	s_cmp_gt_i32 s4, 31
	s_cselect_b64 s[10:11], -1, 0
	s_cmp_gt_i32 s7, 56
	s_cselect_b64 s[12:13], -1, 0
	s_or_b64 s[10:11], s[10:11], s[12:13]
	s_mov_b32 s6, 4
	s_and_b64 vcc, exec, s[10:11]
	s_cbranch_vccnz .LBB0_499
	s_ashr_i32 s23, s5, 3
	s_and_b32 s5, s16, 7
	s_lshl_b32 s4, s4, 8
	s_lshl_b32 s24, s5, 8
	s_ashr_i32 s5, s4, 31
	s_lshl_b64 s[12:13], s[4:5], 11
	v_lshl_add_u64 v[0:1], v[186:187], 0, s[12:13]
	v_add_co_u32_e32 v2, vcc, 0x10000, v0
	s_lshl_b32 s10, s7, 7
	s_nop 0
	v_addc_co_u32_e32 v3, vcc, 0, v1, vcc
	s_nop 0
	v_readfirstlane_b32 s98, v0
	v_readfirstlane_b32 s99, v1
	v_add_co_u32_e32 v2, vcc, 0x20000, v0
	s_ashr_i32 s11, s10, 31
	s_nop 0
	v_addc_co_u32_e32 v3, vcc, 0, v1, vcc
	v_add_co_u32_e32 v4, vcc, 0x30000, v0
	s_lshl_b64 s[6:7], s[10:11], 11
	s_nop 0
	v_addc_co_u32_e32 v5, vcc, 0, v1, vcc
	v_add_co_u32_e32 v2, vcc, 0x40000, v0
	s_mov_b32 s5, 0x10000
	s_nop 0
	v_addc_co_u32_e32 v3, vcc, 0, v1, vcc
	v_add_co_u32_e32 v4, vcc, 0x50000, v0
	s_lshl_b32 s0, s0, 3
	s_nop 0
	v_addc_co_u32_e32 v5, vcc, 0, v1, vcc
	v_add_co_u32_e32 v2, vcc, 0x60000, v0
	s_or_b32 s0, s0, s1
	s_nop 0
	v_addc_co_u32_e32 v3, vcc, 0, v1, vcc
	v_add_co_u32_e32 v0, vcc, 0x70000, v0
	s_lshl_b32 s1, s23, 6
	s_nop 0
	v_addc_co_u32_e32 v1, vcc, 0, v1, vcc
	v_lshl_add_u64 v[0:1], v[188:189], 0, s[6:7]
	v_add_co_u32_e32 v2, vcc, s5, v0
	s_mov_b32 s5, 0x20000
	s_nop 0
	v_addc_co_u32_e32 v3, vcc, 0, v1, vcc
	s_nop 0
	v_readfirstlane_b32 s100, v0
	v_readfirstlane_b32 s101, v1
	v_add_co_u32_e32 v2, vcc, s5, v0
	s_mov_b32 s5, 0x30000
	s_nop 0
	v_addc_co_u32_e32 v3, vcc, 0, v1, vcc
	v_add_co_u32_e32 v0, vcc, s5, v0
	s_lshl_b32 s5, s23, 11
	s_nop 0
	v_addc_co_u32_e32 v1, vcc, 0, v1, vcc
	s_sub_i32 s0, s0, s1
	s_or_b32 s6, s5, s24
	s_lshl_b32 s0, s0, 7
	s_ashr_i32 s7, s6, 31
	s_ashr_i32 s1, s0, 31
	s_lshl_b64 s[6:7], s[6:7], 11
	s_lshl_b64 s[0:1], s[0:1], 11
	v_mov_b32_e32 v124, 0
	v_lshl_add_u64 v[192:193], v[190:191], 0, s[6:7]
	v_lshl_add_u64 v[194:195], v[190:191], 0, s[0:1]
	s_mov_b64 s[0:1], 0
	v_mov_b32_e32 v125, v124
	v_mov_b32_e32 v126, v124
	v_mov_b32_e32 v127, v124
	v_mov_b32_e32 v80, v124
	v_mov_b32_e32 v81, v124
	v_mov_b32_e32 v82, v124
	v_mov_b32_e32 v83, v124
	v_mov_b32_e32 v88, v124
	v_mov_b32_e32 v89, v124
	v_mov_b32_e32 v90, v124
	v_mov_b32_e32 v91, v124
	v_mov_b32_e32 v92, v124
	v_mov_b32_e32 v93, v124
	v_mov_b32_e32 v94, v124
	v_mov_b32_e32 v95, v124
	v_mov_b32_e32 v100, v124
	v_mov_b32_e32 v101, v124
	v_mov_b32_e32 v102, v124
	v_mov_b32_e32 v103, v124
	v_mov_b32_e32 v104, v124
	v_mov_b32_e32 v105, v124
	v_mov_b32_e32 v106, v124
	v_mov_b32_e32 v107, v124
	v_mov_b32_e32 v48, v124
	v_mov_b32_e32 v49, v124
	v_mov_b32_e32 v50, v124
	v_mov_b32_e32 v51, v124
	v_mov_b32_e32 v40, v124
	v_mov_b32_e32 v41, v124
	v_mov_b32_e32 v42, v124
	v_mov_b32_e32 v43, v124
	v_mov_b32_e32 v52, v124
	v_mov_b32_e32 v53, v124
	v_mov_b32_e32 v54, v124
	v_mov_b32_e32 v55, v124
	v_mov_b32_e32 v44, v124
	v_mov_b32_e32 v45, v124
	v_mov_b32_e32 v46, v124
	v_mov_b32_e32 v47, v124
	v_mov_b32_e32 v32, v124
	v_mov_b32_e32 v33, v124
	v_mov_b32_e32 v34, v124
	v_mov_b32_e32 v35, v124
	v_mov_b32_e32 v12, v124
	v_mov_b32_e32 v13, v124
	v_mov_b32_e32 v14, v124
	v_mov_b32_e32 v15, v124
	v_mov_b32_e32 v36, v124
	v_mov_b32_e32 v37, v124
	v_mov_b32_e32 v38, v124
	v_mov_b32_e32 v39, v124
	v_mov_b32_e32 v16, v124
	v_mov_b32_e32 v17, v124
	v_mov_b32_e32 v18, v124
	v_mov_b32_e32 v19, v124
	v_mov_b32_e32 v8, v124
	v_mov_b32_e32 v9, v124
	v_mov_b32_e32 v10, v124
	v_mov_b32_e32 v11, v124
	v_mov_b32_e32 v0, v124
	v_mov_b32_e32 v1, v124
	v_mov_b32_e32 v2, v124
	v_mov_b32_e32 v3, v124
	v_mov_b32_e32 v20, v124
	v_mov_b32_e32 v21, v124
	v_mov_b32_e32 v22, v124
	v_mov_b32_e32 v23, v124
	v_mov_b32_e32 v24, v124
	v_mov_b32_e32 v25, v124
	v_mov_b32_e32 v26, v124
	v_mov_b32_e32 v27, v124
	v_mov_b32_e32 v4, v124
	v_mov_b32_e32 v5, v124
	v_mov_b32_e32 v6, v124
	v_mov_b32_e32 v7, v124
	v_mov_b32_e32 v28, v124
	v_mov_b32_e32 v29, v124
	v_mov_b32_e32 v30, v124
	v_mov_b32_e32 v31, v124
	v_mov_b32_e32 v56, v124
	v_mov_b32_e32 v57, v124
	v_mov_b32_e32 v58, v124
	v_mov_b32_e32 v59, v124
	v_mov_b32_e32 v60, v124
	v_mov_b32_e32 v61, v124
	v_mov_b32_e32 v62, v124
	v_mov_b32_e32 v63, v124
	v_mov_b32_e32 v64, v124
	v_mov_b32_e32 v65, v124
	v_mov_b32_e32 v66, v124
	v_mov_b32_e32 v67, v124
	v_mov_b32_e32 v68, v124
	v_mov_b32_e32 v69, v124
	v_mov_b32_e32 v70, v124
	v_mov_b32_e32 v71, v124
	v_mov_b32_e32 v72, v124
	v_mov_b32_e32 v73, v124
	v_mov_b32_e32 v74, v124
	v_mov_b32_e32 v75, v124
	v_mov_b32_e32 v76, v124
	v_mov_b32_e32 v77, v124
	v_mov_b32_e32 v78, v124
	v_mov_b32_e32 v79, v124
	v_mov_b32_e32 v84, v124
	v_mov_b32_e32 v85, v124
	v_mov_b32_e32 v86, v124
	v_mov_b32_e32 v87, v124
	v_mov_b32_e32 v96, v124
	v_mov_b32_e32 v97, v124
	v_mov_b32_e32 v98, v124
	v_mov_b32_e32 v99, v124
	v_mov_b32_e32 v108, v124
	v_mov_b32_e32 v109, v124
	v_mov_b32_e32 v110, v124
	v_mov_b32_e32 v111, v124
	v_mov_b32_e32 v112, v124
	v_mov_b32_e32 v113, v124
	v_mov_b32_e32 v114, v124
	v_mov_b32_e32 v115, v124
	v_mov_b32_e32 v116, v124
	v_mov_b32_e32 v117, v124
	v_mov_b32_e32 v118, v124
	v_mov_b32_e32 v119, v124
	v_mov_b32_e32 v120, v124
	v_mov_b32_e32 v121, v124
	v_mov_b32_e32 v122, v124
	v_mov_b32_e32 v123, v124
	v_mov_b32_e32 v194, 0
	ds_read_b64 v[192:193], v194
	v_and_b32_e32 v195, 63, v196
	v_lshrrev_b32_e32 v246, 3, v195
	v_and_b32_e32 v243, 7, v195
	v_xor_b32_e32 v243, v243, v246
	v_lshlrev_b32_e32 v243, 4, v243
	v_mul_u32_u24_e32 v246, 2048, v246
	v_add_u32_e32 v223, v246, v243
	v_add_u32_e32 v224, 65536, v223
	v_add_u32_e32 v225, 131072, v223
	v_add_u32_e32 v226, 196608, v223
	v_add_u32_e32 v252, 262144, v223
	v_add_u32_e32 v251, 327680, v223
	v_add_u32_e32 v248, 393216, v223
	v_add_u32_e32 v249, 458752, v223
	v_lshrrev_b32_e32 v246, 6, v196
	v_lshrrev_b32_e32 v243, 1, v246
	v_and_b32_e32 v246, 1, v246
	v_and_b32_e32 v240, 15, v195
	v_lshrrev_b32_e32 v241, 4, v195
	v_and_b32_e32 v242, 7, v240
	v_xor_b32_e32 v241, v241, v242
	v_lshlrev_b32_e32 v241, 4, v241
	v_lshlrev_b32_e32 v243, 7, v243
	v_add_u32_e32 v243, v243, v240
	v_lshl_add_u32 v250, v243, 7, v241
	v_xor_b32_e32 v247, 64, v250
	v_lshlrev_b32_e32 v246, 6, v246
	v_add_u32_e32 v246, v246, v240
	v_lshl_add_u32 v244, v246, 7, v241
	v_add_u32_e32 v244, 65536, v244
	v_xor_b32_e32 v245, 64, v244
	v_lshrrev_b32_e32 v246, 6, v196
	v_lshlrev_b32_e32 v246, 10, v246
	s_nop 0
	v_readfirstlane_b32 s0, v246
	s_waitcnt lgkmcnt(0)
	s_barrier
	s_add_u32 m0, s0, 0
	s_nop 0
	global_load_lds_dwordx4 v223, s[98:99]
	s_add_u32 m0, s0, 4096
	s_nop 0
	global_load_lds_dwordx4 v224, s[98:99]
	s_add_u32 m0, s0, 8192
	s_nop 0
	global_load_lds_dwordx4 v225, s[98:99]
	s_add_u32 m0, s0, 12288
	s_nop 0
	global_load_lds_dwordx4 v226, s[98:99]
	s_add_u32 m0, s0, 16384
	s_nop 0
	global_load_lds_dwordx4 v252, s[98:99]
	s_add_u32 m0, s0, 20480
	s_nop 0
	global_load_lds_dwordx4 v251, s[98:99]
	s_add_u32 m0, s0, 24576
	s_nop 0
	global_load_lds_dwordx4 v248, s[98:99]
	s_add_u32 m0, s0, 28672
	s_nop 0
	global_load_lds_dwordx4 v249, s[98:99]
	s_add_u32 m0, s0, 65536
	s_nop 0
	global_load_lds_dwordx4 v223, s[100:101]
	s_add_u32 m0, s0, 69632
	s_nop 0
	global_load_lds_dwordx4 v224, s[100:101]
	s_add_u32 m0, s0, 73728
	s_nop 0
	global_load_lds_dwordx4 v225, s[100:101]
	s_add_u32 m0, s0, 77824
	s_nop 0
	global_load_lds_dwordx4 v226, s[100:101]
	s_add_u32 s98, s98, 0x80
	s_addc_u32 s99, s99, 0
	s_add_u32 s100, s100, 0x80
	s_addc_u32 s101, s101, 0
	s_mov_b32 s1, 7
.Lg8p3_loop:
	s_waitcnt vmcnt(0) lgkmcnt(0)
	s_barrier
	s_add_u32 m0, s0, 32768
	ds_read_b128 v[128:131], v244 offset:0
	global_load_lds_dwordx4 v223, s[98:99]
	s_add_u32 m0, s0, 36864
	ds_read_b128 v[136:139], v244 offset:2048
	global_load_lds_dwordx4 v224, s[98:99]
	s_add_u32 m0, s0, 40960
	ds_read_b128 v[144:147], v244 offset:4096
	global_load_lds_dwordx4 v225, s[98:99]
	s_add_u32 m0, s0, 45056
	ds_read_b128 v[152:155], v244 offset:6144
	global_load_lds_dwordx4 v226, s[98:99]
	s_add_u32 m0, s0, 49152
	ds_read_b128 v[132:135], v245 offset:0
	global_load_lds_dwordx4 v252, s[98:99]
	s_add_u32 m0, s0, 53248
	ds_read_b128 v[140:143], v245 offset:2048
	global_load_lds_dwordx4 v251, s[98:99]
	s_add_u32 m0, s0, 57344
	ds_read_b128 v[148:151], v245 offset:4096
	global_load_lds_dwordx4 v248, s[98:99]
	s_add_u32 m0, s0, 61440
	ds_read_b128 v[156:159], v245 offset:6144
	global_load_lds_dwordx4 v249, s[98:99]
	ds_read_b128 v[160:163], v250 offset:0
	ds_read_b128 v[164:167], v250 offset:2048
	ds_read_b128 v[168:171], v250 offset:4096
	ds_read_b128 v[172:175], v250 offset:6144
	s_waitcnt lgkmcnt(4)
	s_barrier
	s_waitcnt lgkmcnt(3)
	s_add_u32 m0, s0, 65536
	v_mfma_f32_16x16x32_bf16 v[120:123], v[128:131], v[160:163], v[120:123]
	ds_read_b128 v[176:179], v250 offset:8192
	global_load_lds_dwordx4 v223, s[100:101]
	v_mfma_f32_16x16x32_bf16 v[116:119], v[136:139], v[160:163], v[116:119]
	s_add_u32 m0, s0, 69632
	v_mfma_f32_16x16x32_bf16 v[112:115], v[144:147], v[160:163], v[112:115]
	global_load_lds_dwordx4 v224, s[100:101]
	v_mfma_f32_16x16x32_bf16 v[108:111], v[152:155], v[160:163], v[108:111]
	s_waitcnt lgkmcnt(3)
	s_add_u32 m0, s0, 73728
	v_mfma_f32_16x16x32_bf16 v[96:99], v[128:131], v[164:167], v[96:99]
	ds_read_b128 v[180:183], v250 offset:10240
	global_load_lds_dwordx4 v225, s[100:101]
	v_mfma_f32_16x16x32_bf16 v[84:87], v[136:139], v[164:167], v[84:87]
	s_add_u32 m0, s0, 77824
	v_mfma_f32_16x16x32_bf16 v[76:79], v[144:147], v[164:167], v[76:79]
	global_load_lds_dwordx4 v226, s[100:101]
	v_mfma_f32_16x16x32_bf16 v[72:75], v[152:155], v[164:167], v[72:75]
	s_waitcnt lgkmcnt(3)
	v_mfma_f32_16x16x32_bf16 v[68:71], v[128:131], v[168:171], v[68:71]
	ds_read_b128 v[160:163], v250 offset:12288
	v_mfma_f32_16x16x32_bf16 v[64:67], v[136:139], v[168:171], v[64:67]
	v_mfma_f32_16x16x32_bf16 v[60:63], v[144:147], v[168:171], v[60:63]
	v_mfma_f32_16x16x32_bf16 v[56:59], v[152:155], v[168:171], v[56:59]
	s_waitcnt lgkmcnt(3)
	v_mfma_f32_16x16x32_bf16 v[28:31], v[128:131], v[172:175], v[28:31]
	ds_read_b128 v[164:167], v250 offset:14336
	v_mfma_f32_16x16x32_bf16 v[4:7], v[136:139], v[172:175], v[4:7]
	v_mfma_f32_16x16x32_bf16 v[24:27], v[144:147], v[172:175], v[24:27]
	v_mfma_f32_16x16x32_bf16 v[20:23], v[152:155], v[172:175], v[20:23]
	s_waitcnt lgkmcnt(3)
	v_mfma_f32_16x16x32_bf16 v[0:3], v[128:131], v[176:179], v[0:3]
	ds_read_b128 v[168:171], v247 offset:0
	v_mfma_f32_16x16x32_bf16 v[8:11], v[136:139], v[176:179], v[8:11]
	v_mfma_f32_16x16x32_bf16 v[16:19], v[144:147], v[176:179], v[16:19]
	v_mfma_f32_16x16x32_bf16 v[36:39], v[152:155], v[176:179], v[36:39]
	s_waitcnt lgkmcnt(3)
	v_mfma_f32_16x16x32_bf16 v[12:15], v[128:131], v[180:183], v[12:15]
	ds_read_b128 v[172:175], v247 offset:2048
	v_mfma_f32_16x16x32_bf16 v[32:35], v[136:139], v[180:183], v[32:35]
	v_mfma_f32_16x16x32_bf16 v[44:47], v[144:147], v[180:183], v[44:47]
	v_mfma_f32_16x16x32_bf16 v[52:55], v[152:155], v[180:183], v[52:55]
	s_waitcnt lgkmcnt(3)
	v_mfma_f32_16x16x32_bf16 v[40:43], v[128:131], v[160:163], v[40:43]
	ds_read_b128 v[176:179], v247 offset:4096
	v_mfma_f32_16x16x32_bf16 v[48:51], v[136:139], v[160:163], v[48:51]
	v_mfma_f32_16x16x32_bf16 v[104:107], v[144:147], v[160:163], v[104:107]
	v_mfma_f32_16x16x32_bf16 v[100:103], v[152:155], v[160:163], v[100:103]
	s_waitcnt lgkmcnt(3)
	v_mfma_f32_16x16x32_bf16 v[92:95], v[128:131], v[164:167], v[92:95]
	ds_read_b128 v[180:183], v247 offset:6144
	v_mfma_f32_16x16x32_bf16 v[88:91], v[136:139], v[164:167], v[88:91]
	v_mfma_f32_16x16x32_bf16 v[80:83], v[144:147], v[164:167], v[80:83]
	v_mfma_f32_16x16x32_bf16 v[124:127], v[152:155], v[164:167], v[124:127]
	s_waitcnt lgkmcnt(3)
	v_mfma_f32_16x16x32_bf16 v[120:123], v[132:135], v[168:171], v[120:123]
	ds_read_b128 v[160:163], v247 offset:8192
	v_mfma_f32_16x16x32_bf16 v[116:119], v[140:143], v[168:171], v[116:119]
	v_mfma_f32_16x16x32_bf16 v[112:115], v[148:151], v[168:171], v[112:115]
	v_mfma_f32_16x16x32_bf16 v[108:111], v[156:159], v[168:171], v[108:111]
	s_waitcnt lgkmcnt(3)
	v_mfma_f32_16x16x32_bf16 v[96:99], v[132:135], v[172:175], v[96:99]
	ds_read_b128 v[164:167], v247 offset:10240
	v_mfma_f32_16x16x32_bf16 v[84:87], v[140:143], v[172:175], v[84:87]
	v_mfma_f32_16x16x32_bf16 v[76:79], v[148:151], v[172:175], v[76:79]
	v_mfma_f32_16x16x32_bf16 v[72:75], v[156:159], v[172:175], v[72:75]
	s_waitcnt lgkmcnt(3)
	v_mfma_f32_16x16x32_bf16 v[68:71], v[132:135], v[176:179], v[68:71]
	ds_read_b128 v[168:171], v247 offset:12288
	v_mfma_f32_16x16x32_bf16 v[64:67], v[140:143], v[176:179], v[64:67]
	v_mfma_f32_16x16x32_bf16 v[60:63], v[148:151], v[176:179], v[60:63]
	v_mfma_f32_16x16x32_bf16 v[56:59], v[156:159], v[176:179], v[56:59]
	s_waitcnt lgkmcnt(3)
	v_mfma_f32_16x16x32_bf16 v[28:31], v[132:135], v[180:183], v[28:31]
	ds_read_b128 v[172:175], v247 offset:14336
	v_mfma_f32_16x16x32_bf16 v[4:7], v[140:143], v[180:183], v[4:7]
	v_mfma_f32_16x16x32_bf16 v[24:27], v[148:151], v[180:183], v[24:27]
	v_mfma_f32_16x16x32_bf16 v[20:23], v[156:159], v[180:183], v[20:23]
	s_waitcnt lgkmcnt(3)
	v_mfma_f32_16x16x32_bf16 v[0:3], v[132:135], v[160:163], v[0:3]
	v_mfma_f32_16x16x32_bf16 v[8:11], v[140:143], v[160:163], v[8:11]
	v_mfma_f32_16x16x32_bf16 v[16:19], v[148:151], v[160:163], v[16:19]
	v_mfma_f32_16x16x32_bf16 v[36:39], v[156:159], v[160:163], v[36:39]
	s_waitcnt lgkmcnt(2)
	v_mfma_f32_16x16x32_bf16 v[12:15], v[132:135], v[164:167], v[12:15]
	v_mfma_f32_16x16x32_bf16 v[32:35], v[140:143], v[164:167], v[32:35]
	v_mfma_f32_16x16x32_bf16 v[44:47], v[148:151], v[164:167], v[44:47]
	v_mfma_f32_16x16x32_bf16 v[52:55], v[156:159], v[164:167], v[52:55]
	s_waitcnt lgkmcnt(1)
	v_mfma_f32_16x16x32_bf16 v[40:43], v[132:135], v[168:171], v[40:43]
	v_mfma_f32_16x16x32_bf16 v[48:51], v[140:143], v[168:171], v[48:51]
	v_mfma_f32_16x16x32_bf16 v[104:107], v[148:151], v[168:171], v[104:107]
	v_mfma_f32_16x16x32_bf16 v[100:103], v[156:159], v[168:171], v[100:103]
	s_waitcnt lgkmcnt(0)
	v_mfma_f32_16x16x32_bf16 v[92:95], v[132:135], v[172:175], v[92:95]
	v_mfma_f32_16x16x32_bf16 v[88:91], v[140:143], v[172:175], v[88:91]
	v_mfma_f32_16x16x32_bf16 v[80:83], v[148:151], v[172:175], v[80:83]
	v_mfma_f32_16x16x32_bf16 v[124:127], v[156:159], v[172:175], v[124:127]
	s_add_u32 s98, s98, 0x80
	s_addc_u32 s99, s99, 0
	s_add_u32 s100, s100, 0x80
	s_addc_u32 s101, s101, 0
	s_waitcnt vmcnt(0) lgkmcnt(0)
	s_barrier
	s_add_u32 m0, s0, 0
	ds_read_b128 v[128:131], v244 offset:0
	global_load_lds_dwordx4 v223, s[98:99]
	s_add_u32 m0, s0, 4096
	ds_read_b128 v[136:139], v244 offset:2048
	global_load_lds_dwordx4 v224, s[98:99]
	s_add_u32 m0, s0, 8192
	ds_read_b128 v[144:147], v244 offset:4096
	global_load_lds_dwordx4 v225, s[98:99]
	s_add_u32 m0, s0, 12288
	ds_read_b128 v[152:155], v244 offset:6144
	global_load_lds_dwordx4 v226, s[98:99]
	s_add_u32 m0, s0, 16384
	ds_read_b128 v[132:135], v245 offset:0
	global_load_lds_dwordx4 v252, s[98:99]
	s_add_u32 m0, s0, 20480
	ds_read_b128 v[140:143], v245 offset:2048
	global_load_lds_dwordx4 v251, s[98:99]
	s_add_u32 m0, s0, 24576
	ds_read_b128 v[148:151], v245 offset:4096
	global_load_lds_dwordx4 v248, s[98:99]
	s_add_u32 m0, s0, 28672
	ds_read_b128 v[156:159], v245 offset:6144
	global_load_lds_dwordx4 v249, s[98:99]
	ds_read_b128 v[160:163], v250 offset:32768
	ds_read_b128 v[164:167], v250 offset:34816
	ds_read_b128 v[168:171], v250 offset:36864
	ds_read_b128 v[172:175], v250 offset:38912
	s_waitcnt lgkmcnt(4)
	s_barrier
	s_waitcnt lgkmcnt(3)
	s_add_u32 m0, s0, 65536
	v_mfma_f32_16x16x32_bf16 v[120:123], v[128:131], v[160:163], v[120:123]
	ds_read_b128 v[176:179], v250 offset:40960
	global_load_lds_dwordx4 v223, s[100:101]
	v_mfma_f32_16x16x32_bf16 v[116:119], v[136:139], v[160:163], v[116:119]
	s_add_u32 m0, s0, 69632
	v_mfma_f32_16x16x32_bf16 v[112:115], v[144:147], v[160:163], v[112:115]
	global_load_lds_dwordx4 v224, s[100:101]
	v_mfma_f32_16x16x32_bf16 v[108:111], v[152:155], v[160:163], v[108:111]
	s_waitcnt lgkmcnt(3)
	s_add_u32 m0, s0, 73728
	v_mfma_f32_16x16x32_bf16 v[96:99], v[128:131], v[164:167], v[96:99]
	ds_read_b128 v[180:183], v250 offset:43008
	global_load_lds_dwordx4 v225, s[100:101]
	v_mfma_f32_16x16x32_bf16 v[84:87], v[136:139], v[164:167], v[84:87]
	s_add_u32 m0, s0, 77824
	v_mfma_f32_16x16x32_bf16 v[76:79], v[144:147], v[164:167], v[76:79]
	global_load_lds_dwordx4 v226, s[100:101]
	v_mfma_f32_16x16x32_bf16 v[72:75], v[152:155], v[164:167], v[72:75]
	s_waitcnt lgkmcnt(3)
	v_mfma_f32_16x16x32_bf16 v[68:71], v[128:131], v[168:171], v[68:71]
	ds_read_b128 v[160:163], v250 offset:45056
	v_mfma_f32_16x16x32_bf16 v[64:67], v[136:139], v[168:171], v[64:67]
	v_mfma_f32_16x16x32_bf16 v[60:63], v[144:147], v[168:171], v[60:63]
	v_mfma_f32_16x16x32_bf16 v[56:59], v[152:155], v[168:171], v[56:59]
	s_waitcnt lgkmcnt(3)
	v_mfma_f32_16x16x32_bf16 v[28:31], v[128:131], v[172:175], v[28:31]
	ds_read_b128 v[164:167], v250 offset:47104
	v_mfma_f32_16x16x32_bf16 v[4:7], v[136:139], v[172:175], v[4:7]
	v_mfma_f32_16x16x32_bf16 v[24:27], v[144:147], v[172:175], v[24:27]
	v_mfma_f32_16x16x32_bf16 v[20:23], v[152:155], v[172:175], v[20:23]
	s_waitcnt lgkmcnt(3)
	v_mfma_f32_16x16x32_bf16 v[0:3], v[128:131], v[176:179], v[0:3]
	ds_read_b128 v[168:171], v247 offset:32768
	v_mfma_f32_16x16x32_bf16 v[8:11], v[136:139], v[176:179], v[8:11]
	v_mfma_f32_16x16x32_bf16 v[16:19], v[144:147], v[176:179], v[16:19]
	v_mfma_f32_16x16x32_bf16 v[36:39], v[152:155], v[176:179], v[36:39]
	s_waitcnt lgkmcnt(3)
	v_mfma_f32_16x16x32_bf16 v[12:15], v[128:131], v[180:183], v[12:15]
	ds_read_b128 v[172:175], v247 offset:34816
	v_mfma_f32_16x16x32_bf16 v[32:35], v[136:139], v[180:183], v[32:35]
	v_mfma_f32_16x16x32_bf16 v[44:47], v[144:147], v[180:183], v[44:47]
	v_mfma_f32_16x16x32_bf16 v[52:55], v[152:155], v[180:183], v[52:55]
	s_waitcnt lgkmcnt(3)
	v_mfma_f32_16x16x32_bf16 v[40:43], v[128:131], v[160:163], v[40:43]
	ds_read_b128 v[176:179], v247 offset:36864
	v_mfma_f32_16x16x32_bf16 v[48:51], v[136:139], v[160:163], v[48:51]
	v_mfma_f32_16x16x32_bf16 v[104:107], v[144:147], v[160:163], v[104:107]
	v_mfma_f32_16x16x32_bf16 v[100:103], v[152:155], v[160:163], v[100:103]
	s_waitcnt lgkmcnt(3)
	v_mfma_f32_16x16x32_bf16 v[92:95], v[128:131], v[164:167], v[92:95]
	ds_read_b128 v[180:183], v247 offset:38912
	v_mfma_f32_16x16x32_bf16 v[88:91], v[136:139], v[164:167], v[88:91]
	v_mfma_f32_16x16x32_bf16 v[80:83], v[144:147], v[164:167], v[80:83]
	v_mfma_f32_16x16x32_bf16 v[124:127], v[152:155], v[164:167], v[124:127]
	s_waitcnt lgkmcnt(3)
	v_mfma_f32_16x16x32_bf16 v[120:123], v[132:135], v[168:171], v[120:123]
	ds_read_b128 v[160:163], v247 offset:40960
	v_mfma_f32_16x16x32_bf16 v[116:119], v[140:143], v[168:171], v[116:119]
	v_mfma_f32_16x16x32_bf16 v[112:115], v[148:151], v[168:171], v[112:115]
	v_mfma_f32_16x16x32_bf16 v[108:111], v[156:159], v[168:171], v[108:111]
	s_waitcnt lgkmcnt(3)
	v_mfma_f32_16x16x32_bf16 v[96:99], v[132:135], v[172:175], v[96:99]
	ds_read_b128 v[164:167], v247 offset:43008
	v_mfma_f32_16x16x32_bf16 v[84:87], v[140:143], v[172:175], v[84:87]
	v_mfma_f32_16x16x32_bf16 v[76:79], v[148:151], v[172:175], v[76:79]
	v_mfma_f32_16x16x32_bf16 v[72:75], v[156:159], v[172:175], v[72:75]
	s_waitcnt lgkmcnt(3)
	v_mfma_f32_16x16x32_bf16 v[68:71], v[132:135], v[176:179], v[68:71]
	ds_read_b128 v[168:171], v247 offset:45056
	v_mfma_f32_16x16x32_bf16 v[64:67], v[140:143], v[176:179], v[64:67]
	v_mfma_f32_16x16x32_bf16 v[60:63], v[148:151], v[176:179], v[60:63]
	v_mfma_f32_16x16x32_bf16 v[56:59], v[156:159], v[176:179], v[56:59]
	s_waitcnt lgkmcnt(3)
	v_mfma_f32_16x16x32_bf16 v[28:31], v[132:135], v[180:183], v[28:31]
	ds_read_b128 v[172:175], v247 offset:47104
	v_mfma_f32_16x16x32_bf16 v[4:7], v[140:143], v[180:183], v[4:7]
	v_mfma_f32_16x16x32_bf16 v[24:27], v[148:151], v[180:183], v[24:27]
	v_mfma_f32_16x16x32_bf16 v[20:23], v[156:159], v[180:183], v[20:23]
	s_waitcnt lgkmcnt(3)
	v_mfma_f32_16x16x32_bf16 v[0:3], v[132:135], v[160:163], v[0:3]
	v_mfma_f32_16x16x32_bf16 v[8:11], v[140:143], v[160:163], v[8:11]
	v_mfma_f32_16x16x32_bf16 v[16:19], v[148:151], v[160:163], v[16:19]
	v_mfma_f32_16x16x32_bf16 v[36:39], v[156:159], v[160:163], v[36:39]
	s_waitcnt lgkmcnt(2)
	v_mfma_f32_16x16x32_bf16 v[12:15], v[132:135], v[164:167], v[12:15]
	v_mfma_f32_16x16x32_bf16 v[32:35], v[140:143], v[164:167], v[32:35]
	v_mfma_f32_16x16x32_bf16 v[44:47], v[148:151], v[164:167], v[44:47]
	v_mfma_f32_16x16x32_bf16 v[52:55], v[156:159], v[164:167], v[52:55]
	s_waitcnt lgkmcnt(1)
	v_mfma_f32_16x16x32_bf16 v[40:43], v[132:135], v[168:171], v[40:43]
	v_mfma_f32_16x16x32_bf16 v[48:51], v[140:143], v[168:171], v[48:51]
	v_mfma_f32_16x16x32_bf16 v[104:107], v[148:151], v[168:171], v[104:107]
	v_mfma_f32_16x16x32_bf16 v[100:103], v[156:159], v[168:171], v[100:103]
	s_waitcnt lgkmcnt(0)
	v_mfma_f32_16x16x32_bf16 v[92:95], v[132:135], v[172:175], v[92:95]
	v_mfma_f32_16x16x32_bf16 v[88:91], v[140:143], v[172:175], v[88:91]
	v_mfma_f32_16x16x32_bf16 v[80:83], v[148:151], v[172:175], v[80:83]
	v_mfma_f32_16x16x32_bf16 v[124:127], v[156:159], v[172:175], v[124:127]
	s_add_u32 s98, s98, 0x80
	s_addc_u32 s99, s99, 0
	s_add_u32 s100, s100, 0x80
	s_addc_u32 s101, s101, 0
	s_sub_u32 s1, s1, 1
	s_cmp_lg_u32 s1, 0
	s_cbranch_scc1 .Lg8p3_loop
	s_waitcnt vmcnt(0) lgkmcnt(0)
	s_barrier
	s_add_u32 m0, s0, 32768
	ds_read_b128 v[128:131], v244 offset:0
	global_load_lds_dwordx4 v223, s[98:99]
	s_add_u32 m0, s0, 36864
	ds_read_b128 v[136:139], v244 offset:2048
	global_load_lds_dwordx4 v224, s[98:99]
	s_add_u32 m0, s0, 40960
	ds_read_b128 v[144:147], v244 offset:4096
	global_load_lds_dwordx4 v225, s[98:99]
	s_add_u32 m0, s0, 45056
	ds_read_b128 v[152:155], v244 offset:6144
	global_load_lds_dwordx4 v226, s[98:99]
	s_add_u32 m0, s0, 49152
	ds_read_b128 v[132:135], v245 offset:0
	global_load_lds_dwordx4 v252, s[98:99]
	s_add_u32 m0, s0, 53248
	ds_read_b128 v[140:143], v245 offset:2048
	global_load_lds_dwordx4 v251, s[98:99]
	s_add_u32 m0, s0, 57344
	ds_read_b128 v[148:151], v245 offset:4096
	global_load_lds_dwordx4 v248, s[98:99]
	s_add_u32 m0, s0, 61440
	ds_read_b128 v[156:159], v245 offset:6144
	global_load_lds_dwordx4 v249, s[98:99]
	ds_read_b128 v[160:163], v250 offset:0
	ds_read_b128 v[164:167], v250 offset:2048
	ds_read_b128 v[168:171], v250 offset:4096
	ds_read_b128 v[172:175], v250 offset:6144
	s_waitcnt lgkmcnt(4)
	s_barrier
	s_waitcnt lgkmcnt(3)
	s_add_u32 m0, s0, 65536
	v_mfma_f32_16x16x32_bf16 v[120:123], v[128:131], v[160:163], v[120:123]
	ds_read_b128 v[176:179], v250 offset:8192
	global_load_lds_dwordx4 v223, s[100:101]
	v_mfma_f32_16x16x32_bf16 v[116:119], v[136:139], v[160:163], v[116:119]
	s_add_u32 m0, s0, 69632
	v_mfma_f32_16x16x32_bf16 v[112:115], v[144:147], v[160:163], v[112:115]
	global_load_lds_dwordx4 v224, s[100:101]
	v_mfma_f32_16x16x32_bf16 v[108:111], v[152:155], v[160:163], v[108:111]
	s_waitcnt lgkmcnt(3)
	s_add_u32 m0, s0, 73728
	v_mfma_f32_16x16x32_bf16 v[96:99], v[128:131], v[164:167], v[96:99]
	ds_read_b128 v[180:183], v250 offset:10240
	global_load_lds_dwordx4 v225, s[100:101]
	v_mfma_f32_16x16x32_bf16 v[84:87], v[136:139], v[164:167], v[84:87]
	s_add_u32 m0, s0, 77824
	v_mfma_f32_16x16x32_bf16 v[76:79], v[144:147], v[164:167], v[76:79]
	global_load_lds_dwordx4 v226, s[100:101]
	v_mfma_f32_16x16x32_bf16 v[72:75], v[152:155], v[164:167], v[72:75]
	s_waitcnt lgkmcnt(3)
	v_mfma_f32_16x16x32_bf16 v[68:71], v[128:131], v[168:171], v[68:71]
	ds_read_b128 v[160:163], v250 offset:12288
	v_mfma_f32_16x16x32_bf16 v[64:67], v[136:139], v[168:171], v[64:67]
	v_mfma_f32_16x16x32_bf16 v[60:63], v[144:147], v[168:171], v[60:63]
	v_mfma_f32_16x16x32_bf16 v[56:59], v[152:155], v[168:171], v[56:59]
	s_waitcnt lgkmcnt(3)
	v_mfma_f32_16x16x32_bf16 v[28:31], v[128:131], v[172:175], v[28:31]
	ds_read_b128 v[164:167], v250 offset:14336
	v_mfma_f32_16x16x32_bf16 v[4:7], v[136:139], v[172:175], v[4:7]
	v_mfma_f32_16x16x32_bf16 v[24:27], v[144:147], v[172:175], v[24:27]
	v_mfma_f32_16x16x32_bf16 v[20:23], v[152:155], v[172:175], v[20:23]
	s_waitcnt lgkmcnt(3)
	v_mfma_f32_16x16x32_bf16 v[0:3], v[128:131], v[176:179], v[0:3]
	ds_read_b128 v[168:171], v247 offset:0
	v_mfma_f32_16x16x32_bf16 v[8:11], v[136:139], v[176:179], v[8:11]
	v_mfma_f32_16x16x32_bf16 v[16:19], v[144:147], v[176:179], v[16:19]
	v_mfma_f32_16x16x32_bf16 v[36:39], v[152:155], v[176:179], v[36:39]
	s_waitcnt lgkmcnt(3)
	v_mfma_f32_16x16x32_bf16 v[12:15], v[128:131], v[180:183], v[12:15]
	ds_read_b128 v[172:175], v247 offset:2048
	v_mfma_f32_16x16x32_bf16 v[32:35], v[136:139], v[180:183], v[32:35]
	v_mfma_f32_16x16x32_bf16 v[44:47], v[144:147], v[180:183], v[44:47]
	v_mfma_f32_16x16x32_bf16 v[52:55], v[152:155], v[180:183], v[52:55]
	s_waitcnt lgkmcnt(3)
	v_mfma_f32_16x16x32_bf16 v[40:43], v[128:131], v[160:163], v[40:43]
	ds_read_b128 v[176:179], v247 offset:4096
	v_mfma_f32_16x16x32_bf16 v[48:51], v[136:139], v[160:163], v[48:51]
	v_mfma_f32_16x16x32_bf16 v[104:107], v[144:147], v[160:163], v[104:107]
	v_mfma_f32_16x16x32_bf16 v[100:103], v[152:155], v[160:163], v[100:103]
	s_waitcnt lgkmcnt(3)
	v_mfma_f32_16x16x32_bf16 v[92:95], v[128:131], v[164:167], v[92:95]
	ds_read_b128 v[180:183], v247 offset:6144
	v_mfma_f32_16x16x32_bf16 v[88:91], v[136:139], v[164:167], v[88:91]
	v_mfma_f32_16x16x32_bf16 v[80:83], v[144:147], v[164:167], v[80:83]
	v_mfma_f32_16x16x32_bf16 v[124:127], v[152:155], v[164:167], v[124:127]
	s_waitcnt lgkmcnt(3)
	v_mfma_f32_16x16x32_bf16 v[120:123], v[132:135], v[168:171], v[120:123]
	ds_read_b128 v[160:163], v247 offset:8192
	v_mfma_f32_16x16x32_bf16 v[116:119], v[140:143], v[168:171], v[116:119]
	v_mfma_f32_16x16x32_bf16 v[112:115], v[148:151], v[168:171], v[112:115]
	v_mfma_f32_16x16x32_bf16 v[108:111], v[156:159], v[168:171], v[108:111]
	s_waitcnt lgkmcnt(3)
	v_mfma_f32_16x16x32_bf16 v[96:99], v[132:135], v[172:175], v[96:99]
	ds_read_b128 v[164:167], v247 offset:10240
	v_mfma_f32_16x16x32_bf16 v[84:87], v[140:143], v[172:175], v[84:87]
	v_mfma_f32_16x16x32_bf16 v[76:79], v[148:151], v[172:175], v[76:79]
	v_mfma_f32_16x16x32_bf16 v[72:75], v[156:159], v[172:175], v[72:75]
	s_waitcnt lgkmcnt(3)
	v_mfma_f32_16x16x32_bf16 v[68:71], v[132:135], v[176:179], v[68:71]
	ds_read_b128 v[168:171], v247 offset:12288
	v_mfma_f32_16x16x32_bf16 v[64:67], v[140:143], v[176:179], v[64:67]
	v_mfma_f32_16x16x32_bf16 v[60:63], v[148:151], v[176:179], v[60:63]
	v_mfma_f32_16x16x32_bf16 v[56:59], v[156:159], v[176:179], v[56:59]
	s_waitcnt lgkmcnt(3)
	v_mfma_f32_16x16x32_bf16 v[28:31], v[132:135], v[180:183], v[28:31]
	ds_read_b128 v[172:175], v247 offset:14336
	v_mfma_f32_16x16x32_bf16 v[4:7], v[140:143], v[180:183], v[4:7]
	v_mfma_f32_16x16x32_bf16 v[24:27], v[148:151], v[180:183], v[24:27]
	v_mfma_f32_16x16x32_bf16 v[20:23], v[156:159], v[180:183], v[20:23]
	s_waitcnt lgkmcnt(3)
	v_mfma_f32_16x16x32_bf16 v[0:3], v[132:135], v[160:163], v[0:3]
	v_mfma_f32_16x16x32_bf16 v[8:11], v[140:143], v[160:163], v[8:11]
	v_mfma_f32_16x16x32_bf16 v[16:19], v[148:151], v[160:163], v[16:19]
	v_mfma_f32_16x16x32_bf16 v[36:39], v[156:159], v[160:163], v[36:39]
	s_waitcnt lgkmcnt(2)
	v_mfma_f32_16x16x32_bf16 v[12:15], v[132:135], v[164:167], v[12:15]
	v_mfma_f32_16x16x32_bf16 v[32:35], v[140:143], v[164:167], v[32:35]
	v_mfma_f32_16x16x32_bf16 v[44:47], v[148:151], v[164:167], v[44:47]
	v_mfma_f32_16x16x32_bf16 v[52:55], v[156:159], v[164:167], v[52:55]
	s_waitcnt lgkmcnt(1)
	v_mfma_f32_16x16x32_bf16 v[40:43], v[132:135], v[168:171], v[40:43]
	v_mfma_f32_16x16x32_bf16 v[48:51], v[140:143], v[168:171], v[48:51]
	v_mfma_f32_16x16x32_bf16 v[104:107], v[148:151], v[168:171], v[104:107]
	v_mfma_f32_16x16x32_bf16 v[100:103], v[156:159], v[168:171], v[100:103]
	s_waitcnt lgkmcnt(0)
	v_mfma_f32_16x16x32_bf16 v[92:95], v[132:135], v[172:175], v[92:95]
	v_mfma_f32_16x16x32_bf16 v[88:91], v[140:143], v[172:175], v[88:91]
	v_mfma_f32_16x16x32_bf16 v[80:83], v[148:151], v[172:175], v[80:83]
	v_mfma_f32_16x16x32_bf16 v[124:127], v[156:159], v[172:175], v[124:127]
	s_add_u32 s98, s98, 0x80
	s_addc_u32 s99, s99, 0
	s_add_u32 s100, s100, 0x80
	s_addc_u32 s101, s101, 0
	s_waitcnt vmcnt(0) lgkmcnt(0)
	s_barrier
	ds_read_b128 v[128:131], v244 offset:0
	ds_read_b128 v[136:139], v244 offset:2048
	ds_read_b128 v[144:147], v244 offset:4096
	ds_read_b128 v[152:155], v244 offset:6144
	ds_read_b128 v[132:135], v245 offset:0
	ds_read_b128 v[140:143], v245 offset:2048
	ds_read_b128 v[148:151], v245 offset:4096
	ds_read_b128 v[156:159], v245 offset:6144
	ds_read_b128 v[160:163], v250 offset:32768
	ds_read_b128 v[164:167], v250 offset:34816
	ds_read_b128 v[168:171], v250 offset:36864
	ds_read_b128 v[172:175], v250 offset:38912
	s_waitcnt lgkmcnt(4)
	s_waitcnt lgkmcnt(3)
	v_mfma_f32_16x16x32_bf16 v[120:123], v[128:131], v[160:163], v[120:123]
	ds_read_b128 v[176:179], v250 offset:40960
	v_mfma_f32_16x16x32_bf16 v[116:119], v[136:139], v[160:163], v[116:119]
	v_mfma_f32_16x16x32_bf16 v[112:115], v[144:147], v[160:163], v[112:115]
	v_mfma_f32_16x16x32_bf16 v[108:111], v[152:155], v[160:163], v[108:111]
	s_waitcnt lgkmcnt(3)
	v_mfma_f32_16x16x32_bf16 v[96:99], v[128:131], v[164:167], v[96:99]
	ds_read_b128 v[180:183], v250 offset:43008
	v_mfma_f32_16x16x32_bf16 v[84:87], v[136:139], v[164:167], v[84:87]
	v_mfma_f32_16x16x32_bf16 v[76:79], v[144:147], v[164:167], v[76:79]
	v_mfma_f32_16x16x32_bf16 v[72:75], v[152:155], v[164:167], v[72:75]
	s_waitcnt lgkmcnt(3)
	v_mfma_f32_16x16x32_bf16 v[68:71], v[128:131], v[168:171], v[68:71]
	ds_read_b128 v[160:163], v250 offset:45056
	v_mfma_f32_16x16x32_bf16 v[64:67], v[136:139], v[168:171], v[64:67]
	v_mfma_f32_16x16x32_bf16 v[60:63], v[144:147], v[168:171], v[60:63]
	v_mfma_f32_16x16x32_bf16 v[56:59], v[152:155], v[168:171], v[56:59]
	s_waitcnt lgkmcnt(3)
	v_mfma_f32_16x16x32_bf16 v[28:31], v[128:131], v[172:175], v[28:31]
	ds_read_b128 v[164:167], v250 offset:47104
	v_mfma_f32_16x16x32_bf16 v[4:7], v[136:139], v[172:175], v[4:7]
	v_mfma_f32_16x16x32_bf16 v[24:27], v[144:147], v[172:175], v[24:27]
	v_mfma_f32_16x16x32_bf16 v[20:23], v[152:155], v[172:175], v[20:23]
	s_waitcnt lgkmcnt(3)
	v_mfma_f32_16x16x32_bf16 v[0:3], v[128:131], v[176:179], v[0:3]
	ds_read_b128 v[168:171], v247 offset:32768
	v_mfma_f32_16x16x32_bf16 v[8:11], v[136:139], v[176:179], v[8:11]
	v_mfma_f32_16x16x32_bf16 v[16:19], v[144:147], v[176:179], v[16:19]
	v_mfma_f32_16x16x32_bf16 v[36:39], v[152:155], v[176:179], v[36:39]
	s_waitcnt lgkmcnt(3)
	v_mfma_f32_16x16x32_bf16 v[12:15], v[128:131], v[180:183], v[12:15]
	ds_read_b128 v[172:175], v247 offset:34816
	v_mfma_f32_16x16x32_bf16 v[32:35], v[136:139], v[180:183], v[32:35]
	v_mfma_f32_16x16x32_bf16 v[44:47], v[144:147], v[180:183], v[44:47]
	v_mfma_f32_16x16x32_bf16 v[52:55], v[152:155], v[180:183], v[52:55]
	s_waitcnt lgkmcnt(3)
	v_mfma_f32_16x16x32_bf16 v[40:43], v[128:131], v[160:163], v[40:43]
	ds_read_b128 v[176:179], v247 offset:36864
	v_mfma_f32_16x16x32_bf16 v[48:51], v[136:139], v[160:163], v[48:51]
	v_mfma_f32_16x16x32_bf16 v[104:107], v[144:147], v[160:163], v[104:107]
	v_mfma_f32_16x16x32_bf16 v[100:103], v[152:155], v[160:163], v[100:103]
	s_waitcnt lgkmcnt(3)
	v_mfma_f32_16x16x32_bf16 v[92:95], v[128:131], v[164:167], v[92:95]
	ds_read_b128 v[180:183], v247 offset:38912
	v_mfma_f32_16x16x32_bf16 v[88:91], v[136:139], v[164:167], v[88:91]
	v_mfma_f32_16x16x32_bf16 v[80:83], v[144:147], v[164:167], v[80:83]
	v_mfma_f32_16x16x32_bf16 v[124:127], v[152:155], v[164:167], v[124:127]
	s_waitcnt lgkmcnt(3)
	v_mfma_f32_16x16x32_bf16 v[120:123], v[132:135], v[168:171], v[120:123]
	ds_read_b128 v[160:163], v247 offset:40960
	v_mfma_f32_16x16x32_bf16 v[116:119], v[140:143], v[168:171], v[116:119]
	v_mfma_f32_16x16x32_bf16 v[112:115], v[148:151], v[168:171], v[112:115]
	v_mfma_f32_16x16x32_bf16 v[108:111], v[156:159], v[168:171], v[108:111]
	s_waitcnt lgkmcnt(3)
	v_mfma_f32_16x16x32_bf16 v[96:99], v[132:135], v[172:175], v[96:99]
	ds_read_b128 v[164:167], v247 offset:43008
	v_mfma_f32_16x16x32_bf16 v[84:87], v[140:143], v[172:175], v[84:87]
	v_mfma_f32_16x16x32_bf16 v[76:79], v[148:151], v[172:175], v[76:79]
	v_mfma_f32_16x16x32_bf16 v[72:75], v[156:159], v[172:175], v[72:75]
	s_waitcnt lgkmcnt(3)
	v_mfma_f32_16x16x32_bf16 v[68:71], v[132:135], v[176:179], v[68:71]
	ds_read_b128 v[168:171], v247 offset:45056
	v_mfma_f32_16x16x32_bf16 v[64:67], v[140:143], v[176:179], v[64:67]
	v_mfma_f32_16x16x32_bf16 v[60:63], v[148:151], v[176:179], v[60:63]
	v_mfma_f32_16x16x32_bf16 v[56:59], v[156:159], v[176:179], v[56:59]
	s_waitcnt lgkmcnt(3)
	v_mfma_f32_16x16x32_bf16 v[28:31], v[132:135], v[180:183], v[28:31]
	ds_read_b128 v[172:175], v247 offset:47104
	v_mfma_f32_16x16x32_bf16 v[4:7], v[140:143], v[180:183], v[4:7]
	v_mfma_f32_16x16x32_bf16 v[24:27], v[148:151], v[180:183], v[24:27]
	v_mfma_f32_16x16x32_bf16 v[20:23], v[156:159], v[180:183], v[20:23]
	s_waitcnt lgkmcnt(3)
	v_mfma_f32_16x16x32_bf16 v[0:3], v[132:135], v[160:163], v[0:3]
	v_mfma_f32_16x16x32_bf16 v[8:11], v[140:143], v[160:163], v[8:11]
	v_mfma_f32_16x16x32_bf16 v[16:19], v[148:151], v[160:163], v[16:19]
	v_mfma_f32_16x16x32_bf16 v[36:39], v[156:159], v[160:163], v[36:39]
	s_waitcnt lgkmcnt(2)
	v_mfma_f32_16x16x32_bf16 v[12:15], v[132:135], v[164:167], v[12:15]
	v_mfma_f32_16x16x32_bf16 v[32:35], v[140:143], v[164:167], v[32:35]
	v_mfma_f32_16x16x32_bf16 v[44:47], v[148:151], v[164:167], v[44:47]
	v_mfma_f32_16x16x32_bf16 v[52:55], v[156:159], v[164:167], v[52:55]
	s_waitcnt lgkmcnt(1)
	v_mfma_f32_16x16x32_bf16 v[40:43], v[132:135], v[168:171], v[40:43]
	v_mfma_f32_16x16x32_bf16 v[48:51], v[140:143], v[168:171], v[48:51]
	v_mfma_f32_16x16x32_bf16 v[104:107], v[148:151], v[168:171], v[104:107]
	v_mfma_f32_16x16x32_bf16 v[100:103], v[156:159], v[168:171], v[100:103]
	s_waitcnt lgkmcnt(0)
	v_mfma_f32_16x16x32_bf16 v[92:95], v[132:135], v[172:175], v[92:95]
	v_mfma_f32_16x16x32_bf16 v[88:91], v[140:143], v[172:175], v[88:91]
	v_mfma_f32_16x16x32_bf16 v[80:83], v[148:151], v[172:175], v[80:83]
	v_mfma_f32_16x16x32_bf16 v[124:127], v[156:159], v[172:175], v[124:127]
	s_nop 7
	s_nop 7
	s_barrier
	ds_write_b64 v194, v[192:193]
	s_movk_i32 s0, 0xc00
	v_mov_b32_e32 v172, v84
	v_mov_b32_e32 v173, v85
	v_mov_b32_e32 v174, v86
	v_mov_b32_e32 v175, v87
	v_mov_b32_e32 v176, v76
	v_mov_b32_e32 v177, v77
	v_mov_b32_e32 v178, v78
	v_mov_b32_e32 v179, v79
	v_mov_b32_e32 v180, v72
	v_mov_b32_e32 v181, v73
	v_mov_b32_e32 v182, v74
	v_mov_b32_e32 v183, v75
	v_mov_b32_e32 v168, v56
	v_mov_b32_e32 v169, v57
	v_mov_b32_e32 v170, v58
	v_mov_b32_e32 v171, v59
	v_mov_b32_e32 v76, v64
	v_mov_b32_e32 v77, v65
	v_mov_b32_e32 v78, v66
	v_mov_b32_e32 v79, v67
	v_mov_b32_e32 v64, v4
	v_mov_b32_e32 v65, v5
	v_mov_b32_e32 v66, v6
	v_mov_b32_e32 v67, v7
	v_mov_b32_e32 v72, v68
	v_mov_b32_e32 v73, v69
	v_mov_b32_e32 v74, v70
	v_mov_b32_e32 v75, v71
	v_mov_b32_e32 v84, v60
	v_mov_b32_e32 v85, v61
	v_mov_b32_e32 v86, v62
	v_mov_b32_e32 v87, v63
	v_mov_b32_e32 v60, v28
	v_mov_b32_e32 v61, v29
	v_mov_b32_e32 v62, v30
	v_mov_b32_e32 v63, v31
	v_mov_b32_e32 v68, v24
	v_mov_b32_e32 v69, v25
	v_mov_b32_e32 v70, v26
	v_mov_b32_e32 v71, v27
	v_mov_b32_e32 v164, v20
	v_mov_b32_e32 v165, v21
	v_mov_b32_e32 v166, v22
	v_mov_b32_e32 v167, v23
	v_mov_b32_e32 v56, v0
	v_mov_b32_e32 v57, v1
	v_mov_b32_e32 v58, v2
	v_mov_b32_e32 v59, v3
	v_mov_b32_e32 v20, v12
	v_mov_b32_e32 v21, v13
	v_mov_b32_e32 v22, v14
	v_mov_b32_e32 v23, v15
	v_mov_b32_e32 v24, v32
	v_mov_b32_e32 v25, v33
	v_mov_b32_e32 v26, v34
	v_mov_b32_e32 v27, v35
	v_mov_b32_e32 v28, v44
	v_mov_b32_e32 v29, v45
	v_mov_b32_e32 v30, v46
	v_mov_b32_e32 v31, v47
	v_mov_b32_e32 v32, v52
	v_mov_b32_e32 v33, v53
	v_mov_b32_e32 v34, v54
	v_mov_b32_e32 v35, v55
	v_mov_b32_e32 v156, v8
	v_mov_b32_e32 v157, v9
	v_mov_b32_e32 v158, v10
	v_mov_b32_e32 v159, v11
	v_mov_b32_e32 v8, v40
	v_mov_b32_e32 v9, v41
	v_mov_b32_e32 v10, v42
	v_mov_b32_e32 v11, v43
	v_mov_b32_e32 v160, v16
	v_mov_b32_e32 v161, v17
	v_mov_b32_e32 v162, v18
	v_mov_b32_e32 v163, v19
	v_mov_b32_e32 v12, v48
	v_mov_b32_e32 v13, v49
	v_mov_b32_e32 v14, v50
	v_mov_b32_e32 v15, v51
	v_mov_b32_e32 v16, v104
	v_mov_b32_e32 v17, v105
	v_mov_b32_e32 v18, v106
	v_mov_b32_e32 v19, v107
	v_mov_b32_e32 v136, v100
	v_mov_b32_e32 v137, v101
	v_mov_b32_e32 v138, v102
	v_mov_b32_e32 v139, v103
	v_mov_b32_e32 v0, v92
	v_mov_b32_e32 v1, v93
	v_mov_b32_e32 v2, v94
	v_mov_b32_e32 v3, v95
	v_mov_b32_e32 v4, v88
	v_mov_b32_e32 v5, v89
	v_mov_b32_e32 v6, v90
	v_mov_b32_e32 v7, v91
	v_mov_b32_e32 v128, v80
	v_mov_b32_e32 v129, v81
	v_mov_b32_e32 v130, v82
	v_mov_b32_e32 v131, v83
	v_mov_b32_e32 v132, v120
	v_mov_b32_e32 v133, v121
	v_mov_b32_e32 v134, v122
	v_mov_b32_e32 v135, v123
	v_mov_b32_e32 v120, v116
	v_mov_b32_e32 v121, v117
	v_mov_b32_e32 v122, v118
	v_mov_b32_e32 v123, v119
	v_mov_b32_e32 v116, v112
	v_mov_b32_e32 v117, v113
	v_mov_b32_e32 v118, v114
	v_mov_b32_e32 v119, v115
	v_mov_b32_e32 v112, v108
	v_mov_b32_e32 v113, v109
	v_mov_b32_e32 v114, v110
	v_mov_b32_e32 v115, v111
	v_mov_b32_e32 v108, v96
	v_mov_b32_e32 v109, v97
	v_mov_b32_e32 v110, v98
	v_mov_b32_e32 v111, v99
	v_mov_b32_e32 v104, v172
	v_mov_b32_e32 v105, v173
	v_mov_b32_e32 v106, v174
	v_mov_b32_e32 v107, v175
	v_mov_b32_e32 v100, v176
	v_mov_b32_e32 v101, v177
	v_mov_b32_e32 v102, v178
	v_mov_b32_e32 v103, v179
	v_mov_b32_e32 v96, v180
	v_mov_b32_e32 v97, v181
	v_mov_b32_e32 v98, v182
	v_mov_b32_e32 v99, v183
	v_mov_b32_e32 v92, v72
	v_mov_b32_e32 v93, v73
	v_mov_b32_e32 v94, v74
	v_mov_b32_e32 v95, v75
	v_mov_b32_e32 v88, v76
	v_mov_b32_e32 v89, v77
	v_mov_b32_e32 v90, v78
	v_mov_b32_e32 v91, v79
	v_mov_b32_e32 v80, v168
	v_mov_b32_e32 v81, v169
	v_mov_b32_e32 v82, v170
	v_mov_b32_e32 v83, v171
	v_mov_b32_e32 v76, v60
	v_mov_b32_e32 v77, v61
	v_mov_b32_e32 v78, v62
	v_mov_b32_e32 v79, v63
	v_mov_b32_e32 v72, v64
	v_mov_b32_e32 v73, v65
	v_mov_b32_e32 v74, v66
	v_mov_b32_e32 v75, v67
	v_mov_b32_e32 v64, v164
	v_mov_b32_e32 v65, v165
	v_mov_b32_e32 v66, v166
	v_mov_b32_e32 v67, v167
	v_mov_b32_e32 v60, v56
	v_mov_b32_e32 v61, v57
	v_mov_b32_e32 v62, v58
	v_mov_b32_e32 v63, v59
	v_mov_b32_e32 v56, v156
	v_mov_b32_e32 v57, v157
	v_mov_b32_e32 v58, v158
	v_mov_b32_e32 v59, v159
	v_mov_b32_e32 v52, v160
	v_mov_b32_e32 v53, v161
	v_mov_b32_e32 v54, v162
	v_mov_b32_e32 v55, v163
	v_mov_b32_e32 v48, v36
	v_mov_b32_e32 v49, v37
	v_mov_b32_e32 v50, v38
	v_mov_b32_e32 v51, v39
	v_mov_b32_e32 v44, v20
	v_mov_b32_e32 v45, v21
	v_mov_b32_e32 v46, v22
	v_mov_b32_e32 v47, v23
	v_mov_b32_e32 v40, v24
	v_mov_b32_e32 v41, v25
	v_mov_b32_e32 v42, v26
	v_mov_b32_e32 v43, v27
	v_mov_b32_e32 v36, v28
	v_mov_b32_e32 v37, v29
	v_mov_b32_e32 v38, v30
	v_mov_b32_e32 v39, v31
	v_mov_b32_e32 v28, v8
	v_mov_b32_e32 v29, v9
	v_mov_b32_e32 v30, v10
	v_mov_b32_e32 v31, v11
	v_mov_b32_e32 v8, v136
	v_mov_b32_e32 v9, v137
	v_mov_b32_e32 v10, v138
	v_mov_b32_e32 v11, v139
	v_mov_b32_e32 v24, v12
	v_mov_b32_e32 v25, v13
	v_mov_b32_e32 v26, v14
	v_mov_b32_e32 v27, v15
	v_mov_b32_e32 v20, v16
	v_mov_b32_e32 v21, v17
	v_mov_b32_e32 v22, v18
	v_mov_b32_e32 v23, v19
	v_mov_b32_e32 v16, v0
	v_mov_b32_e32 v17, v1
	v_mov_b32_e32 v18, v2
	v_mov_b32_e32 v19, v3
	v_mov_b32_e32 v12, v4
	v_mov_b32_e32 v13, v5
	v_mov_b32_e32 v14, v6
	v_mov_b32_e32 v15, v7
	v_mov_b32_e32 v4, v128
	v_mov_b32_e32 v5, v129
	v_mov_b32_e32 v6, v130
	v_mov_b32_e32 v7, v131
	v_mov_b32_e32 v0, v124
	v_mov_b32_e32 v1, v125
	v_mov_b32_e32 v2, v126
	v_mov_b32_e32 v3, v127
	s_nop 2
	v_or_b32_e32 v124, s10, v202
	v_cmp_ne_u32_e64 s[0:1], s0, v124
	s_and_saveexec_b64 s[6:7], s[0:1]
	s_xor_b64 s[6:7], exec, s[6:7]
	s_or_saveexec_b64 s[6:7], s[6:7]
	v_add_u32_e32 v126, s4, v201
	v_or_b32_e32 v124, v126, v197
	v_lshlrev_b32_e32 v124, 6, v124
	v_ashrrev_i32_e32 v125, 31, v124
	v_or_b32_e32 v184, s10, v203
	v_lshl_add_u64 v[124:125], v[124:125], 2, s[30:31]
	s_xor_b64 exec, exec, s[6:7]
	s_cbranch_execz .LBB0_418
	v_lshl_add_u64 v[128:129], v[184:185], 2, v[124:125]
	v_add_co_u32_e32 v128, vcc, 0xffffd000, v128
	s_nop 1
	v_addc_co_u32_e32 v129, vcc, -1, v129, vcc
	global_store_dwordx4 v[128:129], v[132:135], off

.LBB0_819:
	s_bfe_u32 s4, s14, 0x30005
	s_mul_i32 s9, s4, 0xc0
	s_lshl_b32 s4, s16, 12
	s_and_b32 s4, s4, 0x380000
	s_lshl_b32 s6, s13, 5
	v_lshl_add_u64 v[144:145], v[142:143], 0, s[4:5]
	s_lshl_b32 s4, s8, 8
	s_and_b32 s6, s6, 0xe0
	s_or_b32 s4, s6, s4
	s_mul_i32 s6, s4, 6
	s_ashr_i32 s7, s6, 31
	s_lshl_b64 s[34:35], s[6:7], 12
	v_lshl_add_u64 v[0:1], v[138:139], 0, s[34:35]
	v_add_co_u32_e32 v2, vcc, s18, v0
	s_lshl_b32 s4, s13, 4
	s_nop 0
	v_addc_co_u32_e32 v3, vcc, 0, v1, vcc
	s_nop 0
	v_readfirstlane_b32 s98, v0
	v_readfirstlane_b32 s99, v1
	v_add_co_u32_e32 v2, vcc, s19, v0
	s_and_b32 s33, s4, 0x380
	s_nop 0
	v_addc_co_u32_e32 v3, vcc, 0, v1, vcc
	v_add_co_u32_e32 v4, vcc, s20, v0
	s_lshl_b32 s4, s33, 12
	s_nop 0
	v_addc_co_u32_e32 v5, vcc, 0, v1, vcc
	v_add_co_u32_e32 v2, vcc, s21, v0
	v_mov_b32_e32 v64, 0
	s_nop 0
	v_addc_co_u32_e32 v3, vcc, 0, v1, vcc
	v_add_co_u32_e32 v0, vcc, 0xa0000, v0
	v_mov_b32_e32 v65, v137
	s_nop 0
	v_addc_co_u32_e32 v1, vcc, 0, v1, vcc
	v_lshl_add_u64 v[0:1], v[140:141], 0, s[4:5]
	v_add_co_u32_e32 v2, vcc, s18, v0
	s_mul_i32 s4, s8, 0x600
	s_nop 0
	v_addc_co_u32_e32 v3, vcc, 0, v1, vcc
	s_nop 0
	v_readfirstlane_b32 s100, v0
	v_readfirstlane_b32 s101, v1
	v_add_co_u32_e32 v2, vcc, 0x40000, v0
	s_add_i32 s8, s4, s9
	s_nop 0
	v_addc_co_u32_e32 v3, vcc, 0, v1, vcc
	v_add_co_u32_e32 v0, vcc, 0x60000, v0
	s_ashr_i32 s9, s8, 31
	s_nop 0
	v_addc_co_u32_e32 v1, vcc, 0, v1, vcc
	s_lshl_b64 s[8:9], s[8:9], 12
	v_lshl_add_u64 v[146:147], v[142:143], 0, s[8:9]
	s_mov_b64 s[8:9], 0
	v_mov_b32_e32 v66, v137
	v_mov_b32_e32 v67, v137
	v_mov_b32_e32 v0, 0
	v_mov_b32_e32 v1, v137
	v_mov_b32_e32 v2, v137
	v_mov_b32_e32 v3, v137
	v_mov_b32_e32 v4, 0
	v_mov_b32_e32 v5, v137
	v_mov_b32_e32 v6, v137
	v_mov_b32_e32 v7, v137
	v_mov_b32_e32 v8, 0
	v_mov_b32_e32 v9, v137
	v_mov_b32_e32 v10, v137
	v_mov_b32_e32 v11, v137
	v_mov_b32_e32 v12, 0
	v_mov_b32_e32 v13, v137
	v_mov_b32_e32 v14, v137
	v_mov_b32_e32 v15, v137
	v_mov_b32_e32 v16, 0
	v_mov_b32_e32 v17, v137
	v_mov_b32_e32 v18, v137
	v_mov_b32_e32 v19, v137
	v_mov_b32_e32 v20, 0
	v_mov_b32_e32 v21, v137
	v_mov_b32_e32 v22, v137
	v_mov_b32_e32 v23, v137
	v_mov_b32_e32 v24, 0
	v_mov_b32_e32 v25, v137
	v_mov_b32_e32 v26, v137
	v_mov_b32_e32 v27, v137
	v_mov_b32_e32 v28, 0
	v_mov_b32_e32 v29, v137
	v_mov_b32_e32 v30, v137
	v_mov_b32_e32 v31, v137
	v_mov_b32_e32 v32, 0
	v_mov_b32_e32 v33, v137
	v_mov_b32_e32 v34, v137
	v_mov_b32_e32 v35, v137
	v_mov_b32_e32 v36, 0
	v_mov_b32_e32 v37, v137
	v_mov_b32_e32 v38, v137
	v_mov_b32_e32 v39, v137
	v_mov_b32_e32 v40, 0
	v_mov_b32_e32 v41, v137
	v_mov_b32_e32 v42, v137
	v_mov_b32_e32 v43, v137
	v_mov_b32_e32 v44, 0
	v_mov_b32_e32 v45, v137
	v_mov_b32_e32 v46, v137
	v_mov_b32_e32 v47, v137
	v_mov_b32_e32 v48, 0
	v_mov_b32_e32 v49, v137
	v_mov_b32_e32 v50, v137
	v_mov_b32_e32 v51, v137
	v_mov_b32_e32 v52, 0
	v_mov_b32_e32 v53, v137
	v_mov_b32_e32 v54, v137
	v_mov_b32_e32 v55, v137
	v_mov_b32_e32 v56, 0
	v_mov_b32_e32 v57, v137
	v_mov_b32_e32 v58, v137
	v_mov_b32_e32 v59, v137
	v_mov_b32_e32 v60, 0
	v_mov_b32_e32 v61, v137
	v_mov_b32_e32 v62, v137
	v_mov_b32_e32 v63, v137
	v_mov_b32_e32 v68, 0
	v_mov_b32_e32 v69, v137
	v_mov_b32_e32 v70, v137
	v_mov_b32_e32 v71, v137
	v_mov_b32_e32 v72, 0
	v_mov_b32_e32 v73, v137
	v_mov_b32_e32 v74, v137
	v_mov_b32_e32 v75, v137
	v_mov_b32_e32 v76, 0
	v_mov_b32_e32 v77, v137
	v_mov_b32_e32 v78, v137
	v_mov_b32_e32 v79, v137
	v_mov_b32_e32 v80, 0
	v_mov_b32_e32 v81, v137
	v_mov_b32_e32 v82, v137
	v_mov_b32_e32 v83, v137
	v_mov_b32_e32 v84, 0
	v_mov_b32_e32 v85, v137
	v_mov_b32_e32 v86, v137
	v_mov_b32_e32 v87, v137
	v_mov_b32_e32 v88, 0
	v_mov_b32_e32 v89, v137
	v_mov_b32_e32 v90, v137
	v_mov_b32_e32 v91, v137
	v_mov_b32_e32 v92, 0
	v_mov_b32_e32 v93, v137
	v_mov_b32_e32 v94, v137
	v_mov_b32_e32 v95, v137
	v_and_b32_e32 v197, 63, v196
	v_lshrrev_b32_e32 v198, 3, v197
	v_and_b32_e32 v199, 7, v197
	v_xor_b32_e32 v199, v199, v198
	v_lshlrev_b32_e32 v199, 4, v199
	v_mul_u32_u24_e32 v198, 4096, v198
	v_add_u32_e32 v240, v198, v199
	v_add_u32_e32 v241, 131072, v240
	v_add_u32_e32 v242, 262144, v240
	v_add_u32_e32 v243, 393216, v240
	v_add_u32_e32 v244, 524288, v240
	v_add_u32_e32 v245, 655360, v240
	v_lshrrev_b32_e32 v198, 6, v196
	v_lshrrev_b32_e32 v199, 1, v198
	v_and_b32_e32 v198, 1, v198
	v_and_b32_e32 v190, 15, v197
	v_lshrrev_b32_e32 v191, 4, v197
	v_and_b32_e32 v192, 7, v190
	v_xor_b32_e32 v191, v191, v192
	v_lshlrev_b32_e32 v191, 4, v191
	v_mul_u32_u24_e32 v199, 0x60, v199
	v_add_u32_e32 v199, v199, v190
	v_lshl_add_u32 v246, v199, 7, v191
	v_xor_b32_e32 v247, 64, v246
	v_lshlrev_b32_e32 v198, 6, v198
	v_add_u32_e32 v198, v198, v190
	v_lshl_add_u32 v248, v198, 7, v191
	v_add_u32_e32 v248, 0x6000, v248
	v_xor_b32_e32 v249, 64, v248
	v_lshrrev_b32_e32 v198, 6, v196
	v_lshlrev_b32_e32 v198, 10, v198
	s_nop 0
	v_readfirstlane_b32 s8, v198
	s_waitcnt lgkmcnt(0)
	s_barrier
	s_add_u32 m0, s8, 0
	s_nop 0
	global_load_lds_dwordx4 v240, s[98:99]
	s_add_u32 m0, s8, 4096
	s_nop 0
	global_load_lds_dwordx4 v241, s[98:99]
	s_add_u32 m0, s8, 8192
	s_nop 0
	global_load_lds_dwordx4 v242, s[98:99]
	s_add_u32 m0, s8, 12288
	s_nop 0
	global_load_lds_dwordx4 v243, s[98:99]
	s_add_u32 m0, s8, 16384
	s_nop 0
	global_load_lds_dwordx4 v244, s[98:99]
	s_add_u32 m0, s8, 20480
	s_nop 0
	global_load_lds_dwordx4 v245, s[98:99]
	s_add_u32 m0, s8, 24576
	s_nop 0
	global_load_lds_dwordx4 v240, s[100:101]
	s_add_u32 m0, s8, 28672
	s_nop 0
	global_load_lds_dwordx4 v241, s[100:101]
	s_add_u32 m0, s8, 32768
	s_nop 0
	global_load_lds_dwordx4 v242, s[100:101]
	s_add_u32 m0, s8, 36864
	s_nop 0
	global_load_lds_dwordx4 v243, s[100:101]
	s_add_u32 s98, s98, 0x80
	s_addc_u32 s99, s99, 0
	s_add_u32 s100, s100, 0x80
	s_addc_u32 s101, s101, 0
	s_waitcnt vmcnt(0)
	s_barrier
	ds_read_b128 v[120:123], v248 offset:0
	ds_read_b128 v[124:127], v248 offset:2048
	ds_read_b128 v[128:131], v248 offset:4096
	ds_read_b128 v[132:135], v248 offset:6144
	ds_read_b128 v[96:99], v246 offset:0
	ds_read_b128 v[100:103], v246 offset:2048
	ds_read_b128 v[104:107], v246 offset:4096
	ds_read_b128 v[108:111], v246 offset:6144
	ds_read_b128 v[112:115], v246 offset:8192
	ds_read_b128 v[116:119], v246 offset:10240
	s_add_u32 m0, s8, 40960
	s_nop 0
	global_load_lds_dwordx4 v240, s[98:99]
	s_add_u32 m0, s8, 45056
	s_nop 0
	global_load_lds_dwordx4 v241, s[98:99]
	s_add_u32 m0, s8, 49152
	s_nop 0
	global_load_lds_dwordx4 v242, s[98:99]
	s_add_u32 m0, s8, 53248
	s_nop 0
	global_load_lds_dwordx4 v243, s[98:99]
	s_add_u32 m0, s8, 57344
	s_nop 0
	global_load_lds_dwordx4 v244, s[98:99]
	s_add_u32 m0, s8, 61440
	s_nop 0
	global_load_lds_dwordx4 v245, s[98:99]
	s_add_u32 m0, s8, 65536
	s_nop 0
	global_load_lds_dwordx4 v240, s[100:101]
	s_add_u32 m0, s8, 69632
	s_nop 0
	global_load_lds_dwordx4 v241, s[100:101]
	s_add_u32 m0, s8, 73728
	s_nop 0
	global_load_lds_dwordx4 v242, s[100:101]
	s_add_u32 m0, s8, 77824
	s_nop 0
	global_load_lds_dwordx4 v243, s[100:101]
	s_add_u32 s98, s98, 0x80
	s_addc_u32 s99, s99, 0
	s_add_u32 s100, s100, 0x80
	s_addc_u32 s101, s101, 0
	s_waitcnt lgkmcnt(0)
	v_mfma_f32_16x16x32_bf16 v[92:95], v[120:123], v[96:99], v[92:95]
	v_mfma_f32_16x16x32_bf16 v[88:91], v[124:127], v[96:99], v[88:91]
	ds_read_b128 v[224:227], v249 offset:0
	v_mfma_f32_16x16x32_bf16 v[84:87], v[128:131], v[96:99], v[84:87]
	v_mfma_f32_16x16x32_bf16 v[80:83], v[132:135], v[96:99], v[80:83]
	ds_read_b128 v[228:231], v249 offset:2048
	v_mfma_f32_16x16x32_bf16 v[76:79], v[120:123], v[100:103], v[76:79]
	v_mfma_f32_16x16x32_bf16 v[72:75], v[124:127], v[100:103], v[72:75]
	ds_read_b128 v[232:235], v249 offset:4096
	v_mfma_f32_16x16x32_bf16 v[68:71], v[128:131], v[100:103], v[68:71]
	v_mfma_f32_16x16x32_bf16 v[60:63], v[132:135], v[100:103], v[60:63]
	ds_read_b128 v[236:239], v249 offset:6144
	v_mfma_f32_16x16x32_bf16 v[56:59], v[120:123], v[104:107], v[56:59]
	v_mfma_f32_16x16x32_bf16 v[52:55], v[124:127], v[104:107], v[52:55]
	ds_read_b128 v[200:203], v247 offset:0
	v_mfma_f32_16x16x32_bf16 v[48:51], v[128:131], v[104:107], v[48:51]
	v_mfma_f32_16x16x32_bf16 v[44:47], v[132:135], v[104:107], v[44:47]
	ds_read_b128 v[204:207], v247 offset:2048
	v_mfma_f32_16x16x32_bf16 v[40:43], v[120:123], v[108:111], v[40:43]
	v_mfma_f32_16x16x32_bf16 v[36:39], v[124:127], v[108:111], v[36:39]
	ds_read_b128 v[208:211], v247 offset:4096
	v_mfma_f32_16x16x32_bf16 v[32:35], v[128:131], v[108:111], v[32:35]
	v_mfma_f32_16x16x32_bf16 v[28:31], v[132:135], v[108:111], v[28:31]
	ds_read_b128 v[212:215], v247 offset:6144
	v_mfma_f32_16x16x32_bf16 v[24:27], v[120:123], v[112:115], v[24:27]
	v_mfma_f32_16x16x32_bf16 v[20:23], v[124:127], v[112:115], v[20:23]
	ds_read_b128 v[216:219], v247 offset:8192
	v_mfma_f32_16x16x32_bf16 v[16:19], v[128:131], v[112:115], v[16:19]
	v_mfma_f32_16x16x32_bf16 v[12:15], v[132:135], v[112:115], v[12:15]
	ds_read_b128 v[220:223], v247 offset:10240
	v_mfma_f32_16x16x32_bf16 v[8:11], v[120:123], v[116:119], v[8:11]
	v_mfma_f32_16x16x32_bf16 v[4:7], v[124:127], v[116:119], v[4:7]
	v_mfma_f32_16x16x32_bf16 v[0:3], v[128:131], v[116:119], v[0:3]
	v_mfma_f32_16x16x32_bf16 v[64:67], v[132:135], v[116:119], v[64:67]
	s_mov_b32 s9, 15

.LBB0_970:
	s_ashr_i32 s4, s13, 6
	s_mul_i32 s8, s4, s11
	s_add_i32 s8, s8, s10
	s_cmp_gt_i32 s8, 47
	s_mov_b32 s34, 2
	s_cbranch_scc1 .LBB0_975
	s_mul_hi_i32 s9, s8, 0x2aaaaaab
	s_lshr_b32 s4, s9, 31
	s_add_i32 s9, s9, s4
	s_mul_i32 s4, s9, 6
	s_sub_i32 s4, s8, s4
	s_lshl_b32 s4, s4, 3
	s_bfe_u32 s33, s13, 0x30003
	s_or_b32 s6, s4, s33
	s_cmp_gt_i32 s6, 43
	s_mov_b32 s34, 4
	s_cbranch_scc1 .LBB0_975
	s_bfe_u32 s4, s14, 0x30005
	s_lshl_b32 s5, s13, 5
	s_mul_i32 s38, s4, 0xc0
	s_lshl_b32 s4, s9, 8
	s_and_b32 s5, s5, 0xe0
	s_or_b32 s4, s4, s5
	s_mul_i32 s4, s4, 6
	s_ashr_i32 s5, s4, 31
	s_lshl_b64 s[34:35], s[4:5], 11
	v_lshl_add_u64 v[0:1], v[136:137], 0, s[34:35]
	v_add_co_u32_e32 v2, vcc, s16, v0
	s_lshl_b32 s6, s6, 7
	s_nop 0
	v_addc_co_u32_e32 v3, vcc, 0, v1, vcc
	s_nop 0
	v_readfirstlane_b32 s98, v0
	v_readfirstlane_b32 s99, v1
	v_add_co_u32_e32 v2, vcc, s17, v0
	s_ashr_i32 s7, s6, 31
	s_nop 0
	v_addc_co_u32_e32 v3, vcc, 0, v1, vcc
	v_add_co_u32_e32 v4, vcc, s18, v0
	s_lshl_b64 s[36:37], s[6:7], 11
	s_nop 0
	v_addc_co_u32_e32 v5, vcc, 0, v1, vcc
	v_add_co_u32_e32 v2, vcc, s19, v0
	s_mul_i32 s5, s9, 0x600
	s_nop 0
	v_addc_co_u32_e32 v3, vcc, 0, v1, vcc
	v_add_co_u32_e32 v0, vcc, s20, v0
	s_add_i32 s34, s5, s38
	s_nop 0
	v_addc_co_u32_e32 v1, vcc, 0, v1, vcc
	v_lshl_add_u64 v[0:1], v[138:139], 0, s[36:37]
	v_add_co_u32_e32 v2, vcc, s16, v0
	s_lshl_b32 s5, s8, 3
	s_nop 0
	v_addc_co_u32_e32 v3, vcc, 0, v1, vcc
	s_nop 0
	v_readfirstlane_b32 s100, v0
	v_readfirstlane_b32 s101, v1
	v_add_co_u32_e32 v2, vcc, s17, v0
	s_or_b32 s5, s5, s33
	s_nop 0
	v_addc_co_u32_e32 v3, vcc, 0, v1, vcc
	v_add_co_u32_e32 v0, vcc, s18, v0
	s_mul_i32 s9, s9, 48
	s_nop 0
	v_addc_co_u32_e32 v1, vcc, 0, v1, vcc
	s_sub_i32 s5, s5, s9
	s_lshl_b32 s8, s5, 7
	s_ashr_i32 s35, s34, 31
	s_ashr_i32 s9, s8, 31
	s_lshl_b64 s[34:35], s[34:35], 11
	s_lshl_b64 s[8:9], s[8:9], 11
	v_mov_b32_e32 v60, 0
	v_lshl_add_u64 v[142:143], v[140:141], 0, s[34:35]
	v_lshl_add_u64 v[144:145], v[140:141], 0, s[8:9]
	s_mov_b64 s[8:9], 0
	v_mov_b32_e32 v61, v60
	v_mov_b32_e32 v62, v60
	v_mov_b32_e32 v63, v60
	v_mov_b32_e32 v0, v60
	v_mov_b32_e32 v1, v60
	v_mov_b32_e32 v2, v60
	v_mov_b32_e32 v3, v60
	v_mov_b32_e32 v4, v60
	v_mov_b32_e32 v5, v60
	v_mov_b32_e32 v6, v60
	v_mov_b32_e32 v7, v60
	v_mov_b32_e32 v8, v60
	v_mov_b32_e32 v9, v60
	v_mov_b32_e32 v10, v60
	v_mov_b32_e32 v11, v60
	v_mov_b32_e32 v12, v60
	v_mov_b32_e32 v13, v60
	v_mov_b32_e32 v14, v60
	v_mov_b32_e32 v15, v60
	v_mov_b32_e32 v16, v60
	v_mov_b32_e32 v17, v60
	v_mov_b32_e32 v18, v60
	v_mov_b32_e32 v19, v60
	v_mov_b32_e32 v20, v60
	v_mov_b32_e32 v21, v60
	v_mov_b32_e32 v22, v60
	v_mov_b32_e32 v23, v60
	v_mov_b32_e32 v24, v60
	v_mov_b32_e32 v25, v60
	v_mov_b32_e32 v26, v60
	v_mov_b32_e32 v27, v60
	v_mov_b32_e32 v28, v60
	v_mov_b32_e32 v29, v60
	v_mov_b32_e32 v30, v60
	v_mov_b32_e32 v31, v60
	v_mov_b32_e32 v32, v60
	v_mov_b32_e32 v33, v60
	v_mov_b32_e32 v34, v60
	v_mov_b32_e32 v35, v60
	s_waitcnt vmcnt(22)
	v_mov_b32_e32 v36, v60
	v_mov_b32_e32 v37, v60
	v_mov_b32_e32 v38, v60
	v_mov_b32_e32 v39, v60
	s_waitcnt vmcnt(21)
	v_mov_b32_e32 v40, v60
	v_mov_b32_e32 v41, v60
	v_mov_b32_e32 v42, v60
	v_mov_b32_e32 v43, v60
	s_waitcnt vmcnt(20)
	v_mov_b32_e32 v44, v60
	v_mov_b32_e32 v45, v60
	v_mov_b32_e32 v46, v60
	v_mov_b32_e32 v47, v60
	s_waitcnt vmcnt(19)
	v_mov_b32_e32 v48, v60
	v_mov_b32_e32 v49, v60
	v_mov_b32_e32 v50, v60
	v_mov_b32_e32 v51, v60
	s_waitcnt vmcnt(18)
	v_mov_b32_e32 v52, v60
	v_mov_b32_e32 v53, v60
	v_mov_b32_e32 v54, v60
	v_mov_b32_e32 v55, v60
	v_mov_b32_e32 v56, v60
	v_mov_b32_e32 v57, v60
	v_mov_b32_e32 v58, v60
	v_mov_b32_e32 v59, v60
	v_mov_b32_e32 v64, v60
	v_mov_b32_e32 v65, v60
	v_mov_b32_e32 v66, v60
	v_mov_b32_e32 v67, v60
	v_mov_b32_e32 v68, v60
	v_mov_b32_e32 v69, v60
	v_mov_b32_e32 v70, v60
	v_mov_b32_e32 v71, v60
	v_mov_b32_e32 v72, v60
	v_mov_b32_e32 v73, v60
	v_mov_b32_e32 v74, v60
	v_mov_b32_e32 v75, v60
	v_mov_b32_e32 v76, v60
	v_mov_b32_e32 v77, v60
	v_mov_b32_e32 v78, v60
	v_mov_b32_e32 v79, v60
	v_mov_b32_e32 v80, v60
	v_mov_b32_e32 v81, v60
	v_mov_b32_e32 v82, v60
	v_mov_b32_e32 v83, v60
	v_mov_b32_e32 v84, v60
	v_mov_b32_e32 v85, v60
	v_mov_b32_e32 v86, v60
	v_mov_b32_e32 v87, v60
	v_mov_b32_e32 v88, v60
	v_mov_b32_e32 v89, v60
	v_mov_b32_e32 v90, v60
	v_mov_b32_e32 v91, v60
	v_mov_b32_e32 v92, v60
	v_mov_b32_e32 v93, v60
	v_mov_b32_e32 v94, v60
	v_mov_b32_e32 v95, v60
	v_and_b32_e32 v197, 63, v196
	v_lshrrev_b32_e32 v198, 3, v197
	v_and_b32_e32 v199, 7, v197
	v_xor_b32_e32 v199, v199, v198
	v_lshlrev_b32_e32 v199, 4, v199
	v_mul_u32_u24_e32 v198, 2048, v198
	v_add_u32_e32 v240, v198, v199
	v_add_u32_e32 v241, 65536, v240
	v_add_u32_e32 v242, 131072, v240
	v_add_u32_e32 v243, 196608, v240
	v_add_u32_e32 v244, 262144, v240
	v_add_u32_e32 v245, 327680, v240
	v_lshrrev_b32_e32 v198, 6, v196
	v_lshrrev_b32_e32 v199, 1, v198
	v_and_b32_e32 v198, 1, v198
	v_and_b32_e32 v190, 15, v197
	v_lshrrev_b32_e32 v191, 4, v197
	v_and_b32_e32 v192, 7, v190
	v_xor_b32_e32 v191, v191, v192
	v_lshlrev_b32_e32 v191, 4, v191
	v_mul_u32_u24_e32 v199, 0x60, v199
	v_add_u32_e32 v199, v199, v190
	v_lshl_add_u32 v246, v199, 7, v191
	v_xor_b32_e32 v247, 64, v246
	v_lshlrev_b32_e32 v198, 6, v198
	v_add_u32_e32 v198, v198, v190
	v_lshl_add_u32 v248, v198, 7, v191
	v_add_u32_e32 v248, 0x6000, v248
	v_xor_b32_e32 v249, 64, v248
	v_lshrrev_b32_e32 v198, 6, v196
	v_lshlrev_b32_e32 v198, 10, v198
	s_nop 0
	v_readfirstlane_b32 s8, v198
	s_waitcnt lgkmcnt(0)
	s_barrier
	s_add_u32 m0, s8, 0
	s_nop 0
	global_load_lds_dwordx4 v240, s[98:99]
	s_add_u32 m0, s8, 4096
	s_nop 0
	global_load_lds_dwordx4 v241, s[98:99]
	s_add_u32 m0, s8, 8192
	s_nop 0
	global_load_lds_dwordx4 v242, s[98:99]
	s_add_u32 m0, s8, 12288
	s_nop 0
	global_load_lds_dwordx4 v243, s[98:99]
	s_add_u32 m0, s8, 16384
	s_nop 0
	global_load_lds_dwordx4 v244, s[98:99]
	s_add_u32 m0, s8, 20480
	s_nop 0
	global_load_lds_dwordx4 v245, s[98:99]
	s_add_u32 m0, s8, 24576
	s_nop 0
	global_load_lds_dwordx4 v240, s[100:101]
	s_add_u32 m0, s8, 28672
	s_nop 0
	global_load_lds_dwordx4 v241, s[100:101]
	s_add_u32 m0, s8, 32768
	s_nop 0
	global_load_lds_dwordx4 v242, s[100:101]
	s_add_u32 m0, s8, 36864
	s_nop 0
	global_load_lds_dwordx4 v243, s[100:101]
	s_add_u32 s98, s98, 0x80
	s_addc_u32 s99, s99, 0
	s_add_u32 s100, s100, 0x80
	s_addc_u32 s101, s101, 0
	s_waitcnt vmcnt(0)
	s_barrier
	ds_read_b128 v[120:123], v248 offset:0
	ds_read_b128 v[124:127], v248 offset:2048
	ds_read_b128 v[128:131], v248 offset:4096
	ds_read_b128 v[132:135], v248 offset:6144
	ds_read_b128 v[96:99], v246 offset:0
	ds_read_b128 v[100:103], v246 offset:2048
	ds_read_b128 v[104:107], v246 offset:4096
	ds_read_b128 v[108:111], v246 offset:6144
	ds_read_b128 v[112:115], v246 offset:8192
	ds_read_b128 v[116:119], v246 offset:10240
	s_add_u32 m0, s8, 40960
	s_nop 0
	global_load_lds_dwordx4 v240, s[98:99]
	s_add_u32 m0, s8, 45056
	s_nop 0
	global_load_lds_dwordx4 v241, s[98:99]
	s_add_u32 m0, s8, 49152
	s_nop 0
	global_load_lds_dwordx4 v242, s[98:99]
	s_add_u32 m0, s8, 53248
	s_nop 0
	global_load_lds_dwordx4 v243, s[98:99]
	s_add_u32 m0, s8, 57344
	s_nop 0
	global_load_lds_dwordx4 v244, s[98:99]
	s_add_u32 m0, s8, 61440
	s_nop 0
	global_load_lds_dwordx4 v245, s[98:99]
	s_add_u32 m0, s8, 65536
	s_nop 0
	global_load_lds_dwordx4 v240, s[100:101]
	s_add_u32 m0, s8, 69632
	s_nop 0
	global_load_lds_dwordx4 v241, s[100:101]
	s_add_u32 m0, s8, 73728
	s_nop 0
	global_load_lds_dwordx4 v242, s[100:101]
	s_add_u32 m0, s8, 77824
	s_nop 0
	global_load_lds_dwordx4 v243, s[100:101]
	s_add_u32 s98, s98, 0x80
	s_addc_u32 s99, s99, 0
	s_add_u32 s100, s100, 0x80
	s_addc_u32 s101, s101, 0
	s_waitcnt lgkmcnt(0)
	v_mfma_f32_16x16x32_bf16 v[92:95], v[120:123], v[96:99], v[92:95]
	v_mfma_f32_16x16x32_bf16 v[88:91], v[124:127], v[96:99], v[88:91]
	ds_read_b128 v[224:227], v249 offset:0
	v_mfma_f32_16x16x32_bf16 v[84:87], v[128:131], v[96:99], v[84:87]
	v_mfma_f32_16x16x32_bf16 v[80:83], v[132:135], v[96:99], v[80:83]
	ds_read_b128 v[228:231], v249 offset:2048
	v_mfma_f32_16x16x32_bf16 v[76:79], v[120:123], v[100:103], v[76:79]
	v_mfma_f32_16x16x32_bf16 v[72:75], v[124:127], v[100:103], v[72:75]
	ds_read_b128 v[232:235], v249 offset:4096
	v_mfma_f32_16x16x32_bf16 v[68:71], v[128:131], v[100:103], v[68:71]
	v_mfma_f32_16x16x32_bf16 v[64:67], v[132:135], v[100:103], v[64:67]
	ds_read_b128 v[236:239], v249 offset:6144
	v_mfma_f32_16x16x32_bf16 v[56:59], v[120:123], v[104:107], v[56:59]
	v_mfma_f32_16x16x32_bf16 v[52:55], v[124:127], v[104:107], v[52:55]
	ds_read_b128 v[200:203], v247 offset:0
	v_mfma_f32_16x16x32_bf16 v[48:51], v[128:131], v[104:107], v[48:51]
	v_mfma_f32_16x16x32_bf16 v[44:47], v[132:135], v[104:107], v[44:47]
	ds_read_b128 v[204:207], v247 offset:2048
	v_mfma_f32_16x16x32_bf16 v[40:43], v[120:123], v[108:111], v[40:43]
	v_mfma_f32_16x16x32_bf16 v[36:39], v[124:127], v[108:111], v[36:39]
	ds_read_b128 v[208:211], v247 offset:4096
	v_mfma_f32_16x16x32_bf16 v[32:35], v[128:131], v[108:111], v[32:35]
	v_mfma_f32_16x16x32_bf16 v[28:31], v[132:135], v[108:111], v[28:31]
	ds_read_b128 v[212:215], v247 offset:6144
	v_mfma_f32_16x16x32_bf16 v[24:27], v[120:123], v[112:115], v[24:27]
	v_mfma_f32_16x16x32_bf16 v[20:23], v[124:127], v[112:115], v[20:23]
	ds_read_b128 v[216:219], v247 offset:8192
	v_mfma_f32_16x16x32_bf16 v[16:19], v[128:131], v[112:115], v[16:19]
	v_mfma_f32_16x16x32_bf16 v[12:15], v[132:135], v[112:115], v[12:15]
	ds_read_b128 v[220:223], v247 offset:10240
	v_mfma_f32_16x16x32_bf16 v[8:11], v[120:123], v[116:119], v[8:11]
	v_mfma_f32_16x16x32_bf16 v[4:7], v[124:127], v[116:119], v[4:7]
	v_mfma_f32_16x16x32_bf16 v[0:3], v[128:131], v[116:119], v[0:3]
	v_mfma_f32_16x16x32_bf16 v[60:63], v[132:135], v[116:119], v[60:63]
	s_mov_b32 s9, 7

.LBB0_1118:
	s_bfe_u32 s4, s12, 0x30005
	s_mul_i32 s7, s4, 0xc0
	s_bfe_u32 s4, s14, 0x30007
	v_mad_u64_u32 v[144:145], s[30:31], s4, v162, v[142:143]
	s_lshl_b32 s30, s11, 5
	s_lshl_b32 s4, s6, 8
	s_and_b32 s30, s30, 0xe0
	s_or_b32 s30, s30, s4
	s_mul_i32 s30, s30, 6
	v_mad_i64_i32 v[0:1], s[34:35], s30, v163, v[138:139]
	v_add_co_u32_e32 v2, vcc, s17, v0
	s_lshl_b32 s4, s11, 4
	s_nop 0
	v_addc_co_u32_e32 v3, vcc, 0, v1, vcc
	s_nop 0
	v_readfirstlane_b32 s98, v0
	v_readfirstlane_b32 s99, v1
	v_add_co_u32_e32 v2, vcc, s18, v0
	s_and_b32 s31, s4, 0x380
	s_nop 0
	v_addc_co_u32_e32 v3, vcc, 0, v1, vcc
	v_add_co_u32_e32 v4, vcc, s19, v0
	s_mul_i32 s4, s31, 0x1600
	s_nop 0
	v_addc_co_u32_e32 v5, vcc, 0, v1, vcc
	v_add_co_u32_e32 v2, vcc, s16, v0
	v_mov_b32_e32 v64, 0
	s_nop 0
	v_addc_co_u32_e32 v3, vcc, 0, v1, vcc
	v_add_co_u32_e32 v0, vcc, 0xdc000, v0
	v_mov_b32_e32 v65, v137
	s_nop 0
	v_addc_co_u32_e32 v1, vcc, 0, v1, vcc
	v_lshl_add_u64 v[0:1], v[140:141], 0, s[4:5]
	v_add_co_u32_e32 v2, vcc, s17, v0
	s_mul_i32 s4, s6, 0x600
	s_nop 0
	v_addc_co_u32_e32 v3, vcc, 0, v1, vcc
	s_nop 0
	v_readfirstlane_b32 s100, v0
	v_readfirstlane_b32 s101, v1
	v_add_co_u32_e32 v2, vcc, 0x58000, v0
	s_add_i32 s4, s4, s7
	s_nop 0
	v_addc_co_u32_e32 v3, vcc, 0, v1, vcc
	v_add_co_u32_e32 v0, vcc, 0x84000, v0
	v_mad_i64_i32 v[146:147], s[6:7], s4, v163, v[142:143]
	s_nop 0
	v_addc_co_u32_e32 v1, vcc, 0, v1, vcc
	s_mov_b64 s[6:7], 0
	v_mov_b32_e32 v66, v137
	v_mov_b32_e32 v67, v137
	v_mov_b32_e32 v0, 0
	v_mov_b32_e32 v1, v137
	v_mov_b32_e32 v2, v137
	v_mov_b32_e32 v3, v137
	v_mov_b32_e32 v4, 0
	v_mov_b32_e32 v5, v137
	v_mov_b32_e32 v6, v137
	v_mov_b32_e32 v7, v137
	v_mov_b32_e32 v8, 0
	v_mov_b32_e32 v9, v137
	v_mov_b32_e32 v10, v137
	v_mov_b32_e32 v11, v137
	v_mov_b32_e32 v12, 0
	v_mov_b32_e32 v13, v137
	v_mov_b32_e32 v14, v137
	v_mov_b32_e32 v15, v137
	v_mov_b32_e32 v16, 0
	v_mov_b32_e32 v17, v137
	v_mov_b32_e32 v18, v137
	v_mov_b32_e32 v19, v137
	v_mov_b32_e32 v20, 0
	v_mov_b32_e32 v21, v137
	v_mov_b32_e32 v22, v137
	v_mov_b32_e32 v23, v137
	v_mov_b32_e32 v24, 0
	v_mov_b32_e32 v25, v137
	v_mov_b32_e32 v26, v137
	v_mov_b32_e32 v27, v137
	v_mov_b32_e32 v28, 0
	v_mov_b32_e32 v29, v137
	v_mov_b32_e32 v30, v137
	v_mov_b32_e32 v31, v137
	v_mov_b32_e32 v32, 0
	v_mov_b32_e32 v33, v137
	v_mov_b32_e32 v34, v137
	v_mov_b32_e32 v35, v137
	v_mov_b32_e32 v36, 0
	v_mov_b32_e32 v37, v137
	v_mov_b32_e32 v38, v137
	v_mov_b32_e32 v39, v137
	v_mov_b32_e32 v40, 0
	v_mov_b32_e32 v41, v137
	v_mov_b32_e32 v42, v137
	v_mov_b32_e32 v43, v137
	v_mov_b32_e32 v44, 0
	v_mov_b32_e32 v45, v137
	v_mov_b32_e32 v46, v137
	v_mov_b32_e32 v47, v137
	v_mov_b32_e32 v48, 0
	v_mov_b32_e32 v49, v137
	v_mov_b32_e32 v50, v137
	v_mov_b32_e32 v51, v137
	v_mov_b32_e32 v52, 0
	v_mov_b32_e32 v53, v137
	v_mov_b32_e32 v54, v137
	v_mov_b32_e32 v55, v137
	v_mov_b32_e32 v56, 0
	v_mov_b32_e32 v57, v137
	v_mov_b32_e32 v58, v137
	v_mov_b32_e32 v59, v137
	v_mov_b32_e32 v60, 0
	v_mov_b32_e32 v61, v137
	v_mov_b32_e32 v62, v137
	v_mov_b32_e32 v63, v137
	v_mov_b32_e32 v68, 0
	v_mov_b32_e32 v69, v137
	v_mov_b32_e32 v70, v137
	v_mov_b32_e32 v71, v137
	v_mov_b32_e32 v72, 0
	v_mov_b32_e32 v73, v137
	v_mov_b32_e32 v74, v137
	v_mov_b32_e32 v75, v137
	v_mov_b32_e32 v76, 0
	v_mov_b32_e32 v77, v137
	v_mov_b32_e32 v78, v137
	v_mov_b32_e32 v79, v137
	v_mov_b32_e32 v80, 0
	v_mov_b32_e32 v81, v137
	v_mov_b32_e32 v82, v137
	v_mov_b32_e32 v83, v137
	v_mov_b32_e32 v84, 0
	v_mov_b32_e32 v85, v137
	v_mov_b32_e32 v86, v137
	v_mov_b32_e32 v87, v137
	v_mov_b32_e32 v88, 0
	v_mov_b32_e32 v89, v137
	v_mov_b32_e32 v90, v137
	v_mov_b32_e32 v91, v137
	v_mov_b32_e32 v92, 0
	v_mov_b32_e32 v93, v137
	v_mov_b32_e32 v94, v137
	v_mov_b32_e32 v95, v137
	v_and_b32_e32 v197, 63, v196
	v_lshrrev_b32_e32 v198, 3, v197
	v_and_b32_e32 v199, 7, v197
	v_xor_b32_e32 v199, v199, v198
	v_lshlrev_b32_e32 v199, 4, v199
	v_mul_u32_u24_e32 v198, 5632, v198
	v_add_u32_e32 v240, v198, v199
	v_add_u32_e32 v241, 180224, v240
	v_add_u32_e32 v242, 360448, v240
	v_add_u32_e32 v243, 540672, v240
	v_add_u32_e32 v244, 720896, v240
	v_add_u32_e32 v245, 901120, v240
	v_lshrrev_b32_e32 v198, 6, v196
	v_lshrrev_b32_e32 v199, 1, v198
	v_and_b32_e32 v198, 1, v198
	v_and_b32_e32 v190, 15, v197
	v_lshrrev_b32_e32 v191, 4, v197
	v_and_b32_e32 v192, 7, v190
	v_xor_b32_e32 v191, v191, v192
	v_lshlrev_b32_e32 v191, 4, v191
	v_mul_u32_u24_e32 v199, 0x60, v199
	v_add_u32_e32 v199, v199, v190
	v_lshl_add_u32 v246, v199, 7, v191
	v_xor_b32_e32 v247, 64, v246
	v_lshlrev_b32_e32 v198, 6, v198
	v_add_u32_e32 v198, v198, v190
	v_lshl_add_u32 v248, v198, 7, v191
	v_add_u32_e32 v248, 0x6000, v248
	v_xor_b32_e32 v249, 64, v248
	v_lshrrev_b32_e32 v198, 6, v196
	v_lshlrev_b32_e32 v198, 10, v198
	s_nop 0
	v_readfirstlane_b32 s6, v198
	s_waitcnt lgkmcnt(0)
	s_barrier
	s_add_u32 m0, s6, 0
	s_nop 0
	global_load_lds_dwordx4 v240, s[98:99]
	s_add_u32 m0, s6, 4096
	s_nop 0
	global_load_lds_dwordx4 v241, s[98:99]
	s_add_u32 m0, s6, 8192
	s_nop 0
	global_load_lds_dwordx4 v242, s[98:99]
	s_add_u32 m0, s6, 12288
	s_nop 0
	global_load_lds_dwordx4 v243, s[98:99]
	s_add_u32 m0, s6, 16384
	s_nop 0
	global_load_lds_dwordx4 v244, s[98:99]
	s_add_u32 m0, s6, 20480
	s_nop 0
	global_load_lds_dwordx4 v245, s[98:99]
	s_add_u32 m0, s6, 24576
	s_nop 0
	global_load_lds_dwordx4 v240, s[100:101]
	s_add_u32 m0, s6, 28672
	s_nop 0
	global_load_lds_dwordx4 v241, s[100:101]
	s_add_u32 m0, s6, 32768
	s_nop 0
	global_load_lds_dwordx4 v242, s[100:101]
	s_add_u32 m0, s6, 36864
	s_nop 0
	global_load_lds_dwordx4 v243, s[100:101]
	s_add_u32 s98, s98, 0x80
	s_addc_u32 s99, s99, 0
	s_add_u32 s100, s100, 0x80
	s_addc_u32 s101, s101, 0
	s_waitcnt vmcnt(0)
	s_barrier
	ds_read_b128 v[120:123], v248 offset:0
	ds_read_b128 v[124:127], v248 offset:2048
	ds_read_b128 v[128:131], v248 offset:4096
	ds_read_b128 v[132:135], v248 offset:6144
	ds_read_b128 v[96:99], v246 offset:0
	ds_read_b128 v[100:103], v246 offset:2048
	ds_read_b128 v[104:107], v246 offset:4096
	ds_read_b128 v[108:111], v246 offset:6144
	ds_read_b128 v[112:115], v246 offset:8192
	ds_read_b128 v[116:119], v246 offset:10240
	s_add_u32 m0, s6, 40960
	s_nop 0
	global_load_lds_dwordx4 v240, s[98:99]
	s_add_u32 m0, s6, 45056
	s_nop 0
	global_load_lds_dwordx4 v241, s[98:99]
	s_add_u32 m0, s6, 49152
	s_nop 0
	global_load_lds_dwordx4 v242, s[98:99]
	s_add_u32 m0, s6, 53248
	s_nop 0
	global_load_lds_dwordx4 v243, s[98:99]
	s_add_u32 m0, s6, 57344
	s_nop 0
	global_load_lds_dwordx4 v244, s[98:99]
	s_add_u32 m0, s6, 61440
	s_nop 0
	global_load_lds_dwordx4 v245, s[98:99]
	s_add_u32 m0, s6, 65536
	s_nop 0
	global_load_lds_dwordx4 v240, s[100:101]
	s_add_u32 m0, s6, 69632
	s_nop 0
	global_load_lds_dwordx4 v241, s[100:101]
	s_add_u32 m0, s6, 73728
	s_nop 0
	global_load_lds_dwordx4 v242, s[100:101]
	s_add_u32 m0, s6, 77824
	s_nop 0
	global_load_lds_dwordx4 v243, s[100:101]
	s_add_u32 s98, s98, 0x80
	s_addc_u32 s99, s99, 0
	s_add_u32 s100, s100, 0x80
	s_addc_u32 s101, s101, 0
	s_waitcnt lgkmcnt(0)
	v_mfma_f32_16x16x32_bf16 v[92:95], v[120:123], v[96:99], v[92:95]
	v_mfma_f32_16x16x32_bf16 v[88:91], v[124:127], v[96:99], v[88:91]
	ds_read_b128 v[224:227], v249 offset:0
	v_mfma_f32_16x16x32_bf16 v[84:87], v[128:131], v[96:99], v[84:87]
	v_mfma_f32_16x16x32_bf16 v[80:83], v[132:135], v[96:99], v[80:83]
	ds_read_b128 v[228:231], v249 offset:2048
	v_mfma_f32_16x16x32_bf16 v[76:79], v[120:123], v[100:103], v[76:79]
	v_mfma_f32_16x16x32_bf16 v[72:75], v[124:127], v[100:103], v[72:75]
	ds_read_b128 v[232:235], v249 offset:4096
	v_mfma_f32_16x16x32_bf16 v[68:71], v[128:131], v[100:103], v[68:71]
	v_mfma_f32_16x16x32_bf16 v[60:63], v[132:135], v[100:103], v[60:63]
	ds_read_b128 v[236:239], v249 offset:6144
	v_mfma_f32_16x16x32_bf16 v[56:59], v[120:123], v[104:107], v[56:59]
	v_mfma_f32_16x16x32_bf16 v[52:55], v[124:127], v[104:107], v[52:55]
	ds_read_b128 v[200:203], v247 offset:0
	v_mfma_f32_16x16x32_bf16 v[48:51], v[128:131], v[104:107], v[48:51]
	v_mfma_f32_16x16x32_bf16 v[44:47], v[132:135], v[104:107], v[44:47]
	ds_read_b128 v[204:207], v247 offset:2048
	v_mfma_f32_16x16x32_bf16 v[40:43], v[120:123], v[108:111], v[40:43]
	v_mfma_f32_16x16x32_bf16 v[36:39], v[124:127], v[108:111], v[36:39]
	ds_read_b128 v[208:211], v247 offset:4096
	v_mfma_f32_16x16x32_bf16 v[32:35], v[128:131], v[108:111], v[32:35]
	v_mfma_f32_16x16x32_bf16 v[28:31], v[132:135], v[108:111], v[28:31]
	ds_read_b128 v[212:215], v247 offset:6144
	v_mfma_f32_16x16x32_bf16 v[24:27], v[120:123], v[112:115], v[24:27]
	v_mfma_f32_16x16x32_bf16 v[20:23], v[124:127], v[112:115], v[20:23]
	ds_read_b128 v[216:219], v247 offset:8192
	v_mfma_f32_16x16x32_bf16 v[16:19], v[128:131], v[112:115], v[16:19]
	v_mfma_f32_16x16x32_bf16 v[12:15], v[132:135], v[112:115], v[12:15]
	ds_read_b128 v[220:223], v247 offset:10240
	v_mfma_f32_16x16x32_bf16 v[8:11], v[120:123], v[116:119], v[8:11]
	v_mfma_f32_16x16x32_bf16 v[4:7], v[124:127], v[116:119], v[4:7]
	v_mfma_f32_16x16x32_bf16 v[0:3], v[128:131], v[116:119], v[0:3]
	v_mfma_f32_16x16x32_bf16 v[64:67], v[132:135], v[116:119], v[64:67]
	s_mov_b32 s7, 21

.LBB0_1242:
	s_ashr_i32 s0, s29, 6
	s_mul_i32 s2, s0, s27
	s_add_i32 s2, s2, s26
	s_cmp_gt_i32 s2, 23
	s_mov_b32 s4, 2
	s_cbranch_scc1 .LBB0_1569
	s_ashr_i32 s0, s2, 31
	s_lshr_b32 s0, s0, 30
	s_add_i32 s0, s2, s0
	s_and_b32 s1, s0, 0x1ffffffc
	s_sub_i32 s1, s2, s1
	s_lshl_b32 s1, s1, 3
	s_bfe_u32 s3, s29, 0x30003
	s_or_b32 s6, s1, s3
	s_cmp_gt_i32 s6, 27
	s_mov_b32 s4, 4
	s_cbranch_scc1 .LBB0_1569
	s_ashr_i32 s7, s0, 2
	s_lshl_b32 s0, s29, 8
	s_lshl_b32 s11, s7, 11
	s_and_b32 s0, s0, 0x700
	s_or_b32 s0, s11, s0
	s_ashr_i32 s1, s0, 31
	s_lshl_b64 s[4:5], s[0:1], 11
	v_lshl_add_u64 v[0:1], v[182:183], 0, s[4:5]
	v_add_co_u32_e32 v2, vcc, 0x10000, v0
	s_lshl_b32 s22, s6, 7
	s_nop 0
	v_addc_co_u32_e32 v3, vcc, 0, v1, vcc
	s_nop 0
	v_readfirstlane_b32 s98, v0
	v_readfirstlane_b32 s99, v1
	v_add_co_u32_e32 v2, vcc, 0x20000, v0
	s_ashr_i32 s23, s22, 31
	s_nop 0
	v_addc_co_u32_e32 v3, vcc, 0, v1, vcc
	v_add_co_u32_e32 v4, vcc, 0x30000, v0
	s_lshl_b64 s[8:9], s[22:23], 11
	s_nop 0
	v_addc_co_u32_e32 v5, vcc, 0, v1, vcc
	v_add_co_u32_e32 v2, vcc, 0x40000, v0
	s_lshl_b32 s1, s2, 3
	s_nop 0
	v_addc_co_u32_e32 v3, vcc, 0, v1, vcc
	v_add_co_u32_e32 v4, vcc, 0x50000, v0
	s_or_b32 s1, s1, s3
	s_nop 0
	v_addc_co_u32_e32 v5, vcc, 0, v1, vcc
	v_add_co_u32_e32 v2, vcc, 0x60000, v0
	s_lshl_b32 s2, s7, 5
	s_nop 0
	v_addc_co_u32_e32 v3, vcc, 0, v1, vcc
	v_add_co_u32_e32 v0, vcc, 0x70000, v0
	s_and_b32 s10, s30, 0x700
	s_nop 0
	v_addc_co_u32_e32 v1, vcc, 0, v1, vcc
	v_lshl_add_u64 v[0:1], v[184:185], 0, s[8:9]
	v_add_co_u32_e32 v2, vcc, s34, v0
	s_sub_i32 s1, s1, s2
	s_nop 0
	v_addc_co_u32_e32 v3, vcc, 0, v1, vcc
	s_nop 0
	v_readfirstlane_b32 s100, v0
	v_readfirstlane_b32 s101, v1
	v_add_co_u32_e32 v2, vcc, s35, v0
	s_or_b32 s4, s11, s10
	s_nop 0
	v_addc_co_u32_e32 v3, vcc, 0, v1, vcc
	v_add_co_u32_e32 v0, vcc, s38, v0
	s_lshl_b32 s2, s1, 7
	s_nop 0
	v_addc_co_u32_e32 v1, vcc, 0, v1, vcc
	s_ashr_i32 s5, s4, 31
	s_ashr_i32 s3, s2, 31
	s_lshl_b64 s[4:5], s[4:5], 11
	s_lshl_b64 s[2:3], s[2:3], 11
	v_mov_b32_e32 v76, 0
	v_lshl_add_u64 v[188:189], v[186:187], 0, s[4:5]
	v_lshl_add_u64 v[190:191], v[186:187], 0, s[2:3]
	s_mov_b64 s[2:3], 0
	v_mov_b32_e32 v77, v76
	v_mov_b32_e32 v78, v76
	v_mov_b32_e32 v79, v76
	v_mov_b32_e32 v0, v76
	v_mov_b32_e32 v1, v76
	v_mov_b32_e32 v2, v76
	v_mov_b32_e32 v3, v76
	v_mov_b32_e32 v4, v76
	v_mov_b32_e32 v5, v76
	v_mov_b32_e32 v6, v76
	v_mov_b32_e32 v7, v76
	v_mov_b32_e32 v8, v76
	v_mov_b32_e32 v9, v76
	v_mov_b32_e32 v10, v76
	v_mov_b32_e32 v11, v76
	v_mov_b32_e32 v12, v76
	v_mov_b32_e32 v13, v76
	v_mov_b32_e32 v14, v76
	v_mov_b32_e32 v15, v76
	v_mov_b32_e32 v16, v76
	v_mov_b32_e32 v17, v76
	v_mov_b32_e32 v18, v76
	v_mov_b32_e32 v19, v76
	v_mov_b32_e32 v20, v76
	v_mov_b32_e32 v21, v76
	v_mov_b32_e32 v22, v76
	v_mov_b32_e32 v23, v76
	v_mov_b32_e32 v24, v76
	v_mov_b32_e32 v25, v76
	v_mov_b32_e32 v26, v76
	v_mov_b32_e32 v27, v76
	v_mov_b32_e32 v28, v76
	v_mov_b32_e32 v29, v76
	v_mov_b32_e32 v30, v76
	v_mov_b32_e32 v31, v76
	v_mov_b32_e32 v32, v76
	v_mov_b32_e32 v33, v76
	v_mov_b32_e32 v34, v76
	v_mov_b32_e32 v35, v76
	s_waitcnt vmcnt(24)
	v_mov_b32_e32 v36, v76
	v_mov_b32_e32 v37, v76
	v_mov_b32_e32 v38, v76
	v_mov_b32_e32 v39, v76
	s_waitcnt vmcnt(23)
	v_mov_b32_e32 v40, v76
	v_mov_b32_e32 v41, v76
	v_mov_b32_e32 v42, v76
	v_mov_b32_e32 v43, v76
	s_waitcnt vmcnt(22)
	v_mov_b32_e32 v44, v76
	v_mov_b32_e32 v45, v76
	v_mov_b32_e32 v46, v76
	v_mov_b32_e32 v47, v76
	s_waitcnt vmcnt(21)
	v_mov_b32_e32 v48, v76
	v_mov_b32_e32 v49, v76
	v_mov_b32_e32 v50, v76
	v_mov_b32_e32 v51, v76
	s_waitcnt vmcnt(20)
	v_mov_b32_e32 v52, v76
	v_mov_b32_e32 v53, v76
	v_mov_b32_e32 v54, v76
	v_mov_b32_e32 v55, v76
	v_mov_b32_e32 v56, v76
	v_mov_b32_e32 v57, v76
	v_mov_b32_e32 v58, v76
	v_mov_b32_e32 v59, v76
	v_mov_b32_e32 v60, v76
	v_mov_b32_e32 v61, v76
	v_mov_b32_e32 v62, v76
	v_mov_b32_e32 v63, v76
	v_mov_b32_e32 v64, v76
	v_mov_b32_e32 v65, v76
	v_mov_b32_e32 v66, v76
	v_mov_b32_e32 v67, v76
	v_mov_b32_e32 v68, v76
	v_mov_b32_e32 v69, v76
	v_mov_b32_e32 v70, v76
	v_mov_b32_e32 v71, v76
	v_mov_b32_e32 v72, v76
	v_mov_b32_e32 v73, v76
	v_mov_b32_e32 v74, v76
	v_mov_b32_e32 v75, v76
	v_mov_b32_e32 v80, v76
	v_mov_b32_e32 v81, v76
	v_mov_b32_e32 v82, v76
	v_mov_b32_e32 v83, v76
	v_mov_b32_e32 v84, v76
	v_mov_b32_e32 v85, v76
	v_mov_b32_e32 v86, v76
	v_mov_b32_e32 v87, v76
	v_mov_b32_e32 v88, v76
	v_mov_b32_e32 v89, v76
	v_mov_b32_e32 v90, v76
	v_mov_b32_e32 v91, v76
	v_mov_b32_e32 v92, v76
	v_mov_b32_e32 v93, v76
	v_mov_b32_e32 v94, v76
	v_mov_b32_e32 v95, v76
	v_mov_b32_e32 v96, v76
	v_mov_b32_e32 v97, v76
	v_mov_b32_e32 v98, v76
	v_mov_b32_e32 v99, v76
	v_mov_b32_e32 v100, v76
	v_mov_b32_e32 v101, v76
	v_mov_b32_e32 v102, v76
	v_mov_b32_e32 v103, v76
	v_mov_b32_e32 v104, v76
	v_mov_b32_e32 v105, v76
	v_mov_b32_e32 v106, v76
	v_mov_b32_e32 v107, v76
	v_mov_b32_e32 v108, v76
	v_mov_b32_e32 v109, v76
	v_mov_b32_e32 v110, v76
	v_mov_b32_e32 v111, v76
	v_mov_b32_e32 v112, v76
	v_mov_b32_e32 v113, v76
	v_mov_b32_e32 v114, v76
	v_mov_b32_e32 v115, v76
	v_mov_b32_e32 v116, v76
	v_mov_b32_e32 v117, v76
	v_mov_b32_e32 v118, v76
	v_mov_b32_e32 v119, v76
	v_mov_b32_e32 v120, v76
	v_mov_b32_e32 v121, v76
	v_mov_b32_e32 v122, v76
	v_mov_b32_e32 v123, v76
	v_mov_b32_e32 v124, v76
	v_mov_b32_e32 v125, v76
	v_mov_b32_e32 v126, v76
	v_mov_b32_e32 v127, v76
	v_mov_b32_e32 v234, 0
	ds_read_b64 v[232:233], v234
	v_and_b32_e32 v235, 63, v196
	v_lshrrev_b32_e32 v250, 3, v235
	v_and_b32_e32 v247, 7, v235
	v_xor_b32_e32 v247, v247, v250
	v_lshlrev_b32_e32 v247, 4, v247
	v_mul_u32_u24_e32 v250, 2048, v250
	v_add_u32_e32 v134, v250, v247
	v_add_u32_e32 v142, 65536, v134
	v_add_u32_e32 v143, 131072, v134
	v_add_u32_e32 v180, 196608, v134
	v_add_u32_e32 v215, 262144, v134
	v_add_u32_e32 v216, 327680, v134
	v_add_u32_e32 v217, 393216, v134
	v_add_u32_e32 v218, 458752, v134
	v_lshrrev_b32_e32 v250, 6, v196
	v_lshrrev_b32_e32 v247, 1, v250
	v_and_b32_e32 v250, 1, v250
	v_and_b32_e32 v244, 15, v235
	v_lshrrev_b32_e32 v245, 4, v235
	v_and_b32_e32 v246, 7, v244
	v_xor_b32_e32 v245, v245, v246
	v_lshlrev_b32_e32 v245, 4, v245
	v_lshlrev_b32_e32 v247, 7, v247
	v_add_u32_e32 v247, v247, v244
	v_lshl_add_u32 v252, v247, 7, v245
	v_xor_b32_e32 v251, 64, v252
	v_lshlrev_b32_e32 v250, 6, v250
	v_add_u32_e32 v250, v250, v244
	v_lshl_add_u32 v248, v250, 7, v245
	v_add_u32_e32 v248, 65536, v248
	v_xor_b32_e32 v249, 64, v248
	v_lshrrev_b32_e32 v250, 6, v196
	v_lshlrev_b32_e32 v250, 10, v250
	s_nop 0
	v_readfirstlane_b32 s2, v250
	s_waitcnt lgkmcnt(0)
	s_barrier
	s_add_u32 m0, s2, 0
	s_nop 0
	global_load_lds_dwordx4 v134, s[98:99]
	s_add_u32 m0, s2, 4096
	s_nop 0
	global_load_lds_dwordx4 v142, s[98:99]
	s_add_u32 m0, s2, 8192
	s_nop 0
	global_load_lds_dwordx4 v143, s[98:99]
	s_add_u32 m0, s2, 12288
	s_nop 0
	global_load_lds_dwordx4 v180, s[98:99]
	s_add_u32 m0, s2, 16384
	s_nop 0
	global_load_lds_dwordx4 v215, s[98:99]
	s_add_u32 m0, s2, 20480
	s_nop 0
	global_load_lds_dwordx4 v216, s[98:99]
	s_add_u32 m0, s2, 24576
	s_nop 0
	global_load_lds_dwordx4 v217, s[98:99]
	s_add_u32 m0, s2, 28672
	s_nop 0
	global_load_lds_dwordx4 v218, s[98:99]
	s_add_u32 m0, s2, 65536
	s_nop 0
	global_load_lds_dwordx4 v134, s[100:101]
	s_add_u32 m0, s2, 69632
	s_nop 0
	global_load_lds_dwordx4 v142, s[100:101]
	s_add_u32 m0, s2, 73728
	s_nop 0
	global_load_lds_dwordx4 v143, s[100:101]
	s_add_u32 m0, s2, 77824
	s_nop 0
	global_load_lds_dwordx4 v180, s[100:101]
	s_add_u32 s98, s98, 0x80
	s_addc_u32 s99, s99, 0
	s_add_u32 s100, s100, 0x80
	s_addc_u32 s101, s101, 0
	s_mov_b32 s3, 7
.Lg8p11_loop:
	s_waitcnt vmcnt(0) lgkmcnt(0)
	s_barrier
	s_add_u32 m0, s2, 32768
	ds_read_b128 v[128:131], v248 offset:0
	global_load_lds_dwordx4 v134, s[98:99]
	s_add_u32 m0, s2, 36864
	ds_read_b128 v[148:151], v248 offset:2048
	global_load_lds_dwordx4 v142, s[98:99]
	s_add_u32 m0, s2, 40960
	ds_read_b128 v[156:159], v248 offset:4096
	global_load_lds_dwordx4 v143, s[98:99]
	s_add_u32 m0, s2, 45056
	ds_read_b128 v[164:167], v248 offset:6144
	global_load_lds_dwordx4 v180, s[98:99]
	s_add_u32 m0, s2, 49152
	ds_read_b128 v[144:147], v249 offset:0
	global_load_lds_dwordx4 v215, s[98:99]
	s_add_u32 m0, s2, 53248
	ds_read_b128 v[152:155], v249 offset:2048
	global_load_lds_dwordx4 v216, s[98:99]
	s_add_u32 m0, s2, 57344
	ds_read_b128 v[160:163], v249 offset:4096
	global_load_lds_dwordx4 v217, s[98:99]
	s_add_u32 m0, s2, 61440
	ds_read_b128 v[168:171], v249 offset:6144
	global_load_lds_dwordx4 v218, s[98:99]
	ds_read_b128 v[172:175], v252 offset:0
	ds_read_b128 v[176:179], v252 offset:2048
	ds_read_b128 v[188:191], v252 offset:4096
	ds_read_b128 v[220:223], v252 offset:6144
	s_waitcnt lgkmcnt(4)
	s_barrier
	s_waitcnt lgkmcnt(3)
	s_add_u32 m0, s2, 65536
	v_mfma_f32_16x16x32_bf16 v[124:127], v[128:131], v[172:175], v[124:127]
	ds_read_b128 v[224:227], v252 offset:8192
	global_load_lds_dwordx4 v134, s[100:101]
	v_mfma_f32_16x16x32_bf16 v[120:123], v[148:151], v[172:175], v[120:123]
	s_add_u32 m0, s2, 69632
	v_mfma_f32_16x16x32_bf16 v[116:119], v[156:159], v[172:175], v[116:119]
	global_load_lds_dwordx4 v142, s[100:101]
	v_mfma_f32_16x16x32_bf16 v[112:115], v[164:167], v[172:175], v[112:115]
	s_waitcnt lgkmcnt(3)
	s_add_u32 m0, s2, 73728
	v_mfma_f32_16x16x32_bf16 v[108:111], v[128:131], v[176:179], v[108:111]
	ds_read_b128 v[228:231], v252 offset:10240
	global_load_lds_dwordx4 v143, s[100:101]
	v_mfma_f32_16x16x32_bf16 v[104:107], v[148:151], v[176:179], v[104:107]
	s_add_u32 m0, s2, 77824
	v_mfma_f32_16x16x32_bf16 v[100:103], v[156:159], v[176:179], v[100:103]
	global_load_lds_dwordx4 v180, s[100:101]
	v_mfma_f32_16x16x32_bf16 v[96:99], v[164:167], v[176:179], v[96:99]
	s_waitcnt lgkmcnt(3)
	v_mfma_f32_16x16x32_bf16 v[92:95], v[128:131], v[188:191], v[92:95]
	ds_read_b128 v[172:175], v252 offset:12288
	v_mfma_f32_16x16x32_bf16 v[88:91], v[148:151], v[188:191], v[88:91]
	v_mfma_f32_16x16x32_bf16 v[84:87], v[156:159], v[188:191], v[84:87]
	v_mfma_f32_16x16x32_bf16 v[80:83], v[164:167], v[188:191], v[80:83]
	s_waitcnt lgkmcnt(3)
	v_mfma_f32_16x16x32_bf16 v[72:75], v[128:131], v[220:223], v[72:75]
	ds_read_b128 v[176:179], v252 offset:14336
	v_mfma_f32_16x16x32_bf16 v[68:71], v[148:151], v[220:223], v[68:71]
	v_mfma_f32_16x16x32_bf16 v[64:67], v[156:159], v[220:223], v[64:67]
	v_mfma_f32_16x16x32_bf16 v[60:63], v[164:167], v[220:223], v[60:63]
	s_waitcnt lgkmcnt(3)
	v_mfma_f32_16x16x32_bf16 v[56:59], v[128:131], v[224:227], v[56:59]
	ds_read_b128 v[188:191], v251 offset:0
	v_mfma_f32_16x16x32_bf16 v[52:55], v[148:151], v[224:227], v[52:55]
	v_mfma_f32_16x16x32_bf16 v[48:51], v[156:159], v[224:227], v[48:51]
	v_mfma_f32_16x16x32_bf16 v[44:47], v[164:167], v[224:227], v[44:47]
	s_waitcnt lgkmcnt(3)
	v_mfma_f32_16x16x32_bf16 v[40:43], v[128:131], v[228:231], v[40:43]
	ds_read_b128 v[220:223], v251 offset:2048
	v_mfma_f32_16x16x32_bf16 v[36:39], v[148:151], v[228:231], v[36:39]
	v_mfma_f32_16x16x32_bf16 v[32:35], v[156:159], v[228:231], v[32:35]
	v_mfma_f32_16x16x32_bf16 v[28:31], v[164:167], v[228:231], v[28:31]
	s_waitcnt lgkmcnt(3)
	v_mfma_f32_16x16x32_bf16 v[24:27], v[128:131], v[172:175], v[24:27]
	ds_read_b128 v[224:227], v251 offset:4096
	v_mfma_f32_16x16x32_bf16 v[20:23], v[148:151], v[172:175], v[20:23]
	v_mfma_f32_16x16x32_bf16 v[16:19], v[156:159], v[172:175], v[16:19]
	v_mfma_f32_16x16x32_bf16 v[12:15], v[164:167], v[172:175], v[12:15]
	s_waitcnt lgkmcnt(3)
	v_mfma_f32_16x16x32_bf16 v[8:11], v[128:131], v[176:179], v[8:11]
	ds_read_b128 v[228:231], v251 offset:6144
	v_mfma_f32_16x16x32_bf16 v[4:7], v[148:151], v[176:179], v[4:7]
	v_mfma_f32_16x16x32_bf16 v[0:3], v[156:159], v[176:179], v[0:3]
	v_mfma_f32_16x16x32_bf16 v[76:79], v[164:167], v[176:179], v[76:79]
	s_waitcnt lgkmcnt(3)
	v_mfma_f32_16x16x32_bf16 v[124:127], v[144:147], v[188:191], v[124:127]
	ds_read_b128 v[172:175], v251 offset:8192
	v_mfma_f32_16x16x32_bf16 v[120:123], v[152:155], v[188:191], v[120:123]
	v_mfma_f32_16x16x32_bf16 v[116:119], v[160:163], v[188:191], v[116:119]
	v_mfma_f32_16x16x32_bf16 v[112:115], v[168:171], v[188:191], v[112:115]
	s_waitcnt lgkmcnt(3)
	v_mfma_f32_16x16x32_bf16 v[108:111], v[144:147], v[220:223], v[108:111]
	ds_read_b128 v[176:179], v251 offset:10240
	v_mfma_f32_16x16x32_bf16 v[104:107], v[152:155], v[220:223], v[104:107]
	v_mfma_f32_16x16x32_bf16 v[100:103], v[160:163], v[220:223], v[100:103]
	v_mfma_f32_16x16x32_bf16 v[96:99], v[168:171], v[220:223], v[96:99]
	s_waitcnt lgkmcnt(3)
	v_mfma_f32_16x16x32_bf16 v[92:95], v[144:147], v[224:227], v[92:95]
	ds_read_b128 v[188:191], v251 offset:12288
	v_mfma_f32_16x16x32_bf16 v[88:91], v[152:155], v[224:227], v[88:91]
	v_mfma_f32_16x16x32_bf16 v[84:87], v[160:163], v[224:227], v[84:87]
	v_mfma_f32_16x16x32_bf16 v[80:83], v[168:171], v[224:227], v[80:83]
	s_waitcnt lgkmcnt(3)
	v_mfma_f32_16x16x32_bf16 v[72:75], v[144:147], v[228:231], v[72:75]
	ds_read_b128 v[220:223], v251 offset:14336
	v_mfma_f32_16x16x32_bf16 v[68:71], v[152:155], v[228:231], v[68:71]
	v_mfma_f32_16x16x32_bf16 v[64:67], v[160:163], v[228:231], v[64:67]
	v_mfma_f32_16x16x32_bf16 v[60:63], v[168:171], v[228:231], v[60:63]
	s_waitcnt lgkmcnt(3)
	v_mfma_f32_16x16x32_bf16 v[56:59], v[144:147], v[172:175], v[56:59]
	v_mfma_f32_16x16x32_bf16 v[52:55], v[152:155], v[172:175], v[52:55]
	v_mfma_f32_16x16x32_bf16 v[48:51], v[160:163], v[172:175], v[48:51]
	v_mfma_f32_16x16x32_bf16 v[44:47], v[168:171], v[172:175], v[44:47]
	s_waitcnt lgkmcnt(2)
	v_mfma_f32_16x16x32_bf16 v[40:43], v[144:147], v[176:179], v[40:43]
	v_mfma_f32_16x16x32_bf16 v[36:39], v[152:155], v[176:179], v[36:39]
	v_mfma_f32_16x16x32_bf16 v[32:35], v[160:163], v[176:179], v[32:35]
	v_mfma_f32_16x16x32_bf16 v[28:31], v[168:171], v[176:179], v[28:31]
	s_waitcnt lgkmcnt(1)
	v_mfma_f32_16x16x32_bf16 v[24:27], v[144:147], v[188:191], v[24:27]
	v_mfma_f32_16x16x32_bf16 v[20:23], v[152:155], v[188:191], v[20:23]
	v_mfma_f32_16x16x32_bf16 v[16:19], v[160:163], v[188:191], v[16:19]
	v_mfma_f32_16x16x32_bf16 v[12:15], v[168:171], v[188:191], v[12:15]
	s_waitcnt lgkmcnt(0)
	v_mfma_f32_16x16x32_bf16 v[8:11], v[144:147], v[220:223], v[8:11]
	v_mfma_f32_16x16x32_bf16 v[4:7], v[152:155], v[220:223], v[4:7]
	v_mfma_f32_16x16x32_bf16 v[0:3], v[160:163], v[220:223], v[0:3]
	v_mfma_f32_16x16x32_bf16 v[76:79], v[168:171], v[220:223], v[76:79]
	s_add_u32 s98, s98, 0x80
	s_addc_u32 s99, s99, 0
	s_add_u32 s100, s100, 0x80
	s_addc_u32 s101, s101, 0
	s_waitcnt vmcnt(0) lgkmcnt(0)
	s_barrier
	s_add_u32 m0, s2, 0
	ds_read_b128 v[128:131], v248 offset:0
	global_load_lds_dwordx4 v134, s[98:99]
	s_add_u32 m0, s2, 4096
	ds_read_b128 v[148:151], v248 offset:2048
	global_load_lds_dwordx4 v142, s[98:99]
	s_add_u32 m0, s2, 8192
	ds_read_b128 v[156:159], v248 offset:4096
	global_load_lds_dwordx4 v143, s[98:99]
	s_add_u32 m0, s2, 12288
	ds_read_b128 v[164:167], v248 offset:6144
	global_load_lds_dwordx4 v180, s[98:99]
	s_add_u32 m0, s2, 16384
	ds_read_b128 v[144:147], v249 offset:0
	global_load_lds_dwordx4 v215, s[98:99]
	s_add_u32 m0, s2, 20480
	ds_read_b128 v[152:155], v249 offset:2048
	global_load_lds_dwordx4 v216, s[98:99]
	s_add_u32 m0, s2, 24576
	ds_read_b128 v[160:163], v249 offset:4096
	global_load_lds_dwordx4 v217, s[98:99]
	s_add_u32 m0, s2, 28672
	ds_read_b128 v[168:171], v249 offset:6144
	global_load_lds_dwordx4 v218, s[98:99]
	ds_read_b128 v[172:175], v252 offset:32768
	ds_read_b128 v[176:179], v252 offset:34816
	ds_read_b128 v[188:191], v252 offset:36864
	ds_read_b128 v[220:223], v252 offset:38912
	s_waitcnt lgkmcnt(4)
	s_barrier
	s_waitcnt lgkmcnt(3)
	s_add_u32 m0, s2, 65536
	v_mfma_f32_16x16x32_bf16 v[124:127], v[128:131], v[172:175], v[124:127]
	ds_read_b128 v[224:227], v252 offset:40960
	global_load_lds_dwordx4 v134, s[100:101]
	v_mfma_f32_16x16x32_bf16 v[120:123], v[148:151], v[172:175], v[120:123]
	s_add_u32 m0, s2, 69632
	v_mfma_f32_16x16x32_bf16 v[116:119], v[156:159], v[172:175], v[116:119]
	global_load_lds_dwordx4 v142, s[100:101]
	v_mfma_f32_16x16x32_bf16 v[112:115], v[164:167], v[172:175], v[112:115]
	s_waitcnt lgkmcnt(3)
	s_add_u32 m0, s2, 73728
	v_mfma_f32_16x16x32_bf16 v[108:111], v[128:131], v[176:179], v[108:111]
	ds_read_b128 v[228:231], v252 offset:43008
	global_load_lds_dwordx4 v143, s[100:101]
	v_mfma_f32_16x16x32_bf16 v[104:107], v[148:151], v[176:179], v[104:107]
	s_add_u32 m0, s2, 77824
	v_mfma_f32_16x16x32_bf16 v[100:103], v[156:159], v[176:179], v[100:103]
	global_load_lds_dwordx4 v180, s[100:101]
	v_mfma_f32_16x16x32_bf16 v[96:99], v[164:167], v[176:179], v[96:99]
	s_waitcnt lgkmcnt(3)
	v_mfma_f32_16x16x32_bf16 v[92:95], v[128:131], v[188:191], v[92:95]
	ds_read_b128 v[172:175], v252 offset:45056
	v_mfma_f32_16x16x32_bf16 v[88:91], v[148:151], v[188:191], v[88:91]
	v_mfma_f32_16x16x32_bf16 v[84:87], v[156:159], v[188:191], v[84:87]
	v_mfma_f32_16x16x32_bf16 v[80:83], v[164:167], v[188:191], v[80:83]
	s_waitcnt lgkmcnt(3)
	v_mfma_f32_16x16x32_bf16 v[72:75], v[128:131], v[220:223], v[72:75]
	ds_read_b128 v[176:179], v252 offset:47104
	v_mfma_f32_16x16x32_bf16 v[68:71], v[148:151], v[220:223], v[68:71]
	v_mfma_f32_16x16x32_bf16 v[64:67], v[156:159], v[220:223], v[64:67]
	v_mfma_f32_16x16x32_bf16 v[60:63], v[164:167], v[220:223], v[60:63]
	s_waitcnt lgkmcnt(3)
	v_mfma_f32_16x16x32_bf16 v[56:59], v[128:131], v[224:227], v[56:59]
	ds_read_b128 v[188:191], v251 offset:32768
	v_mfma_f32_16x16x32_bf16 v[52:55], v[148:151], v[224:227], v[52:55]
	v_mfma_f32_16x16x32_bf16 v[48:51], v[156:159], v[224:227], v[48:51]
	v_mfma_f32_16x16x32_bf16 v[44:47], v[164:167], v[224:227], v[44:47]
	s_waitcnt lgkmcnt(3)
	v_mfma_f32_16x16x32_bf16 v[40:43], v[128:131], v[228:231], v[40:43]
	ds_read_b128 v[220:223], v251 offset:34816
	v_mfma_f32_16x16x32_bf16 v[36:39], v[148:151], v[228:231], v[36:39]
	v_mfma_f32_16x16x32_bf16 v[32:35], v[156:159], v[228:231], v[32:35]
	v_mfma_f32_16x16x32_bf16 v[28:31], v[164:167], v[228:231], v[28:31]
	s_waitcnt lgkmcnt(3)
	v_mfma_f32_16x16x32_bf16 v[24:27], v[128:131], v[172:175], v[24:27]
	ds_read_b128 v[224:227], v251 offset:36864
	v_mfma_f32_16x16x32_bf16 v[20:23], v[148:151], v[172:175], v[20:23]
	v_mfma_f32_16x16x32_bf16 v[16:19], v[156:159], v[172:175], v[16:19]
	v_mfma_f32_16x16x32_bf16 v[12:15], v[164:167], v[172:175], v[12:15]
	s_waitcnt lgkmcnt(3)
	v_mfma_f32_16x16x32_bf16 v[8:11], v[128:131], v[176:179], v[8:11]
	ds_read_b128 v[228:231], v251 offset:38912
	v_mfma_f32_16x16x32_bf16 v[4:7], v[148:151], v[176:179], v[4:7]
	v_mfma_f32_16x16x32_bf16 v[0:3], v[156:159], v[176:179], v[0:3]
	v_mfma_f32_16x16x32_bf16 v[76:79], v[164:167], v[176:179], v[76:79]
	s_waitcnt lgkmcnt(3)
	v_mfma_f32_16x16x32_bf16 v[124:127], v[144:147], v[188:191], v[124:127]
	ds_read_b128 v[172:175], v251 offset:40960
	v_mfma_f32_16x16x32_bf16 v[120:123], v[152:155], v[188:191], v[120:123]
	v_mfma_f32_16x16x32_bf16 v[116:119], v[160:163], v[188:191], v[116:119]
	v_mfma_f32_16x16x32_bf16 v[112:115], v[168:171], v[188:191], v[112:115]
	s_waitcnt lgkmcnt(3)
	v_mfma_f32_16x16x32_bf16 v[108:111], v[144:147], v[220:223], v[108:111]
	ds_read_b128 v[176:179], v251 offset:43008
	v_mfma_f32_16x16x32_bf16 v[104:107], v[152:155], v[220:223], v[104:107]
	v_mfma_f32_16x16x32_bf16 v[100:103], v[160:163], v[220:223], v[100:103]
	v_mfma_f32_16x16x32_bf16 v[96:99], v[168:171], v[220:223], v[96:99]
	s_waitcnt lgkmcnt(3)
	v_mfma_f32_16x16x32_bf16 v[92:95], v[144:147], v[224:227], v[92:95]
	ds_read_b128 v[188:191], v251 offset:45056
	v_mfma_f32_16x16x32_bf16 v[88:91], v[152:155], v[224:227], v[88:91]
	v_mfma_f32_16x16x32_bf16 v[84:87], v[160:163], v[224:227], v[84:87]
	v_mfma_f32_16x16x32_bf16 v[80:83], v[168:171], v[224:227], v[80:83]
	s_waitcnt lgkmcnt(3)
	v_mfma_f32_16x16x32_bf16 v[72:75], v[144:147], v[228:231], v[72:75]
	ds_read_b128 v[220:223], v251 offset:47104
	v_mfma_f32_16x16x32_bf16 v[68:71], v[152:155], v[228:231], v[68:71]
	v_mfma_f32_16x16x32_bf16 v[64:67], v[160:163], v[228:231], v[64:67]
	v_mfma_f32_16x16x32_bf16 v[60:63], v[168:171], v[228:231], v[60:63]
	s_waitcnt lgkmcnt(3)
	v_mfma_f32_16x16x32_bf16 v[56:59], v[144:147], v[172:175], v[56:59]
	v_mfma_f32_16x16x32_bf16 v[52:55], v[152:155], v[172:175], v[52:55]
	v_mfma_f32_16x16x32_bf16 v[48:51], v[160:163], v[172:175], v[48:51]
	v_mfma_f32_16x16x32_bf16 v[44:47], v[168:171], v[172:175], v[44:47]
	s_waitcnt lgkmcnt(2)
	v_mfma_f32_16x16x32_bf16 v[40:43], v[144:147], v[176:179], v[40:43]
	v_mfma_f32_16x16x32_bf16 v[36:39], v[152:155], v[176:179], v[36:39]
	v_mfma_f32_16x16x32_bf16 v[32:35], v[160:163], v[176:179], v[32:35]
	v_mfma_f32_16x16x32_bf16 v[28:31], v[168:171], v[176:179], v[28:31]
	s_waitcnt lgkmcnt(1)
	v_mfma_f32_16x16x32_bf16 v[24:27], v[144:147], v[188:191], v[24:27]
	v_mfma_f32_16x16x32_bf16 v[20:23], v[152:155], v[188:191], v[20:23]
	v_mfma_f32_16x16x32_bf16 v[16:19], v[160:163], v[188:191], v[16:19]
	v_mfma_f32_16x16x32_bf16 v[12:15], v[168:171], v[188:191], v[12:15]
	s_waitcnt lgkmcnt(0)
	v_mfma_f32_16x16x32_bf16 v[8:11], v[144:147], v[220:223], v[8:11]
	v_mfma_f32_16x16x32_bf16 v[4:7], v[152:155], v[220:223], v[4:7]
	v_mfma_f32_16x16x32_bf16 v[0:3], v[160:163], v[220:223], v[0:3]
	v_mfma_f32_16x16x32_bf16 v[76:79], v[168:171], v[220:223], v[76:79]
	s_add_u32 s98, s98, 0x80
	s_addc_u32 s99, s99, 0
	s_add_u32 s100, s100, 0x80
	s_addc_u32 s101, s101, 0
	s_sub_u32 s3, s3, 1
	s_cmp_lg_u32 s3, 0
	s_cbranch_scc1 .Lg8p11_loop
	s_waitcnt vmcnt(0) lgkmcnt(0)
	s_barrier
	s_add_u32 m0, s2, 32768
	ds_read_b128 v[128:131], v248 offset:0
	global_load_lds_dwordx4 v134, s[98:99]
	s_add_u32 m0, s2, 36864
	ds_read_b128 v[148:151], v248 offset:2048
	global_load_lds_dwordx4 v142, s[98:99]
	s_add_u32 m0, s2, 40960
	ds_read_b128 v[156:159], v248 offset:4096
	global_load_lds_dwordx4 v143, s[98:99]
	s_add_u32 m0, s2, 45056
	ds_read_b128 v[164:167], v248 offset:6144
	global_load_lds_dwordx4 v180, s[98:99]
	s_add_u32 m0, s2, 49152
	ds_read_b128 v[144:147], v249 offset:0
	global_load_lds_dwordx4 v215, s[98:99]
	s_add_u32 m0, s2, 53248
	ds_read_b128 v[152:155], v249 offset:2048
	global_load_lds_dwordx4 v216, s[98:99]
	s_add_u32 m0, s2, 57344
	ds_read_b128 v[160:163], v249 offset:4096
	global_load_lds_dwordx4 v217, s[98:99]
	s_add_u32 m0, s2, 61440
	ds_read_b128 v[168:171], v249 offset:6144
	global_load_lds_dwordx4 v218, s[98:99]
	ds_read_b128 v[172:175], v252 offset:0
	ds_read_b128 v[176:179], v252 offset:2048
	ds_read_b128 v[188:191], v252 offset:4096
	ds_read_b128 v[220:223], v252 offset:6144
	s_waitcnt lgkmcnt(4)
	s_barrier
	s_waitcnt lgkmcnt(3)
	s_add_u32 m0, s2, 65536
	v_mfma_f32_16x16x32_bf16 v[124:127], v[128:131], v[172:175], v[124:127]
	ds_read_b128 v[224:227], v252 offset:8192
	global_load_lds_dwordx4 v134, s[100:101]
	v_mfma_f32_16x16x32_bf16 v[120:123], v[148:151], v[172:175], v[120:123]
	s_add_u32 m0, s2, 69632
	v_mfma_f32_16x16x32_bf16 v[116:119], v[156:159], v[172:175], v[116:119]
	global_load_lds_dwordx4 v142, s[100:101]
	v_mfma_f32_16x16x32_bf16 v[112:115], v[164:167], v[172:175], v[112:115]
	s_waitcnt lgkmcnt(3)
	s_add_u32 m0, s2, 73728
	v_mfma_f32_16x16x32_bf16 v[108:111], v[128:131], v[176:179], v[108:111]
	ds_read_b128 v[228:231], v252 offset:10240
	global_load_lds_dwordx4 v143, s[100:101]
	v_mfma_f32_16x16x32_bf16 v[104:107], v[148:151], v[176:179], v[104:107]
	s_add_u32 m0, s2, 77824
	v_mfma_f32_16x16x32_bf16 v[100:103], v[156:159], v[176:179], v[100:103]
	global_load_lds_dwordx4 v180, s[100:101]
	v_mfma_f32_16x16x32_bf16 v[96:99], v[164:167], v[176:179], v[96:99]
	s_waitcnt lgkmcnt(3)
	v_mfma_f32_16x16x32_bf16 v[92:95], v[128:131], v[188:191], v[92:95]
	ds_read_b128 v[172:175], v252 offset:12288
	v_mfma_f32_16x16x32_bf16 v[88:91], v[148:151], v[188:191], v[88:91]
	v_mfma_f32_16x16x32_bf16 v[84:87], v[156:159], v[188:191], v[84:87]
	v_mfma_f32_16x16x32_bf16 v[80:83], v[164:167], v[188:191], v[80:83]
	s_waitcnt lgkmcnt(3)
	v_mfma_f32_16x16x32_bf16 v[72:75], v[128:131], v[220:223], v[72:75]
	ds_read_b128 v[176:179], v252 offset:14336
	v_mfma_f32_16x16x32_bf16 v[68:71], v[148:151], v[220:223], v[68:71]
	v_mfma_f32_16x16x32_bf16 v[64:67], v[156:159], v[220:223], v[64:67]
	v_mfma_f32_16x16x32_bf16 v[60:63], v[164:167], v[220:223], v[60:63]
	s_waitcnt lgkmcnt(3)
	v_mfma_f32_16x16x32_bf16 v[56:59], v[128:131], v[224:227], v[56:59]
	ds_read_b128 v[188:191], v251 offset:0
	v_mfma_f32_16x16x32_bf16 v[52:55], v[148:151], v[224:227], v[52:55]
	v_mfma_f32_16x16x32_bf16 v[48:51], v[156:159], v[224:227], v[48:51]
	v_mfma_f32_16x16x32_bf16 v[44:47], v[164:167], v[224:227], v[44:47]
	s_waitcnt lgkmcnt(3)
	v_mfma_f32_16x16x32_bf16 v[40:43], v[128:131], v[228:231], v[40:43]
	ds_read_b128 v[220:223], v251 offset:2048
	v_mfma_f32_16x16x32_bf16 v[36:39], v[148:151], v[228:231], v[36:39]
	v_mfma_f32_16x16x32_bf16 v[32:35], v[156:159], v[228:231], v[32:35]
	v_mfma_f32_16x16x32_bf16 v[28:31], v[164:167], v[228:231], v[28:31]
	s_waitcnt lgkmcnt(3)
	v_mfma_f32_16x16x32_bf16 v[24:27], v[128:131], v[172:175], v[24:27]
	ds_read_b128 v[224:227], v251 offset:4096
	v_mfma_f32_16x16x32_bf16 v[20:23], v[148:151], v[172:175], v[20:23]
	v_mfma_f32_16x16x32_bf16 v[16:19], v[156:159], v[172:175], v[16:19]
	v_mfma_f32_16x16x32_bf16 v[12:15], v[164:167], v[172:175], v[12:15]
	s_waitcnt lgkmcnt(3)
	v_mfma_f32_16x16x32_bf16 v[8:11], v[128:131], v[176:179], v[8:11]
	ds_read_b128 v[228:231], v251 offset:6144
	v_mfma_f32_16x16x32_bf16 v[4:7], v[148:151], v[176:179], v[4:7]
	v_mfma_f32_16x16x32_bf16 v[0:3], v[156:159], v[176:179], v[0:3]
	v_mfma_f32_16x16x32_bf16 v[76:79], v[164:167], v[176:179], v[76:79]
	s_waitcnt lgkmcnt(3)
	v_mfma_f32_16x16x32_bf16 v[124:127], v[144:147], v[188:191], v[124:127]
	ds_read_b128 v[172:175], v251 offset:8192
	v_mfma_f32_16x16x32_bf16 v[120:123], v[152:155], v[188:191], v[120:123]
	v_mfma_f32_16x16x32_bf16 v[116:119], v[160:163], v[188:191], v[116:119]
	v_mfma_f32_16x16x32_bf16 v[112:115], v[168:171], v[188:191], v[112:115]
	s_waitcnt lgkmcnt(3)
	v_mfma_f32_16x16x32_bf16 v[108:111], v[144:147], v[220:223], v[108:111]
	ds_read_b128 v[176:179], v251 offset:10240
	v_mfma_f32_16x16x32_bf16 v[104:107], v[152:155], v[220:223], v[104:107]
	v_mfma_f32_16x16x32_bf16 v[100:103], v[160:163], v[220:223], v[100:103]
	v_mfma_f32_16x16x32_bf16 v[96:99], v[168:171], v[220:223], v[96:99]
	s_waitcnt lgkmcnt(3)
	v_mfma_f32_16x16x32_bf16 v[92:95], v[144:147], v[224:227], v[92:95]
	ds_read_b128 v[188:191], v251 offset:12288
	v_mfma_f32_16x16x32_bf16 v[88:91], v[152:155], v[224:227], v[88:91]
	v_mfma_f32_16x16x32_bf16 v[84:87], v[160:163], v[224:227], v[84:87]
	v_mfma_f32_16x16x32_bf16 v[80:83], v[168:171], v[224:227], v[80:83]
	s_waitcnt lgkmcnt(3)
	v_mfma_f32_16x16x32_bf16 v[72:75], v[144:147], v[228:231], v[72:75]
	ds_read_b128 v[220:223], v251 offset:14336
	v_mfma_f32_16x16x32_bf16 v[68:71], v[152:155], v[228:231], v[68:71]
	v_mfma_f32_16x16x32_bf16 v[64:67], v[160:163], v[228:231], v[64:67]
	v_mfma_f32_16x16x32_bf16 v[60:63], v[168:171], v[228:231], v[60:63]
	s_waitcnt lgkmcnt(3)
	v_mfma_f32_16x16x32_bf16 v[56:59], v[144:147], v[172:175], v[56:59]
	v_mfma_f32_16x16x32_bf16 v[52:55], v[152:155], v[172:175], v[52:55]
	v_mfma_f32_16x16x32_bf16 v[48:51], v[160:163], v[172:175], v[48:51]
	v_mfma_f32_16x16x32_bf16 v[44:47], v[168:171], v[172:175], v[44:47]
	s_waitcnt lgkmcnt(2)
	v_mfma_f32_16x16x32_bf16 v[40:43], v[144:147], v[176:179], v[40:43]
	v_mfma_f32_16x16x32_bf16 v[36:39], v[152:155], v[176:179], v[36:39]
	v_mfma_f32_16x16x32_bf16 v[32:35], v[160:163], v[176:179], v[32:35]
	v_mfma_f32_16x16x32_bf16 v[28:31], v[168:171], v[176:179], v[28:31]
	s_waitcnt lgkmcnt(1)
	v_mfma_f32_16x16x32_bf16 v[24:27], v[144:147], v[188:191], v[24:27]
	v_mfma_f32_16x16x32_bf16 v[20:23], v[152:155], v[188:191], v[20:23]
	v_mfma_f32_16x16x32_bf16 v[16:19], v[160:163], v[188:191], v[16:19]
	v_mfma_f32_16x16x32_bf16 v[12:15], v[168:171], v[188:191], v[12:15]
	s_waitcnt lgkmcnt(0)
	v_mfma_f32_16x16x32_bf16 v[8:11], v[144:147], v[220:223], v[8:11]
	v_mfma_f32_16x16x32_bf16 v[4:7], v[152:155], v[220:223], v[4:7]
	v_mfma_f32_16x16x32_bf16 v[0:3], v[160:163], v[220:223], v[0:3]
	v_mfma_f32_16x16x32_bf16 v[76:79], v[168:171], v[220:223], v[76:79]
	s_add_u32 s98, s98, 0x80
	s_addc_u32 s99, s99, 0
	s_add_u32 s100, s100, 0x80
	s_addc_u32 s101, s101, 0
	s_waitcnt vmcnt(0) lgkmcnt(0)
	s_barrier
	ds_read_b128 v[128:131], v248 offset:0
	ds_read_b128 v[148:151], v248 offset:2048
	ds_read_b128 v[156:159], v248 offset:4096
	ds_read_b128 v[164:167], v248 offset:6144
	ds_read_b128 v[144:147], v249 offset:0
	ds_read_b128 v[152:155], v249 offset:2048
	ds_read_b128 v[160:163], v249 offset:4096
	ds_read_b128 v[168:171], v249 offset:6144
	ds_read_b128 v[172:175], v252 offset:32768
	ds_read_b128 v[176:179], v252 offset:34816
	ds_read_b128 v[188:191], v252 offset:36864
	ds_read_b128 v[220:223], v252 offset:38912
	s_waitcnt lgkmcnt(4)
	s_waitcnt lgkmcnt(3)
	v_mfma_f32_16x16x32_bf16 v[124:127], v[128:131], v[172:175], v[124:127]
	ds_read_b128 v[224:227], v252 offset:40960
	v_mfma_f32_16x16x32_bf16 v[120:123], v[148:151], v[172:175], v[120:123]
	v_mfma_f32_16x16x32_bf16 v[116:119], v[156:159], v[172:175], v[116:119]
	v_mfma_f32_16x16x32_bf16 v[112:115], v[164:167], v[172:175], v[112:115]
	s_waitcnt lgkmcnt(3)
	v_mfma_f32_16x16x32_bf16 v[108:111], v[128:131], v[176:179], v[108:111]
	ds_read_b128 v[228:231], v252 offset:43008
	v_mfma_f32_16x16x32_bf16 v[104:107], v[148:151], v[176:179], v[104:107]
	v_mfma_f32_16x16x32_bf16 v[100:103], v[156:159], v[176:179], v[100:103]
	v_mfma_f32_16x16x32_bf16 v[96:99], v[164:167], v[176:179], v[96:99]
	s_waitcnt lgkmcnt(3)
	v_mfma_f32_16x16x32_bf16 v[92:95], v[128:131], v[188:191], v[92:95]
	ds_read_b128 v[172:175], v252 offset:45056
	v_mfma_f32_16x16x32_bf16 v[88:91], v[148:151], v[188:191], v[88:91]
	v_mfma_f32_16x16x32_bf16 v[84:87], v[156:159], v[188:191], v[84:87]
	v_mfma_f32_16x16x32_bf16 v[80:83], v[164:167], v[188:191], v[80:83]
	s_waitcnt lgkmcnt(3)
	v_mfma_f32_16x16x32_bf16 v[72:75], v[128:131], v[220:223], v[72:75]
	ds_read_b128 v[176:179], v252 offset:47104
	v_mfma_f32_16x16x32_bf16 v[68:71], v[148:151], v[220:223], v[68:71]
	v_mfma_f32_16x16x32_bf16 v[64:67], v[156:159], v[220:223], v[64:67]
	v_mfma_f32_16x16x32_bf16 v[60:63], v[164:167], v[220:223], v[60:63]
	s_waitcnt lgkmcnt(3)
	v_mfma_f32_16x16x32_bf16 v[56:59], v[128:131], v[224:227], v[56:59]
	ds_read_b128 v[188:191], v251 offset:32768
	v_mfma_f32_16x16x32_bf16 v[52:55], v[148:151], v[224:227], v[52:55]
	v_mfma_f32_16x16x32_bf16 v[48:51], v[156:159], v[224:227], v[48:51]
	v_mfma_f32_16x16x32_bf16 v[44:47], v[164:167], v[224:227], v[44:47]
	s_waitcnt lgkmcnt(3)
	v_mfma_f32_16x16x32_bf16 v[40:43], v[128:131], v[228:231], v[40:43]
	ds_read_b128 v[220:223], v251 offset:34816
	v_mfma_f32_16x16x32_bf16 v[36:39], v[148:151], v[228:231], v[36:39]
	v_mfma_f32_16x16x32_bf16 v[32:35], v[156:159], v[228:231], v[32:35]
	v_mfma_f32_16x16x32_bf16 v[28:31], v[164:167], v[228:231], v[28:31]
	s_waitcnt lgkmcnt(3)
	v_mfma_f32_16x16x32_bf16 v[24:27], v[128:131], v[172:175], v[24:27]
	ds_read_b128 v[224:227], v251 offset:36864
	v_mfma_f32_16x16x32_bf16 v[20:23], v[148:151], v[172:175], v[20:23]
	v_mfma_f32_16x16x32_bf16 v[16:19], v[156:159], v[172:175], v[16:19]
	v_mfma_f32_16x16x32_bf16 v[12:15], v[164:167], v[172:175], v[12:15]
	s_waitcnt lgkmcnt(3)
	v_mfma_f32_16x16x32_bf16 v[8:11], v[128:131], v[176:179], v[8:11]
	ds_read_b128 v[228:231], v251 offset:38912
	v_mfma_f32_16x16x32_bf16 v[4:7], v[148:151], v[176:179], v[4:7]
	v_mfma_f32_16x16x32_bf16 v[0:3], v[156:159], v[176:179], v[0:3]
	v_mfma_f32_16x16x32_bf16 v[76:79], v[164:167], v[176:179], v[76:79]
	s_waitcnt lgkmcnt(3)
	v_mfma_f32_16x16x32_bf16 v[124:127], v[144:147], v[188:191], v[124:127]
	ds_read_b128 v[172:175], v251 offset:40960
	v_mfma_f32_16x16x32_bf16 v[120:123], v[152:155], v[188:191], v[120:123]
	v_mfma_f32_16x16x32_bf16 v[116:119], v[160:163], v[188:191], v[116:119]
	v_mfma_f32_16x16x32_bf16 v[112:115], v[168:171], v[188:191], v[112:115]
	s_waitcnt lgkmcnt(3)
	v_mfma_f32_16x16x32_bf16 v[108:111], v[144:147], v[220:223], v[108:111]
	ds_read_b128 v[176:179], v251 offset:43008
	v_mfma_f32_16x16x32_bf16 v[104:107], v[152:155], v[220:223], v[104:107]
	v_mfma_f32_16x16x32_bf16 v[100:103], v[160:163], v[220:223], v[100:103]
	v_mfma_f32_16x16x32_bf16 v[96:99], v[168:171], v[220:223], v[96:99]
	s_waitcnt lgkmcnt(3)
	v_mfma_f32_16x16x32_bf16 v[92:95], v[144:147], v[224:227], v[92:95]
	ds_read_b128 v[188:191], v251 offset:45056
	v_mfma_f32_16x16x32_bf16 v[88:91], v[152:155], v[224:227], v[88:91]
	v_mfma_f32_16x16x32_bf16 v[84:87], v[160:163], v[224:227], v[84:87]
	v_mfma_f32_16x16x32_bf16 v[80:83], v[168:171], v[224:227], v[80:83]
	s_waitcnt lgkmcnt(3)
	v_mfma_f32_16x16x32_bf16 v[72:75], v[144:147], v[228:231], v[72:75]
	ds_read_b128 v[220:223], v251 offset:47104
	v_mfma_f32_16x16x32_bf16 v[68:71], v[152:155], v[228:231], v[68:71]
	v_mfma_f32_16x16x32_bf16 v[64:67], v[160:163], v[228:231], v[64:67]
	v_mfma_f32_16x16x32_bf16 v[60:63], v[168:171], v[228:231], v[60:63]
	s_waitcnt lgkmcnt(3)
	v_mfma_f32_16x16x32_bf16 v[56:59], v[144:147], v[172:175], v[56:59]
	v_mfma_f32_16x16x32_bf16 v[52:55], v[152:155], v[172:175], v[52:55]
	v_mfma_f32_16x16x32_bf16 v[48:51], v[160:163], v[172:175], v[48:51]
	v_mfma_f32_16x16x32_bf16 v[44:47], v[168:171], v[172:175], v[44:47]
	s_waitcnt lgkmcnt(2)
	v_mfma_f32_16x16x32_bf16 v[40:43], v[144:147], v[176:179], v[40:43]
	v_mfma_f32_16x16x32_bf16 v[36:39], v[152:155], v[176:179], v[36:39]
	v_mfma_f32_16x16x32_bf16 v[32:35], v[160:163], v[176:179], v[32:35]
	v_mfma_f32_16x16x32_bf16 v[28:31], v[168:171], v[176:179], v[28:31]
	s_waitcnt lgkmcnt(1)
	v_mfma_f32_16x16x32_bf16 v[24:27], v[144:147], v[188:191], v[24:27]
	v_mfma_f32_16x16x32_bf16 v[20:23], v[152:155], v[188:191], v[20:23]
	v_mfma_f32_16x16x32_bf16 v[16:19], v[160:163], v[188:191], v[16:19]
	v_mfma_f32_16x16x32_bf16 v[12:15], v[168:171], v[188:191], v[12:15]
	s_waitcnt lgkmcnt(0)
	v_mfma_f32_16x16x32_bf16 v[8:11], v[144:147], v[220:223], v[8:11]
	v_mfma_f32_16x16x32_bf16 v[4:7], v[152:155], v[220:223], v[4:7]
	v_mfma_f32_16x16x32_bf16 v[0:3], v[160:163], v[220:223], v[0:3]
	v_mfma_f32_16x16x32_bf16 v[76:79], v[168:171], v[220:223], v[76:79]
	s_nop 7
	s_nop 7
	s_barrier
	ds_write_b64 v234, v[232:233]
	v_or_b32_e32 v180, s22, v194
	v_cmp_lt_i32_e64 s[4:5], s52, v180
	v_mov_b32_e32 v144, v76
	v_mov_b32_e32 v145, v77
	v_mov_b32_e32 v146, v78
	v_mov_b32_e32 v147, v79
	v_add_u32_e32 v134, s0, v192
	v_or_b32_e32 v128, v134, v193
	v_ashrrev_i32_e32 v129, 31, v128
	v_cmp_gt_i32_e64 s[12:13], s51, v128
	v_lshlrev_b64 v[130:131], 10, v[128:129]
	v_mov_b32_e32 v76, v72
	v_mov_b32_e32 v77, v73
	v_mov_b32_e32 v78, v74
	v_mov_b32_e32 v79, v75
	v_mov_b32_e32 v72, v68
	v_mov_b32_e32 v73, v69
	v_mov_b32_e32 v74, v70
	v_mov_b32_e32 v75, v71
	v_mov_b32_e32 v68, v64
	v_mov_b32_e32 v69, v65
	v_mov_b32_e32 v70, v66
	v_mov_b32_e32 v71, v67
	v_mov_b32_e32 v64, v60
	v_mov_b32_e32 v65, v61
	v_mov_b32_e32 v66, v62
	v_mov_b32_e32 v67, v63
	v_mov_b32_e32 v60, v56
	v_mov_b32_e32 v61, v57
	v_mov_b32_e32 v62, v58
	v_mov_b32_e32 v63, v59
	v_mov_b32_e32 v56, v52
	v_mov_b32_e32 v57, v53
	v_mov_b32_e32 v58, v54
	v_mov_b32_e32 v59, v55
	v_mov_b32_e32 v52, v48
	v_mov_b32_e32 v53, v49
	v_mov_b32_e32 v54, v50
	v_mov_b32_e32 v55, v51
	v_mov_b32_e32 v48, v44
	v_mov_b32_e32 v49, v45
	v_mov_b32_e32 v50, v46
	v_mov_b32_e32 v51, v47
	v_mov_b32_e32 v44, v40
	v_mov_b32_e32 v45, v41
	v_mov_b32_e32 v46, v42
	v_mov_b32_e32 v47, v43
	v_mov_b32_e32 v40, v36
	v_mov_b32_e32 v41, v37
	v_mov_b32_e32 v42, v38
	v_mov_b32_e32 v43, v39
	v_mov_b32_e32 v36, v32
	v_mov_b32_e32 v37, v33
	v_mov_b32_e32 v38, v34
	v_mov_b32_e32 v39, v35
	v_mov_b32_e32 v32, v28
	v_mov_b32_e32 v33, v29
	v_mov_b32_e32 v34, v30
	v_mov_b32_e32 v35, v31
	v_mov_b32_e32 v28, v24
	v_mov_b32_e32 v29, v25
	v_mov_b32_e32 v30, v26
	v_mov_b32_e32 v31, v27
	v_mov_b32_e32 v24, v20
	v_mov_b32_e32 v25, v21
	v_mov_b32_e32 v26, v22
	v_mov_b32_e32 v27, v23
	v_mov_b32_e32 v20, v16
	v_mov_b32_e32 v21, v17
	v_mov_b32_e32 v22, v18
	v_mov_b32_e32 v23, v19
	v_mov_b32_e32 v16, v12
	v_mov_b32_e32 v17, v13
	v_mov_b32_e32 v18, v14
	v_mov_b32_e32 v19, v15
	v_mov_b32_e32 v12, v8
	v_mov_b32_e32 v13, v9
	v_mov_b32_e32 v14, v10
	v_mov_b32_e32 v15, v11
	v_mov_b32_e32 v8, v4
	v_mov_b32_e32 v9, v5
	v_mov_b32_e32 v10, v6
	v_mov_b32_e32 v11, v7
	v_mov_b32_e32 v4, v0
	v_mov_b32_e32 v5, v1
	v_mov_b32_e32 v6, v2
	v_mov_b32_e32 v7, v3
	v_mov_b32_e32 v0, v144
	v_mov_b32_e32 v1, v145
	v_mov_b32_e32 v2, v146
	v_mov_b32_e32 v3, v147
	s_and_saveexec_b64 s[0:1], s[4:5]
	s_cbranch_execz .LBB0_1254
	s_cmpk_gt_u32 s22, 0xcff
	s_mov_b64 s[2:3], -1
	s_cbranch_scc0 .LBB0_1251
	v_add_u32_e32 v132, 0xfffff300, v180
	v_mov_b64_e32 v[136:137], s[16:17]
	v_mad_u64_u32 v[138:139], s[2:3], v132, s53, v[136:137]
	v_lshlrev_b64 v[140:141], 1, v[128:129]
	v_cvt_pk_bf16_f32 v133, v124, s0
	v_lshl_add_u64 v[138:139], v[138:139], 0, v[140:141]
	v_add_u32_e32 v135, 0xfffff301, v180
	global_store_short v[138:139], v133, off
	v_mad_u64_u32 v[138:139], s[2:3], v135, s53, v[136:137]
	v_cvt_pk_bf16_f32 v133, v125, s0
	v_lshl_add_u64 v[138:139], v[138:139], 0, v[140:141]
	v_add_u32_e32 v135, 0xfffff302, v180
	global_store_short v[138:139], v133, off
	v_mad_u64_u32 v[138:139], s[2:3], v135, s53, v[136:137]
	v_add_u32_e32 v135, 0xfffff303, v180
	v_cvt_pk_bf16_f32 v133, v126, s0
	v_lshl_add_u64 v[138:139], v[138:139], 0, v[140:141]
	v_mad_u64_u32 v[136:137], s[2:3], v135, s53, v[136:137]
	global_store_short v[138:139], v133, off
	v_cvt_pk_bf16_f32 v133, v127, s0
	v_lshl_add_u64 v[136:137], v[136:137], 0, v[140:141]
	global_store_short v[136:137], v133, off
	s_and_saveexec_b64 s[2:3], s[12:13]
	s_cbranch_execz .LBB0_1250
	v_mov_b32_e32 v133, v181
	v_lshl_add_u64 v[136:137], s[20:21], 0, v[130:131]
	v_lshl_add_u64 v[132:133], v[132:133], 2, v[136:137]
	global_store_dwordx4 v[132:133], v[124:127], off

.LBB0_1774:
	s_bfe_u32 s4, s14, 0x30005
	s_mul_i32 s9, s4, 0xc0
	s_lshl_b32 s4, s16, 12
	s_and_b32 s4, s4, 0x380000
	s_lshl_b32 s6, s13, 5
	v_lshl_add_u64 v[144:145], v[142:143], 0, s[4:5]
	s_lshl_b32 s4, s8, 8
	s_and_b32 s6, s6, 0xe0
	s_or_b32 s4, s6, s4
	s_mul_i32 s6, s4, 6
	s_ashr_i32 s7, s6, 31
	s_lshl_b64 s[34:35], s[6:7], 12
	v_lshl_add_u64 v[0:1], v[138:139], 0, s[34:35]
	v_add_co_u32_e32 v2, vcc, s18, v0
	s_lshl_b32 s4, s13, 4
	s_nop 0
	v_addc_co_u32_e32 v3, vcc, 0, v1, vcc
	s_nop 0
	v_readfirstlane_b32 s98, v0
	v_readfirstlane_b32 s99, v1
	v_add_co_u32_e32 v2, vcc, s19, v0
	s_and_b32 s33, s4, 0x380
	s_nop 0
	v_addc_co_u32_e32 v3, vcc, 0, v1, vcc
	v_add_co_u32_e32 v4, vcc, s20, v0
	s_lshl_b32 s4, s33, 12
	s_nop 0
	v_addc_co_u32_e32 v5, vcc, 0, v1, vcc
	v_add_co_u32_e32 v2, vcc, s21, v0
	v_mov_b32_e32 v64, 0
	s_nop 0
	v_addc_co_u32_e32 v3, vcc, 0, v1, vcc
	v_add_co_u32_e32 v0, vcc, 0xa0000, v0
	v_mov_b32_e32 v65, v137
	s_nop 0
	v_addc_co_u32_e32 v1, vcc, 0, v1, vcc
	v_lshl_add_u64 v[0:1], v[140:141], 0, s[4:5]
	v_add_co_u32_e32 v2, vcc, s18, v0
	s_mul_i32 s4, s8, 0x600
	s_nop 0
	v_addc_co_u32_e32 v3, vcc, 0, v1, vcc
	s_nop 0
	v_readfirstlane_b32 s100, v0
	v_readfirstlane_b32 s101, v1
	v_add_co_u32_e32 v2, vcc, 0x40000, v0
	s_add_i32 s8, s4, s9
	s_nop 0
	v_addc_co_u32_e32 v3, vcc, 0, v1, vcc
	v_add_co_u32_e32 v0, vcc, 0x60000, v0
	s_ashr_i32 s9, s8, 31
	s_nop 0
	v_addc_co_u32_e32 v1, vcc, 0, v1, vcc
	s_lshl_b64 s[8:9], s[8:9], 12
	v_lshl_add_u64 v[146:147], v[142:143], 0, s[8:9]
	s_mov_b64 s[8:9], 0
	v_mov_b32_e32 v66, v137
	v_mov_b32_e32 v67, v137
	v_mov_b32_e32 v0, 0
	v_mov_b32_e32 v1, v137
	v_mov_b32_e32 v2, v137
	v_mov_b32_e32 v3, v137
	v_mov_b32_e32 v4, 0
	v_mov_b32_e32 v5, v137
	v_mov_b32_e32 v6, v137
	v_mov_b32_e32 v7, v137
	v_mov_b32_e32 v8, 0
	v_mov_b32_e32 v9, v137
	v_mov_b32_e32 v10, v137
	v_mov_b32_e32 v11, v137
	v_mov_b32_e32 v12, 0
	v_mov_b32_e32 v13, v137
	v_mov_b32_e32 v14, v137
	v_mov_b32_e32 v15, v137
	v_mov_b32_e32 v16, 0
	v_mov_b32_e32 v17, v137
	v_mov_b32_e32 v18, v137
	v_mov_b32_e32 v19, v137
	v_mov_b32_e32 v20, 0
	v_mov_b32_e32 v21, v137
	v_mov_b32_e32 v22, v137
	v_mov_b32_e32 v23, v137
	v_mov_b32_e32 v24, 0
	v_mov_b32_e32 v25, v137
	v_mov_b32_e32 v26, v137
	v_mov_b32_e32 v27, v137
	v_mov_b32_e32 v28, 0
	v_mov_b32_e32 v29, v137
	v_mov_b32_e32 v30, v137
	v_mov_b32_e32 v31, v137
	v_mov_b32_e32 v32, 0
	v_mov_b32_e32 v33, v137
	v_mov_b32_e32 v34, v137
	v_mov_b32_e32 v35, v137
	s_waitcnt vmcnt(22)
	v_mov_b32_e32 v36, 0
	v_mov_b32_e32 v37, v137
	v_mov_b32_e32 v38, v137
	v_mov_b32_e32 v39, v137
	s_waitcnt vmcnt(21)
	v_mov_b32_e32 v40, 0
	v_mov_b32_e32 v41, v137
	v_mov_b32_e32 v42, v137
	v_mov_b32_e32 v43, v137
	s_waitcnt vmcnt(20)
	v_mov_b32_e32 v44, 0
	v_mov_b32_e32 v45, v137
	v_mov_b32_e32 v46, v137
	v_mov_b32_e32 v47, v137
	s_waitcnt vmcnt(19)
	v_mov_b32_e32 v48, 0
	v_mov_b32_e32 v49, v137
	v_mov_b32_e32 v50, v137
	v_mov_b32_e32 v51, v137
	s_waitcnt vmcnt(18)
	v_mov_b32_e32 v52, 0
	v_mov_b32_e32 v53, v137
	v_mov_b32_e32 v54, v137
	v_mov_b32_e32 v55, v137
	v_mov_b32_e32 v56, 0
	v_mov_b32_e32 v57, v137
	v_mov_b32_e32 v58, v137
	v_mov_b32_e32 v59, v137
	v_mov_b32_e32 v60, 0
	v_mov_b32_e32 v61, v137
	v_mov_b32_e32 v62, v137
	v_mov_b32_e32 v63, v137
	v_mov_b32_e32 v68, 0
	v_mov_b32_e32 v69, v137
	v_mov_b32_e32 v70, v137
	v_mov_b32_e32 v71, v137
	v_mov_b32_e32 v72, 0
	v_mov_b32_e32 v73, v137
	v_mov_b32_e32 v74, v137
	v_mov_b32_e32 v75, v137
	v_mov_b32_e32 v76, 0
	v_mov_b32_e32 v77, v137
	v_mov_b32_e32 v78, v137
	v_mov_b32_e32 v79, v137
	v_mov_b32_e32 v80, 0
	v_mov_b32_e32 v81, v137
	v_mov_b32_e32 v82, v137
	v_mov_b32_e32 v83, v137
	v_mov_b32_e32 v84, 0
	v_mov_b32_e32 v85, v137
	v_mov_b32_e32 v86, v137
	v_mov_b32_e32 v87, v137
	v_mov_b32_e32 v88, 0
	v_mov_b32_e32 v89, v137
	v_mov_b32_e32 v90, v137
	v_mov_b32_e32 v91, v137
	v_mov_b32_e32 v92, 0
	v_mov_b32_e32 v93, v137
	v_mov_b32_e32 v94, v137
	v_mov_b32_e32 v95, v137
	v_and_b32_e32 v197, 63, v196
	v_lshrrev_b32_e32 v198, 3, v197
	v_and_b32_e32 v199, 7, v197
	v_xor_b32_e32 v199, v199, v198
	v_lshlrev_b32_e32 v199, 4, v199
	v_mul_u32_u24_e32 v198, 4096, v198
	v_add_u32_e32 v240, v198, v199
	v_add_u32_e32 v241, 131072, v240
	v_add_u32_e32 v242, 262144, v240
	v_add_u32_e32 v243, 393216, v240
	v_add_u32_e32 v244, 524288, v240
	v_add_u32_e32 v245, 655360, v240
	v_lshrrev_b32_e32 v198, 6, v196
	v_lshrrev_b32_e32 v199, 1, v198
	v_and_b32_e32 v198, 1, v198
	v_and_b32_e32 v190, 15, v197
	v_lshrrev_b32_e32 v191, 4, v197
	v_and_b32_e32 v192, 7, v190
	v_xor_b32_e32 v191, v191, v192
	v_lshlrev_b32_e32 v191, 4, v191
	v_mul_u32_u24_e32 v199, 0x60, v199
	v_add_u32_e32 v199, v199, v190
	v_lshl_add_u32 v246, v199, 7, v191
	v_xor_b32_e32 v247, 64, v246
	v_lshlrev_b32_e32 v198, 6, v198
	v_add_u32_e32 v198, v198, v190
	v_lshl_add_u32 v248, v198, 7, v191
	v_add_u32_e32 v248, 0x6000, v248
	v_xor_b32_e32 v249, 64, v248
	v_lshrrev_b32_e32 v198, 6, v196
	v_lshlrev_b32_e32 v198, 10, v198
	s_nop 0
	v_readfirstlane_b32 s8, v198
	s_waitcnt lgkmcnt(0)
	s_barrier
	s_add_u32 m0, s8, 0
	s_nop 0
	global_load_lds_dwordx4 v240, s[98:99]
	s_add_u32 m0, s8, 4096
	s_nop 0
	global_load_lds_dwordx4 v241, s[98:99]
	s_add_u32 m0, s8, 8192
	s_nop 0
	global_load_lds_dwordx4 v242, s[98:99]
	s_add_u32 m0, s8, 12288
	s_nop 0
	global_load_lds_dwordx4 v243, s[98:99]
	s_add_u32 m0, s8, 16384
	s_nop 0
	global_load_lds_dwordx4 v244, s[98:99]
	s_add_u32 m0, s8, 20480
	s_nop 0
	global_load_lds_dwordx4 v245, s[98:99]
	s_add_u32 m0, s8, 24576
	s_nop 0
	global_load_lds_dwordx4 v240, s[100:101]
	s_add_u32 m0, s8, 28672
	s_nop 0
	global_load_lds_dwordx4 v241, s[100:101]
	s_add_u32 m0, s8, 32768
	s_nop 0
	global_load_lds_dwordx4 v242, s[100:101]
	s_add_u32 m0, s8, 36864
	s_nop 0
	global_load_lds_dwordx4 v243, s[100:101]
	s_add_u32 s98, s98, 0x80
	s_addc_u32 s99, s99, 0
	s_add_u32 s100, s100, 0x80
	s_addc_u32 s101, s101, 0
	s_waitcnt vmcnt(0)
	s_barrier
	ds_read_b128 v[120:123], v248 offset:0
	ds_read_b128 v[124:127], v248 offset:2048
	ds_read_b128 v[128:131], v248 offset:4096
	ds_read_b128 v[132:135], v248 offset:6144
	ds_read_b128 v[96:99], v246 offset:0
	ds_read_b128 v[100:103], v246 offset:2048
	ds_read_b128 v[104:107], v246 offset:4096
	ds_read_b128 v[108:111], v246 offset:6144
	ds_read_b128 v[112:115], v246 offset:8192
	ds_read_b128 v[116:119], v246 offset:10240
	s_add_u32 m0, s8, 40960
	s_nop 0
	global_load_lds_dwordx4 v240, s[98:99]
	s_add_u32 m0, s8, 45056
	s_nop 0
	global_load_lds_dwordx4 v241, s[98:99]
	s_add_u32 m0, s8, 49152
	s_nop 0
	global_load_lds_dwordx4 v242, s[98:99]
	s_add_u32 m0, s8, 53248
	s_nop 0
	global_load_lds_dwordx4 v243, s[98:99]
	s_add_u32 m0, s8, 57344
	s_nop 0
	global_load_lds_dwordx4 v244, s[98:99]
	s_add_u32 m0, s8, 61440
	s_nop 0
	global_load_lds_dwordx4 v245, s[98:99]
	s_add_u32 m0, s8, 65536
	s_nop 0
	global_load_lds_dwordx4 v240, s[100:101]
	s_add_u32 m0, s8, 69632
	s_nop 0
	global_load_lds_dwordx4 v241, s[100:101]
	s_add_u32 m0, s8, 73728
	s_nop 0
	global_load_lds_dwordx4 v242, s[100:101]
	s_add_u32 m0, s8, 77824
	s_nop 0
	global_load_lds_dwordx4 v243, s[100:101]
	s_add_u32 s98, s98, 0x80
	s_addc_u32 s99, s99, 0
	s_add_u32 s100, s100, 0x80
	s_addc_u32 s101, s101, 0
	s_waitcnt lgkmcnt(0)
	v_mfma_f32_16x16x32_bf16 v[92:95], v[120:123], v[96:99], v[92:95]
	v_mfma_f32_16x16x32_bf16 v[88:91], v[124:127], v[96:99], v[88:91]
	ds_read_b128 v[224:227], v249 offset:0
	v_mfma_f32_16x16x32_bf16 v[84:87], v[128:131], v[96:99], v[84:87]
	v_mfma_f32_16x16x32_bf16 v[80:83], v[132:135], v[96:99], v[80:83]
	ds_read_b128 v[228:231], v249 offset:2048
	v_mfma_f32_16x16x32_bf16 v[76:79], v[120:123], v[100:103], v[76:79]
	v_mfma_f32_16x16x32_bf16 v[72:75], v[124:127], v[100:103], v[72:75]
	ds_read_b128 v[232:235], v249 offset:4096
	v_mfma_f32_16x16x32_bf16 v[68:71], v[128:131], v[100:103], v[68:71]
	v_mfma_f32_16x16x32_bf16 v[60:63], v[132:135], v[100:103], v[60:63]
	ds_read_b128 v[236:239], v249 offset:6144
	v_mfma_f32_16x16x32_bf16 v[56:59], v[120:123], v[104:107], v[56:59]
	v_mfma_f32_16x16x32_bf16 v[52:55], v[124:127], v[104:107], v[52:55]
	ds_read_b128 v[200:203], v247 offset:0
	v_mfma_f32_16x16x32_bf16 v[48:51], v[128:131], v[104:107], v[48:51]
	v_mfma_f32_16x16x32_bf16 v[44:47], v[132:135], v[104:107], v[44:47]
	ds_read_b128 v[204:207], v247 offset:2048
	v_mfma_f32_16x16x32_bf16 v[40:43], v[120:123], v[108:111], v[40:43]
	v_mfma_f32_16x16x32_bf16 v[36:39], v[124:127], v[108:111], v[36:39]
	ds_read_b128 v[208:211], v247 offset:4096
	v_mfma_f32_16x16x32_bf16 v[32:35], v[128:131], v[108:111], v[32:35]
	v_mfma_f32_16x16x32_bf16 v[28:31], v[132:135], v[108:111], v[28:31]
	ds_read_b128 v[212:215], v247 offset:6144
	v_mfma_f32_16x16x32_bf16 v[24:27], v[120:123], v[112:115], v[24:27]
	v_mfma_f32_16x16x32_bf16 v[20:23], v[124:127], v[112:115], v[20:23]
	ds_read_b128 v[216:219], v247 offset:8192
	v_mfma_f32_16x16x32_bf16 v[16:19], v[128:131], v[112:115], v[16:19]
	v_mfma_f32_16x16x32_bf16 v[12:15], v[132:135], v[112:115], v[12:15]
	ds_read_b128 v[220:223], v247 offset:10240
	v_mfma_f32_16x16x32_bf16 v[8:11], v[120:123], v[116:119], v[8:11]
	v_mfma_f32_16x16x32_bf16 v[4:7], v[124:127], v[116:119], v[4:7]
	v_mfma_f32_16x16x32_bf16 v[0:3], v[128:131], v[116:119], v[0:3]
	v_mfma_f32_16x16x32_bf16 v[64:67], v[132:135], v[116:119], v[64:67]
	s_mov_b32 s9, 15
